# v40 plus merged pre-barrier waits and s_setprio 1 placed before the barrier (the two neutral-to-positive GEMM segment-edge edits combined)
# baseline (speedup 1.0000x reference)
; #define PG8_STAGE(bufoff, gbase, voff) do { _Pragma("unroll") for (int _i = 0; _i < 2; ++_i) \
;         __builtin_amdgcn_global_load_lds((const unsigned*)((const char*)(gbase) + (voff)[_i]), (PG8_LAS unsigned*)(lds + (bufoff) + ldsw + _i * 8192), 16, 0, 0); } while (0)
; #define PG8_LDA(dst, b, h) do { _Pragma("unroll") for (int m = 0; m < 4; ++m) _Pragma("unroll") for (int k = 0; k < 2; ++k) dst[m][k] = *(const PG8_LAS bf16x8*)(lds + PG8_SA(b, h) + aoff + m * 2048 + k * 1024); } while (0)
; #define PG8_LDB(dst, b, h) do { _Pragma("unroll") for (int n = 0; n < 2; ++n) _Pragma("unroll") for (int k = 0; k < 2; ++k) dst[n][k] = *(const PG8_LAS bf16x8*)(lds + PG8_SB(b, h) + boff + n * 2048 + k * 1024); } while (0)
; #define PG8_MMA(ai, bj, At, Bt) do { __builtin_amdgcn_s_setprio(1); _Pragma("unroll") for (int m = 0; m < 4; ++m) _Pragma("unroll") for (int n = 0; n < 2; ++n) _Pragma("unroll") for (int k = 0; k < 2; ++k) \
;         acc[ai][bj][m][n] = __builtin_amdgcn_mfma_f32_16x16x32_bf16(Bt[n][k], At[m][k], acc[ai][bj][m][n], 0, 0, 0); __builtin_amdgcn_s_setprio(0); } while (0)
; #define PG8_WAIT_V(n) asm volatile("s_waitcnt vmcnt(" #n ")" ::: "memory")
; #define PG8_BAR __builtin_amdgcn_s_barrier()
; template <class Epi, class Sched, bool ALIGN_EPI = false, bool SP2 = false>
; __device__ __forceinline__ void gemm_phase(PG8_LAS unsigned char* lds, const Gemm g, const Sched& S, const Epi& E) {
;     ...
;         for (int t = 0; t < nt; t += 2) {
;             const bool last = (t == nt - 2);
;             const char* a1 = cA + (size_t)(t + 1) * kstep;
;             const char* a2 = last ? nA : cA + (size_t)(t + 2) * kstep; const char* b2 = last ? nB : cB + (size_t)(t + 2) * kstep;
;             const char* a3 = a2 + kstep; const char* b3 = b2 + kstep;
;             if (last && has_next) S.a_ready(nxt);
;             if constexpr (SP2) {
;             PG8_LDB(B0, 0, 0); PG8_LDB(B1, 0, 1); PG8_SCHED; PG8_LDA(At, 0, 0); PG8_STAGE(PG8_SA(1, 1), a1 + hstepA, voffA);
;             PG8_WAIT_V(8); PG8_WAIT_L(0); PG8_BAR; PG8_MMA(0, 0, At, B0); PG8_MMA(0, 1, At, B1); PG8_BAR; PG8_SCHED;
;             PG8_LDA(At, 0, 1); PG8_STAGE(PG8_SB(0, 0), b2, voffB); PG8_STAGE(PG8_SB(0, 1), b2 + hstepB, voffB); PG8_STAGE(PG8_SA(0, 0), a2, voffA);
;             PG8_WAIT_V(8); PG8_WAIT_L(0); PG8_BAR; PG8_MMA(1, 0, At, B0); PG8_MMA(1, 1, At, B1); PG8_BAR; PG8_SCHED;
.LBB0_254:
	s_add_u32 s28, s26, 0xfffc0080
	s_addc_u32 s29, s27, -1
	s_add_i32 s53, 0, 0x10000
	s_cmp_eq_u32 s52, 12
	s_cselect_b32 s31, s7, s29
	s_cselect_b32 s30, s9, s28
	v_add_u32_e32 v150, s53, v153
	s_cselect_b32 s29, s19, s51
	s_cselect_b32 s28, s21, s50
	s_add_i32 s56, 0, 0x14000
	ds_read_b128 v[142:145], v150
	ds_read_b128 v[146:149], v150 offset:1024
	ds_read_b128 v[158:161], v150 offset:2048
	ds_read_b128 v[162:165], v150 offset:3072
	v_add_u32_e32 v150, s56, v153
	ds_read_b128 v[166:169], v150
	ds_read_b128 v[170:173], v150 offset:1024
	ds_read_b128 v[174:177], v150 offset:2048
	ds_read_b128 v[178:181], v150 offset:3072
	s_add_i32 m0, s40, 0xc000
	ds_read_b128 v[182:185], v156
	ds_read_b128 v[202:205], v156 offset:1024
	ds_read_b128 v[206:209], v156 offset:2048
	ds_read_b128 v[210:213], v156 offset:3072
	ds_read_b128 v[232:235], v156 offset:4096
	ds_read_b128 v[236:239], v156 offset:5120
	ds_read_b128 v[240:243], v156 offset:6144
	ds_read_b128 v[244:247], v156 offset:7168
	global_load_lds_dwordx4 v138, s[26:27]
	s_add_i32 m0, s40, 0xe000
	s_nop 0
	global_load_lds_dwordx4 v140, s[26:27]
	s_waitcnt vmcnt(8) lgkmcnt(0)
	s_setprio 1
	s_barrier
	v_mfma_f32_16x16x32_bf16 v[126:129], v[142:145], v[182:185], v[126:129]
	v_mfma_f32_16x16x32_bf16 v[122:125], v[158:161], v[182:185], v[122:125]
	v_mfma_f32_16x16x32_bf16 v[110:113], v[142:145], v[206:209], v[110:113]
	v_mfma_f32_16x16x32_bf16 v[106:109], v[158:161], v[206:209], v[106:109]
	v_mfma_f32_16x16x32_bf16 v[94:97], v[142:145], v[232:235], v[94:97]
	v_mfma_f32_16x16x32_bf16 v[90:93], v[158:161], v[232:235], v[90:93]
	v_mfma_f32_16x16x32_bf16 v[78:81], v[142:145], v[240:243], v[78:81]
	v_mfma_f32_16x16x32_bf16 v[74:77], v[158:161], v[240:243], v[74:77]
	v_mfma_f32_16x16x32_bf16 v[126:129], v[146:149], v[202:205], v[126:129]
	v_mfma_f32_16x16x32_bf16 v[122:125], v[162:165], v[202:205], v[122:125]
	v_mfma_f32_16x16x32_bf16 v[110:113], v[146:149], v[210:213], v[110:113]
	v_mfma_f32_16x16x32_bf16 v[106:109], v[162:165], v[210:213], v[106:109]
	v_mfma_f32_16x16x32_bf16 v[94:97], v[146:149], v[236:239], v[94:97]
	v_mfma_f32_16x16x32_bf16 v[90:93], v[162:165], v[236:239], v[90:93]
	v_mfma_f32_16x16x32_bf16 v[78:81], v[146:149], v[244:247], v[78:81]
	v_mfma_f32_16x16x32_bf16 v[74:77], v[162:165], v[244:247], v[74:77]
	s_setprio 0
	s_setprio 1
	v_mfma_f32_16x16x32_bf16 v[118:121], v[166:169], v[182:185], v[118:121]
	v_mfma_f32_16x16x32_bf16 v[114:117], v[174:177], v[182:185], v[114:117]
	v_mfma_f32_16x16x32_bf16 v[102:105], v[166:169], v[206:209], v[102:105]
	v_mfma_f32_16x16x32_bf16 v[98:101], v[174:177], v[206:209], v[98:101]
	v_mfma_f32_16x16x32_bf16 v[86:89], v[166:169], v[232:235], v[86:89]
	v_mfma_f32_16x16x32_bf16 v[82:85], v[174:177], v[232:235], v[82:85]
	v_mfma_f32_16x16x32_bf16 v[70:73], v[166:169], v[240:243], v[70:73]
	v_mfma_f32_16x16x32_bf16 v[66:69], v[174:177], v[240:243], v[66:69]
	v_mfma_f32_16x16x32_bf16 v[118:121], v[170:173], v[202:205], v[118:121]
	v_mfma_f32_16x16x32_bf16 v[114:117], v[178:181], v[202:205], v[114:117]
	v_mfma_f32_16x16x32_bf16 v[102:105], v[170:173], v[210:213], v[102:105]
	v_mfma_f32_16x16x32_bf16 v[98:101], v[178:181], v[210:213], v[98:101]
	v_mfma_f32_16x16x32_bf16 v[86:89], v[170:173], v[236:239], v[86:89]
	v_mfma_f32_16x16x32_bf16 v[82:85], v[178:181], v[236:239], v[82:85]
	v_mfma_f32_16x16x32_bf16 v[70:73], v[170:173], v[244:247], v[70:73]
	v_mfma_f32_16x16x32_bf16 v[66:69], v[178:181], v[244:247], v[66:69]
	s_setprio 0
	s_barrier
	s_add_i32 s53, s53, s39
	s_mov_b32 m0, s53
	ds_read_b128 v[182:185], v156 offset:16384
	ds_read_b128 v[202:205], v156 offset:17408
	ds_read_b128 v[206:209], v156 offset:18432
	ds_read_b128 v[210:213], v156 offset:19456
	ds_read_b128 v[232:235], v156 offset:20480
	ds_read_b128 v[236:239], v156 offset:21504
	ds_read_b128 v[240:243], v156 offset:22528
	ds_read_b128 v[244:247], v156 offset:23552
	s_add_u32 s60, s28, 0x80
	s_addc_u32 s61, s29, 0
	s_add_u32 s62, s30, 0x80
	s_addc_u32 s63, s31, 0
	global_load_lds_dwordx4 v132, s[28:29]
	s_add_i32 m0, s53, 0x2000
	s_add_u32 s54, s28, 0x40000
	s_addc_u32 s55, s29, 0
	s_add_i32 s53, s56, s39
	global_load_lds_dwordx4 v136, s[28:29]
	s_mov_b32 m0, s53
	s_nop 0
	global_load_lds_dwordx4 v132, s[54:55]
	s_add_i32 m0, s53, 0x2000
	s_nop 0
	global_load_lds_dwordx4 v136, s[54:55]
	s_mov_b32 m0, s40
	s_nop 0
	global_load_lds_dwordx4 v130, s[30:31]
	s_mov_b32 m0, s41
	s_nop 0
	global_load_lds_dwordx4 v134, s[30:31]
	s_waitcnt vmcnt(8) lgkmcnt(0)
	s_setprio 1
	s_barrier
	v_mfma_f32_16x16x32_bf16 v[62:65], v[142:145], v[182:185], v[62:65]
	v_mfma_f32_16x16x32_bf16 v[58:61], v[158:161], v[182:185], v[58:61]
	v_mfma_f32_16x16x32_bf16 v[46:49], v[142:145], v[206:209], v[46:49]
	v_mfma_f32_16x16x32_bf16 v[42:45], v[158:161], v[206:209], v[42:45]
	v_mfma_f32_16x16x32_bf16 v[30:33], v[142:145], v[232:235], v[30:33]
	v_mfma_f32_16x16x32_bf16 v[26:29], v[158:161], v[232:235], v[26:29]
	v_mfma_f32_16x16x32_bf16 v[14:17], v[142:145], v[240:243], v[14:17]
	v_mfma_f32_16x16x32_bf16 v[10:13], v[158:161], v[240:243], v[10:13]
	v_mfma_f32_16x16x32_bf16 v[62:65], v[146:149], v[202:205], v[62:65]
	v_mfma_f32_16x16x32_bf16 v[58:61], v[162:165], v[202:205], v[58:61]
	v_mfma_f32_16x16x32_bf16 v[46:49], v[146:149], v[210:213], v[46:49]
	v_mfma_f32_16x16x32_bf16 v[42:45], v[162:165], v[210:213], v[42:45]
	v_mfma_f32_16x16x32_bf16 v[30:33], v[146:149], v[236:239], v[30:33]
	v_mfma_f32_16x16x32_bf16 v[26:29], v[162:165], v[236:239], v[26:29]
	v_mfma_f32_16x16x32_bf16 v[14:17], v[146:149], v[244:247], v[14:17]
	v_mfma_f32_16x16x32_bf16 v[10:13], v[162:165], v[244:247], v[10:13]
	s_setprio 0
	s_setprio 1
	v_mfma_f32_16x16x32_bf16 v[54:57], v[166:169], v[182:185], v[54:57]
	v_mfma_f32_16x16x32_bf16 v[50:53], v[174:177], v[182:185], v[50:53]
	v_mfma_f32_16x16x32_bf16 v[38:41], v[166:169], v[206:209], v[38:41]
	v_mfma_f32_16x16x32_bf16 v[34:37], v[174:177], v[206:209], v[34:37]
	v_mfma_f32_16x16x32_bf16 v[22:25], v[166:169], v[232:235], v[22:25]
	v_mfma_f32_16x16x32_bf16 v[18:21], v[174:177], v[232:235], v[18:21]
	v_mfma_f32_16x16x32_bf16 v[6:9], v[166:169], v[240:243], v[6:9]
	v_mfma_f32_16x16x32_bf16 v[2:5], v[174:177], v[240:243], v[2:5]
	v_mfma_f32_16x16x32_bf16 v[54:57], v[170:173], v[202:205], v[54:57]
	v_mfma_f32_16x16x32_bf16 v[50:53], v[178:181], v[202:205], v[50:53]
	v_mfma_f32_16x16x32_bf16 v[38:41], v[170:173], v[210:213], v[38:41]
	v_mfma_f32_16x16x32_bf16 v[34:37], v[178:181], v[210:213], v[34:37]
	v_mfma_f32_16x16x32_bf16 v[22:25], v[170:173], v[236:239], v[22:25]
	v_mfma_f32_16x16x32_bf16 v[18:21], v[178:181], v[236:239], v[18:21]
	v_mfma_f32_16x16x32_bf16 v[6:9], v[170:173], v[244:247], v[6:9]
	v_mfma_f32_16x16x32_bf16 v[2:5], v[178:181], v[244:247], v[2:5]
	s_setprio 0
	s_barrier
; #define PG8_STAGE(bufoff, gbase, voff) do { _Pragma("unroll") for (int _i = 0; _i < 2; ++_i) \
;         __builtin_amdgcn_global_load_lds((const unsigned*)((const char*)(gbase) + (voff)[_i]), (PG8_LAS unsigned*)(lds + (bufoff) + ldsw + _i * 8192), 16, 0, 0); } while (0)
; #define PG8_LDA(dst, b, h) do { _Pragma("unroll") for (int m = 0; m < 4; ++m) _Pragma("unroll") for (int k = 0; k < 2; ++k) dst[m][k] = *(const PG8_LAS bf16x8*)(lds + PG8_SA(b, h) + aoff + m * 2048 + k * 1024); } while (0)
; #define PG8_LDB(dst, b, h) do { _Pragma("unroll") for (int n = 0; n < 2; ++n) _Pragma("unroll") for (int k = 0; k < 2; ++k) dst[n][k] = *(const PG8_LAS bf16x8*)(lds + PG8_SB(b, h) + boff + n * 2048 + k * 1024); } while (0)
; #define PG8_MMA(ai, bj, At, Bt) do { __builtin_amdgcn_s_setprio(1); _Pragma("unroll") for (int m = 0; m < 4; ++m) _Pragma("unroll") for (int n = 0; n < 2; ++n) _Pragma("unroll") for (int k = 0; k < 2; ++k) \
;         acc[ai][bj][m][n] = __builtin_amdgcn_mfma_f32_16x16x32_bf16(Bt[n][k], At[m][k], acc[ai][bj][m][n], 0, 0, 0); __builtin_amdgcn_s_setprio(0); } while (0)
; #define PG8_WAIT_V(n) asm volatile("s_waitcnt vmcnt(" #n ")" ::: "memory")
; #define PG8_WAIT_L(n) asm volatile("s_waitcnt lgkmcnt(" #n ")" ::: "memory")
; #define PG8_BAR __builtin_amdgcn_s_barrier()
; #define PG8_SCHED __builtin_amdgcn_sched_barrier(0)
; template <class Epi, class Sched, bool ALIGN_EPI = false, bool SP2 = false>
; __device__ __forceinline__ void gemm_phase(PG8_LAS unsigned char* lds, const Gemm g, const Sched& S, const Epi& E) {
;     ...
;             PG8_LDB(B0, 1, 0); PG8_LDB(B1, 1, 1); PG8_SCHED; PG8_LDA(At, 1, 0); PG8_STAGE(PG8_SA(0, 1), a2 + hstepA, voffA);
;             PG8_WAIT_V(8); PG8_WAIT_L(0); PG8_BAR; PG8_MMA(0, 0, At, B0); PG8_MMA(0, 1, At, B1); PG8_BAR; PG8_SCHED;
;             PG8_LDA(At, 1, 1); PG8_STAGE(PG8_SB(1, 0), b3, voffB); PG8_STAGE(PG8_SB(1, 1), b3 + hstepB, voffB); PG8_STAGE(PG8_SA(1, 0), a3, voffA);
;             PG8_WAIT_V(8); PG8_WAIT_L(0); PG8_BAR; PG8_MMA(1, 0, At, B0); PG8_MMA(1, 1, At, B1); PG8_BAR; PG8_SCHED;
;     ...
;         }
;         if constexpr (ALIGN_EPI) { if (wr == 0) PG8_BAR; }
	s_add_i32 s53, 0, 0x18000
	v_add_u32_e32 v157, s53, v153
	s_add_i32 s54, 0, 0x1c000
	ds_read_b128 v[142:145], v157
	ds_read_b128 v[146:149], v157 offset:1024
	ds_read_b128 v[158:161], v157 offset:2048
	ds_read_b128 v[162:165], v157 offset:3072
	v_add_u32_e32 v157, s54, v153
	ds_read_b128 v[166:169], v157
	ds_read_b128 v[170:173], v157 offset:1024
	ds_read_b128 v[174:177], v157 offset:2048
	ds_read_b128 v[178:181], v157 offset:3072
	s_add_u32 s30, s30, 0x40000
	s_addc_u32 s31, s31, 0
	s_mov_b32 m0, s42
	ds_read_b128 v[182:185], v156 offset:32768
	ds_read_b128 v[202:205], v156 offset:33792
	ds_read_b128 v[206:209], v156 offset:34816
	ds_read_b128 v[210:213], v156 offset:35840
	ds_read_b128 v[232:235], v156 offset:36864
	ds_read_b128 v[236:239], v156 offset:37888
	ds_read_b128 v[240:243], v156 offset:38912
	ds_read_b128 v[244:247], v156 offset:39936
	global_load_lds_dwordx4 v130, s[30:31]
	s_mov_b32 m0, s43
	s_nop 0
	global_load_lds_dwordx4 v134, s[30:31]
	s_waitcnt vmcnt(8) lgkmcnt(0)
	s_setprio 1
	s_barrier
	v_mfma_f32_16x16x32_bf16 v[126:129], v[142:145], v[182:185], v[126:129]
	v_mfma_f32_16x16x32_bf16 v[122:125], v[158:161], v[182:185], v[122:125]
	v_mfma_f32_16x16x32_bf16 v[110:113], v[142:145], v[206:209], v[110:113]
	v_mfma_f32_16x16x32_bf16 v[106:109], v[158:161], v[206:209], v[106:109]
	v_mfma_f32_16x16x32_bf16 v[94:97], v[142:145], v[232:235], v[94:97]
	v_mfma_f32_16x16x32_bf16 v[90:93], v[158:161], v[232:235], v[90:93]
	v_mfma_f32_16x16x32_bf16 v[78:81], v[142:145], v[240:243], v[78:81]
	v_mfma_f32_16x16x32_bf16 v[74:77], v[158:161], v[240:243], v[74:77]
	v_mfma_f32_16x16x32_bf16 v[126:129], v[146:149], v[202:205], v[126:129]
	v_mfma_f32_16x16x32_bf16 v[122:125], v[162:165], v[202:205], v[122:125]
	v_mfma_f32_16x16x32_bf16 v[110:113], v[146:149], v[210:213], v[110:113]
	v_mfma_f32_16x16x32_bf16 v[106:109], v[162:165], v[210:213], v[106:109]
	v_mfma_f32_16x16x32_bf16 v[94:97], v[146:149], v[236:239], v[94:97]
	v_mfma_f32_16x16x32_bf16 v[90:93], v[162:165], v[236:239], v[90:93]
	v_mfma_f32_16x16x32_bf16 v[78:81], v[146:149], v[244:247], v[78:81]
	v_mfma_f32_16x16x32_bf16 v[74:77], v[162:165], v[244:247], v[74:77]
	s_setprio 0
	s_setprio 1
	v_mfma_f32_16x16x32_bf16 v[118:121], v[166:169], v[182:185], v[118:121]
	v_mfma_f32_16x16x32_bf16 v[114:117], v[174:177], v[182:185], v[114:117]
	v_mfma_f32_16x16x32_bf16 v[102:105], v[166:169], v[206:209], v[102:105]
	v_mfma_f32_16x16x32_bf16 v[98:101], v[174:177], v[206:209], v[98:101]
	v_mfma_f32_16x16x32_bf16 v[86:89], v[166:169], v[232:235], v[86:89]
	v_mfma_f32_16x16x32_bf16 v[82:85], v[174:177], v[232:235], v[82:85]
	v_mfma_f32_16x16x32_bf16 v[70:73], v[166:169], v[240:243], v[70:73]
	v_mfma_f32_16x16x32_bf16 v[66:69], v[174:177], v[240:243], v[66:69]
	v_mfma_f32_16x16x32_bf16 v[118:121], v[170:173], v[202:205], v[118:121]
	v_mfma_f32_16x16x32_bf16 v[114:117], v[178:181], v[202:205], v[114:117]
	v_mfma_f32_16x16x32_bf16 v[102:105], v[170:173], v[210:213], v[102:105]
	v_mfma_f32_16x16x32_bf16 v[98:101], v[178:181], v[210:213], v[98:101]
	v_mfma_f32_16x16x32_bf16 v[86:89], v[170:173], v[236:239], v[86:89]
	v_mfma_f32_16x16x32_bf16 v[82:85], v[178:181], v[236:239], v[82:85]
	v_mfma_f32_16x16x32_bf16 v[70:73], v[170:173], v[244:247], v[70:73]
	v_mfma_f32_16x16x32_bf16 v[66:69], v[178:181], v[244:247], v[66:69]
	s_setprio 0
	s_barrier
	s_add_i32 s30, s53, s39
	s_mov_b32 m0, s30
	ds_read_b128 v[182:185], v156 offset:49152
	ds_read_b128 v[202:205], v156 offset:50176
	ds_read_b128 v[206:209], v156 offset:51200
	ds_read_b128 v[210:213], v156 offset:52224
	ds_read_b128 v[232:235], v156 offset:53248
	ds_read_b128 v[236:239], v156 offset:54272
	ds_read_b128 v[240:243], v156 offset:55296
	ds_read_b128 v[244:247], v156 offset:56320
	global_load_lds_dwordx4 v132, s[60:61]
	s_add_i32 m0, s30, 0x2000
	s_add_u32 s28, s28, 0x40080
	s_addc_u32 s29, s29, 0
	s_add_i32 s30, s54, s39
	global_load_lds_dwordx4 v136, s[60:61]
	s_mov_b32 m0, s30
	s_nop 0
	global_load_lds_dwordx4 v132, s[28:29]
	s_add_i32 m0, s30, 0x2000
	s_nop 0
	global_load_lds_dwordx4 v136, s[28:29]
	s_mov_b32 m0, s45
	s_nop 0
	global_load_lds_dwordx4 v130, s[62:63]
	s_mov_b32 m0, s46
	s_nop 0
	global_load_lds_dwordx4 v134, s[62:63]
	s_waitcnt vmcnt(8) lgkmcnt(0)
	s_setprio 1
	s_barrier
	v_mfma_f32_16x16x32_bf16 v[62:65], v[142:145], v[182:185], v[62:65]
	v_mfma_f32_16x16x32_bf16 v[58:61], v[158:161], v[182:185], v[58:61]
	v_mfma_f32_16x16x32_bf16 v[46:49], v[142:145], v[206:209], v[46:49]
	v_mfma_f32_16x16x32_bf16 v[42:45], v[158:161], v[206:209], v[42:45]
	v_mfma_f32_16x16x32_bf16 v[30:33], v[142:145], v[232:235], v[30:33]
	v_mfma_f32_16x16x32_bf16 v[26:29], v[158:161], v[232:235], v[26:29]
	v_mfma_f32_16x16x32_bf16 v[14:17], v[142:145], v[240:243], v[14:17]
	v_mfma_f32_16x16x32_bf16 v[10:13], v[158:161], v[240:243], v[10:13]
	v_mfma_f32_16x16x32_bf16 v[62:65], v[146:149], v[202:205], v[62:65]
	v_mfma_f32_16x16x32_bf16 v[58:61], v[162:165], v[202:205], v[58:61]
	v_mfma_f32_16x16x32_bf16 v[46:49], v[146:149], v[210:213], v[46:49]
	v_mfma_f32_16x16x32_bf16 v[42:45], v[162:165], v[210:213], v[42:45]
	v_mfma_f32_16x16x32_bf16 v[30:33], v[146:149], v[236:239], v[30:33]
	v_mfma_f32_16x16x32_bf16 v[26:29], v[162:165], v[236:239], v[26:29]
	v_mfma_f32_16x16x32_bf16 v[14:17], v[146:149], v[244:247], v[14:17]
	v_mfma_f32_16x16x32_bf16 v[10:13], v[162:165], v[244:247], v[10:13]
	s_setprio 0
	s_setprio 1
	v_mfma_f32_16x16x32_bf16 v[54:57], v[166:169], v[182:185], v[54:57]
	v_mfma_f32_16x16x32_bf16 v[50:53], v[174:177], v[182:185], v[50:53]
	v_mfma_f32_16x16x32_bf16 v[38:41], v[166:169], v[206:209], v[38:41]
	v_mfma_f32_16x16x32_bf16 v[34:37], v[174:177], v[206:209], v[34:37]
	v_mfma_f32_16x16x32_bf16 v[22:25], v[166:169], v[232:235], v[22:25]
	v_mfma_f32_16x16x32_bf16 v[18:21], v[174:177], v[232:235], v[18:21]
	v_mfma_f32_16x16x32_bf16 v[6:9], v[166:169], v[240:243], v[6:9]
	v_mfma_f32_16x16x32_bf16 v[2:5], v[174:177], v[240:243], v[2:5]
	v_mfma_f32_16x16x32_bf16 v[54:57], v[170:173], v[202:205], v[54:57]
	v_mfma_f32_16x16x32_bf16 v[50:53], v[178:181], v[202:205], v[50:53]
	v_mfma_f32_16x16x32_bf16 v[38:41], v[170:173], v[210:213], v[38:41]
	v_mfma_f32_16x16x32_bf16 v[34:37], v[178:181], v[210:213], v[34:37]
	v_mfma_f32_16x16x32_bf16 v[22:25], v[170:173], v[236:239], v[22:25]
	v_mfma_f32_16x16x32_bf16 v[18:21], v[178:181], v[236:239], v[18:21]
	v_mfma_f32_16x16x32_bf16 v[6:9], v[170:173], v[244:247], v[6:9]
	v_mfma_f32_16x16x32_bf16 v[2:5], v[178:181], v[244:247], v[2:5]
	s_setprio 0
	s_barrier
	s_add_i32 s52, s52, 2
	s_add_u32 s26, s26, 0x100
	s_addc_u32 s27, s27, 0
	s_add_u32 s50, s50, 0x100
	s_addc_u32 s51, s51, 0
	s_cmp_gt_u32 s52, 13
	s_cbranch_scc0 .LBB0_254
	s_and_b64 vcc, exec, s[16:17]
	s_cbranch_vccz .LBB0_257
	s_barrier

; #define PG8_STAGE(bufoff, gbase, voff) do { _Pragma("unroll") for (int _i = 0; _i < 2; ++_i) \
;         __builtin_amdgcn_global_load_lds((const unsigned*)((const char*)(gbase) + (voff)[_i]), (PG8_LAS unsigned*)(lds + (bufoff) + ldsw + _i * 8192), 16, 0, 0); } while (0)
; #define PG8_LDA(dst, b, h) do { _Pragma("unroll") for (int m = 0; m < 4; ++m) _Pragma("unroll") for (int k = 0; k < 2; ++k) dst[m][k] = *(const PG8_LAS bf16x8*)(lds + PG8_SA(b, h) + aoff + m * 2048 + k * 1024); } while (0)
; #define PG8_LDB(dst, b, h) do { _Pragma("unroll") for (int n = 0; n < 2; ++n) _Pragma("unroll") for (int k = 0; k < 2; ++k) dst[n][k] = *(const PG8_LAS bf16x8*)(lds + PG8_SB(b, h) + boff + n * 2048 + k * 1024); } while (0)
; #define PG8_MMA(ai, bj, At, Bt) do { __builtin_amdgcn_s_setprio(1); _Pragma("unroll") for (int m = 0; m < 4; ++m) _Pragma("unroll") for (int n = 0; n < 2; ++n) _Pragma("unroll") for (int k = 0; k < 2; ++k) \
;         acc[ai][bj][m][n] = __builtin_amdgcn_mfma_f32_16x16x32_bf16(Bt[n][k], At[m][k], acc[ai][bj][m][n], 0, 0, 0); __builtin_amdgcn_s_setprio(0); } while (0)
; #define PG8_WAIT_V(n) asm volatile("s_waitcnt vmcnt(" #n ")" ::: "memory")
; #define PG8_WAIT_L(n) asm volatile("s_waitcnt lgkmcnt(" #n ")" ::: "memory")
; #define PG8_BAR __builtin_amdgcn_s_barrier()
; #define PG8_SCHED __builtin_amdgcn_sched_barrier(0)
; template <class Epi, class Sched, bool ALIGN_EPI = false, bool SP2 = false>
; __device__ __forceinline__ void gemm_phase(PG8_LAS unsigned char* lds, const Gemm g, const Sched& S, const Epi& E) {
;     ...
;             PG8_LDB(B0, 0, 0); PG8_LDB(B1, 0, 1); PG8_SCHED; PG8_LDA(At, 0, 0); PG8_STAGE(PG8_SA(1, 1), a1 + hstepA, voffA);
;             PG8_WAIT_V(8); PG8_WAIT_L(0); PG8_BAR; PG8_MMA(0, 0, At, B0); PG8_MMA(0, 1, At, B1); PG8_BAR; PG8_SCHED;
;             PG8_LDA(At, 0, 1); PG8_STAGE(PG8_SB(0, 0), b2, voffB); PG8_STAGE(PG8_SB(0, 1), b2 + hstepB, voffB); PG8_STAGE(PG8_SA(0, 0), a2, voffA);
;             PG8_WAIT_V(8); PG8_WAIT_L(0); PG8_BAR; PG8_MMA(1, 0, At, B0); PG8_MMA(1, 1, At, B1); PG8_BAR; PG8_SCHED;
.LBB0_448:
	s_add_u32 s16, s38, s14
	s_addc_u32 s17, s39, s15
	s_add_u32 s16, s16, 0x4e00100
	s_addc_u32 s17, s17, 0
	s_add_u32 s43, s40, s14
	s_addc_u32 s44, s41, s15
	s_add_i32 s45, 0, 0x10000
	v_add_u32_e32 v96, s45, v82
	ds_read_b128 v[84:87], v96
	ds_read_b128 v[88:91], v96 offset:1024
	ds_read_b128 v[92:95], v96 offset:2048
	ds_read_b128 v[96:99], v96 offset:3072
	s_cmpk_eq_i32 s14, 0x700
	s_cselect_b32 s19, s13, s17
	s_cselect_b32 s18, s12, s16
	s_cselect_b32 s17, s5, s44
	s_cselect_b32 s16, s4, s43
	v_lshl_add_u64 v[132:133], v[76:77], 0, s[14:15]
	s_add_i32 m0, s25, 0xc000
	ds_read_b128 v[100:103], v83
	ds_read_b128 v[104:107], v83 offset:1024
	ds_read_b128 v[108:111], v83 offset:2048
	ds_read_b128 v[112:115], v83 offset:3072
	ds_read_b128 v[116:119], v83 offset:4096
	ds_read_b128 v[120:123], v83 offset:5120
	ds_read_b128 v[124:127], v83 offset:6144
	ds_read_b128 v[128:131], v83 offset:7168
	global_load_lds_dwordx4 v[132:133], off
	v_lshl_add_u64 v[132:133], v[78:79], 0, s[14:15]
	s_add_i32 m0, s25, 0xe000
	s_nop 0
	global_load_lds_dwordx4 v[132:133], off
	s_waitcnt vmcnt(8) lgkmcnt(0)
	s_setprio 1
	s_barrier
	v_mfma_f32_16x16x32_bf16 v[62:65], v[84:87], v[100:103], v[62:65]
	v_mfma_f32_16x16x32_bf16 v[58:61], v[92:95], v[100:103], v[58:61]
	v_mfma_f32_16x16x32_bf16 v[54:57], v[84:87], v[108:111], v[54:57]
	v_mfma_f32_16x16x32_bf16 v[50:53], v[92:95], v[108:111], v[50:53]
	v_mfma_f32_16x16x32_bf16 v[46:49], v[84:87], v[116:119], v[46:49]
	v_mfma_f32_16x16x32_bf16 v[42:45], v[92:95], v[116:119], v[42:45]
	v_mfma_f32_16x16x32_bf16 v[38:41], v[84:87], v[124:127], v[38:41]
	v_mfma_f32_16x16x32_bf16 v[34:37], v[92:95], v[124:127], v[34:37]
	v_mfma_f32_16x16x32_bf16 v[62:65], v[88:91], v[104:107], v[62:65]
	v_mfma_f32_16x16x32_bf16 v[58:61], v[96:99], v[104:107], v[58:61]
	v_mfma_f32_16x16x32_bf16 v[54:57], v[88:91], v[112:115], v[54:57]
	v_mfma_f32_16x16x32_bf16 v[50:53], v[96:99], v[112:115], v[50:53]
	v_mfma_f32_16x16x32_bf16 v[46:49], v[88:91], v[120:123], v[46:49]
	v_mfma_f32_16x16x32_bf16 v[42:45], v[96:99], v[120:123], v[42:45]
	v_mfma_f32_16x16x32_bf16 v[38:41], v[88:91], v[128:131], v[38:41]
	v_mfma_f32_16x16x32_bf16 v[34:37], v[96:99], v[128:131], v[34:37]
	s_setprio 0
	s_setprio 1
	s_setprio 0
	s_barrier
	s_add_i32 s43, s45, s24
	v_lshl_add_u64 v[132:133], s[16:17], 0, v[72:73]
	s_mov_b32 m0, s43
	ds_read_b128 v[100:103], v83 offset:16384
	ds_read_b128 v[104:107], v83 offset:17408
	ds_read_b128 v[108:111], v83 offset:18432
	ds_read_b128 v[112:115], v83 offset:19456
	ds_read_b128 v[116:119], v83 offset:20480
	ds_read_b128 v[120:123], v83 offset:21504
	ds_read_b128 v[124:127], v83 offset:22528
	ds_read_b128 v[128:131], v83 offset:23552
	global_load_lds_dwordx4 v[132:133], off
	s_add_i32 m0, s43, 0x2000
	s_add_u32 s44, s16, 0x40000
	v_lshl_add_u64 v[134:135], s[16:17], 0, v[68:69]
	s_addc_u32 s45, s17, 0
	global_load_lds_dwordx4 v[134:135], off
	v_lshl_add_u64 v[136:137], s[44:45], 0, v[72:73]
	s_mov_b32 m0, s26
	v_lshl_add_u64 v[138:139], s[18:19], 0, v[70:71]
	global_load_lds_dwordx4 v[136:137], off
	v_lshl_add_u64 v[136:137], s[44:45], 0, v[68:69]
	s_mov_b32 m0, s27
	s_nop 0
	global_load_lds_dwordx4 v[136:137], off
	v_lshl_add_u64 v[136:137], s[18:19], 0, v[74:75]
	s_mov_b32 m0, s25
	s_nop 0
	global_load_lds_dwordx4 v[136:137], off
	s_mov_b32 m0, s28
	s_nop 0
	global_load_lds_dwordx4 v[138:139], off
	s_waitcnt vmcnt(8) lgkmcnt(0)
	s_setprio 1
	s_barrier
	v_mfma_f32_16x16x32_bf16 v[30:33], v[84:87], v[100:103], v[30:33]
	v_mfma_f32_16x16x32_bf16 v[26:29], v[92:95], v[100:103], v[26:29]
	v_mfma_f32_16x16x32_bf16 v[22:25], v[84:87], v[108:111], v[22:25]
	v_mfma_f32_16x16x32_bf16 v[18:21], v[92:95], v[108:111], v[18:21]
	v_mfma_f32_16x16x32_bf16 v[14:17], v[84:87], v[116:119], v[14:17]
	v_mfma_f32_16x16x32_bf16 v[10:13], v[92:95], v[116:119], v[10:13]
	v_mfma_f32_16x16x32_bf16 v[6:9], v[84:87], v[124:127], v[6:9]
	v_mfma_f32_16x16x32_bf16 v[2:5], v[92:95], v[124:127], v[2:5]
	v_mfma_f32_16x16x32_bf16 v[30:33], v[88:91], v[104:107], v[30:33]
	v_mfma_f32_16x16x32_bf16 v[26:29], v[96:99], v[104:107], v[26:29]
	v_mfma_f32_16x16x32_bf16 v[22:25], v[88:91], v[112:115], v[22:25]
	v_mfma_f32_16x16x32_bf16 v[18:21], v[96:99], v[112:115], v[18:21]
	v_mfma_f32_16x16x32_bf16 v[14:17], v[88:91], v[120:123], v[14:17]
	v_mfma_f32_16x16x32_bf16 v[10:13], v[96:99], v[120:123], v[10:13]
	v_mfma_f32_16x16x32_bf16 v[6:9], v[88:91], v[128:131], v[6:9]
	v_mfma_f32_16x16x32_bf16 v[2:5], v[96:99], v[128:131], v[2:5]
	s_setprio 0
	s_setprio 1
	s_setprio 0
	s_barrier
; #define PG8_STAGE(bufoff, gbase, voff) do { _Pragma("unroll") for (int _i = 0; _i < 2; ++_i) \
;         __builtin_amdgcn_global_load_lds((const unsigned*)((const char*)(gbase) + (voff)[_i]), (PG8_LAS unsigned*)(lds + (bufoff) + ldsw + _i * 8192), 16, 0, 0); } while (0)
; #define PG8_LDA(dst, b, h) do { _Pragma("unroll") for (int m = 0; m < 4; ++m) _Pragma("unroll") for (int k = 0; k < 2; ++k) dst[m][k] = *(const PG8_LAS bf16x8*)(lds + PG8_SA(b, h) + aoff + m * 2048 + k * 1024); } while (0)
; #define PG8_LDB(dst, b, h) do { _Pragma("unroll") for (int n = 0; n < 2; ++n) _Pragma("unroll") for (int k = 0; k < 2; ++k) dst[n][k] = *(const PG8_LAS bf16x8*)(lds + PG8_SB(b, h) + boff + n * 2048 + k * 1024); } while (0)
; #define PG8_MMA(ai, bj, At, Bt) do { __builtin_amdgcn_s_setprio(1); _Pragma("unroll") for (int m = 0; m < 4; ++m) _Pragma("unroll") for (int n = 0; n < 2; ++n) _Pragma("unroll") for (int k = 0; k < 2; ++k) \
;         acc[ai][bj][m][n] = __builtin_amdgcn_mfma_f32_16x16x32_bf16(Bt[n][k], At[m][k], acc[ai][bj][m][n], 0, 0, 0); __builtin_amdgcn_s_setprio(0); } while (0)
; #define PG8_WAIT_V(n) asm volatile("s_waitcnt vmcnt(" #n ")" ::: "memory")
; #define PG8_WAIT_L(n) asm volatile("s_waitcnt lgkmcnt(" #n ")" ::: "memory")
; #define PG8_BAR __builtin_amdgcn_s_barrier()
; #define PG8_SCHED __builtin_amdgcn_sched_barrier(0)
; template <class Epi, class Sched, bool ALIGN_EPI = false, bool SP2 = false>
; __device__ __forceinline__ void gemm_phase(PG8_LAS unsigned char* lds, const Gemm g, const Sched& S, const Epi& E) {
;     ...
;             PG8_LDB(B0, 1, 0); PG8_LDB(B1, 1, 1); PG8_SCHED; PG8_LDA(At, 1, 0); PG8_STAGE(PG8_SA(0, 1), a2 + hstepA, voffA);
;             PG8_WAIT_V(8); PG8_WAIT_L(0); PG8_BAR; PG8_MMA(0, 0, At, B0); PG8_MMA(0, 1, At, B1); PG8_BAR; PG8_SCHED;
;             PG8_LDA(At, 1, 1); PG8_STAGE(PG8_SB(1, 0), b3, voffB); PG8_STAGE(PG8_SB(1, 1), b3 + hstepB, voffB); PG8_STAGE(PG8_SA(1, 0), a3, voffA);
;             PG8_WAIT_V(8); PG8_WAIT_L(0); PG8_BAR; PG8_MMA(1, 0, At, B0); PG8_MMA(1, 1, At, B1); PG8_BAR; PG8_SCHED;
;     ...
;         }
;         if constexpr (ALIGN_EPI) { if (wr == 0) PG8_BAR; }
	s_add_i32 s43, 0, 0x18000
	v_add_u32_e32 v96, s43, v82
	ds_read_b128 v[84:87], v96
	ds_read_b128 v[88:91], v96 offset:1024
	ds_read_b128 v[92:95], v96 offset:2048
	ds_read_b128 v[96:99], v96 offset:3072
	s_add_u32 s18, s18, 0x40000
	s_addc_u32 s19, s19, 0
	s_mov_b32 m0, s29
	v_lshl_add_u64 v[140:141], s[18:19], 0, v[74:75]
	ds_read_b128 v[100:103], v83 offset:32768
	ds_read_b128 v[104:107], v83 offset:33792
	ds_read_b128 v[108:111], v83 offset:34816
	ds_read_b128 v[112:115], v83 offset:35840
	ds_read_b128 v[116:119], v83 offset:36864
	ds_read_b128 v[120:123], v83 offset:37888
	ds_read_b128 v[124:127], v83 offset:38912
	ds_read_b128 v[128:131], v83 offset:39936
	global_load_lds_dwordx4 v[140:141], off
	v_lshl_add_u64 v[140:141], s[18:19], 0, v[70:71]
	s_mov_b32 m0, s30
	s_nop 0
	global_load_lds_dwordx4 v[140:141], off
	s_waitcnt vmcnt(8) lgkmcnt(0)
	s_setprio 1
	s_barrier
	v_mfma_f32_16x16x32_bf16 v[62:65], v[84:87], v[100:103], v[62:65]
	v_mfma_f32_16x16x32_bf16 v[58:61], v[92:95], v[100:103], v[58:61]
	v_mfma_f32_16x16x32_bf16 v[54:57], v[84:87], v[108:111], v[54:57]
	v_mfma_f32_16x16x32_bf16 v[50:53], v[92:95], v[108:111], v[50:53]
	v_mfma_f32_16x16x32_bf16 v[46:49], v[84:87], v[116:119], v[46:49]
	v_mfma_f32_16x16x32_bf16 v[42:45], v[92:95], v[116:119], v[42:45]
	v_mfma_f32_16x16x32_bf16 v[38:41], v[84:87], v[124:127], v[38:41]
	v_mfma_f32_16x16x32_bf16 v[34:37], v[92:95], v[124:127], v[34:37]
	v_mfma_f32_16x16x32_bf16 v[62:65], v[88:91], v[104:107], v[62:65]
	v_mfma_f32_16x16x32_bf16 v[58:61], v[96:99], v[104:107], v[58:61]
	v_mfma_f32_16x16x32_bf16 v[54:57], v[88:91], v[112:115], v[54:57]
	v_mfma_f32_16x16x32_bf16 v[50:53], v[96:99], v[112:115], v[50:53]
	v_mfma_f32_16x16x32_bf16 v[46:49], v[88:91], v[120:123], v[46:49]
	v_mfma_f32_16x16x32_bf16 v[42:45], v[96:99], v[120:123], v[42:45]
	v_mfma_f32_16x16x32_bf16 v[38:41], v[88:91], v[128:131], v[38:41]
	v_mfma_f32_16x16x32_bf16 v[34:37], v[96:99], v[128:131], v[34:37]
	s_setprio 0
	s_setprio 1
	s_setprio 0
	s_barrier
	s_add_i32 s18, s43, s24
	v_lshl_add_u64 v[132:133], v[132:133], 0, s[96:97]
	s_mov_b32 m0, s18
	ds_read_b128 v[100:103], v83 offset:49152
	ds_read_b128 v[104:107], v83 offset:50176
	ds_read_b128 v[108:111], v83 offset:51200
	ds_read_b128 v[112:115], v83 offset:52224
	ds_read_b128 v[116:119], v83 offset:53248
	ds_read_b128 v[120:123], v83 offset:54272
	ds_read_b128 v[124:127], v83 offset:55296
	ds_read_b128 v[128:131], v83 offset:56320
	global_load_lds_dwordx4 v[132:133], off
	s_add_i32 m0, s18, 0x2000
	s_add_u32 s16, s16, 0x40080
	v_lshl_add_u64 v[132:133], v[134:135], 0, s[96:97]
	s_addc_u32 s17, s17, 0
	global_load_lds_dwordx4 v[132:133], off
	v_lshl_add_u64 v[132:133], s[16:17], 0, v[72:73]
	s_mov_b32 m0, s36
	s_nop 0
	global_load_lds_dwordx4 v[132:133], off
	v_lshl_add_u64 v[132:133], s[16:17], 0, v[68:69]
	s_mov_b32 m0, s37
	s_nop 0
	global_load_lds_dwordx4 v[132:133], off
	v_lshl_add_u64 v[132:133], v[136:137], 0, s[96:97]
	s_mov_b32 m0, s34
	s_nop 0
	global_load_lds_dwordx4 v[132:133], off
	v_lshl_add_u64 v[132:133], v[138:139], 0, s[96:97]
	s_mov_b32 m0, s35
	s_nop 0
	global_load_lds_dwordx4 v[132:133], off
	s_waitcnt vmcnt(8) lgkmcnt(0)
	s_setprio 1
	s_barrier
	v_mfma_f32_16x16x32_bf16 v[30:33], v[84:87], v[100:103], v[30:33]
	v_mfma_f32_16x16x32_bf16 v[26:29], v[92:95], v[100:103], v[26:29]
	v_mfma_f32_16x16x32_bf16 v[22:25], v[84:87], v[108:111], v[22:25]
	v_mfma_f32_16x16x32_bf16 v[18:21], v[92:95], v[108:111], v[18:21]
	v_mfma_f32_16x16x32_bf16 v[14:17], v[84:87], v[116:119], v[14:17]
	v_mfma_f32_16x16x32_bf16 v[10:13], v[92:95], v[116:119], v[10:13]
	v_mfma_f32_16x16x32_bf16 v[6:9], v[84:87], v[124:127], v[6:9]
	v_mfma_f32_16x16x32_bf16 v[2:5], v[92:95], v[124:127], v[2:5]
	v_mfma_f32_16x16x32_bf16 v[30:33], v[88:91], v[104:107], v[30:33]
	v_mfma_f32_16x16x32_bf16 v[26:29], v[96:99], v[104:107], v[26:29]
	v_mfma_f32_16x16x32_bf16 v[22:25], v[88:91], v[112:115], v[22:25]
	v_mfma_f32_16x16x32_bf16 v[18:21], v[96:99], v[112:115], v[18:21]
	v_mfma_f32_16x16x32_bf16 v[14:17], v[88:91], v[120:123], v[14:17]
	v_mfma_f32_16x16x32_bf16 v[10:13], v[96:99], v[120:123], v[10:13]
	v_mfma_f32_16x16x32_bf16 v[6:9], v[88:91], v[128:131], v[6:9]
	v_mfma_f32_16x16x32_bf16 v[2:5], v[96:99], v[128:131], v[2:5]
	s_setprio 0
	s_setprio 1
	s_setprio 0
	s_barrier
	s_add_i32 s42, s42, 2
	s_add_u32 s14, s14, 0x100
	s_addc_u32 s15, s15, 0
	s_cmp_gt_u32 s42, 13
	s_cbranch_scc0 .LBB0_448
	s_cmpk_lt_u32 s23, 0x100
	s_cbranch_scc0 .LBB0_451
	s_barrier

; #define PG8_STAGE(bufoff, gbase, voff) do { _Pragma("unroll") for (int _i = 0; _i < 2; ++_i) \
;         __builtin_amdgcn_global_load_lds((const unsigned*)((const char*)(gbase) + (voff)[_i]), (PG8_LAS unsigned*)(lds + (bufoff) + ldsw + _i * 8192), 16, 0, 0); } while (0)
; #define PG8_LDA(dst, b, h) do { _Pragma("unroll") for (int m = 0; m < 4; ++m) _Pragma("unroll") for (int k = 0; k < 2; ++k) dst[m][k] = *(const PG8_LAS bf16x8*)(lds + PG8_SA(b, h) + aoff + m * 2048 + k * 1024); } while (0)
; #define PG8_LDB(dst, b, h) do { _Pragma("unroll") for (int n = 0; n < 2; ++n) _Pragma("unroll") for (int k = 0; k < 2; ++k) dst[n][k] = *(const PG8_LAS bf16x8*)(lds + PG8_SB(b, h) + boff + n * 2048 + k * 1024); } while (0)
; #define PG8_MMA(ai, bj, At, Bt) do { __builtin_amdgcn_s_setprio(1); _Pragma("unroll") for (int m = 0; m < 4; ++m) _Pragma("unroll") for (int n = 0; n < 2; ++n) _Pragma("unroll") for (int k = 0; k < 2; ++k) \
;         acc[ai][bj][m][n] = __builtin_amdgcn_mfma_f32_16x16x32_bf16(Bt[n][k], At[m][k], acc[ai][bj][m][n], 0, 0, 0); __builtin_amdgcn_s_setprio(0); } while (0)
; #define PG8_WAIT_V(n) asm volatile("s_waitcnt vmcnt(" #n ")" ::: "memory")
; #define PG8_BAR __builtin_amdgcn_s_barrier()
; template <class Epi, class Sched, bool ALIGN_EPI = false, bool SP2 = false>
; __device__ __forceinline__ void gemm_phase(PG8_LAS unsigned char* lds, const Gemm g, const Sched& S, const Epi& E) {
;     ...
;         for (int t = 0; t < nt; t += 2) {
;             const bool last = (t == nt - 2);
;             const char* a1 = cA + (size_t)(t + 1) * kstep;
;             const char* a2 = last ? nA : cA + (size_t)(t + 2) * kstep; const char* b2 = last ? nB : cB + (size_t)(t + 2) * kstep;
;             const char* a3 = a2 + kstep; const char* b3 = b2 + kstep;
;             if (last && has_next) S.a_ready(nxt);
;             if constexpr (SP2) {
;             PG8_LDB(B0, 0, 0); PG8_LDB(B1, 0, 1); PG8_SCHED; PG8_LDA(At, 0, 0); PG8_STAGE(PG8_SA(1, 1), a1 + hstepA, voffA);
;             PG8_WAIT_V(8); PG8_WAIT_L(0); PG8_BAR; PG8_MMA(0, 0, At, B0); PG8_MMA(0, 1, At, B1); PG8_BAR; PG8_SCHED;
;             PG8_LDA(At, 0, 1); PG8_STAGE(PG8_SB(0, 0), b2, voffB); PG8_STAGE(PG8_SB(0, 1), b2 + hstepB, voffB); PG8_STAGE(PG8_SA(0, 0), a2, voffA);
;             PG8_WAIT_V(8); PG8_WAIT_L(0); PG8_BAR; PG8_MMA(1, 0, At, B0); PG8_MMA(1, 1, At, B1); PG8_BAR; PG8_SCHED;
.LBB0_530:
	s_add_u32 s12, s1, s8
	s_addc_u32 s13, s28, s9
	s_add_u32 s12, s12, 0xfe00100
	s_addc_u32 s13, s13, 0
	s_add_u32 s34, s29, s8
	s_addc_u32 s35, s30, s9
	s_add_i32 s36, 0, 0x10000
	s_cmpk_eq_i32 s8, 0x700
	s_cselect_b32 s15, s7, s13
	s_cselect_b32 s14, s6, s12
	v_add_u32_e32 v145, s36, v143
	s_cselect_b32 s13, s5, s35
	s_cselect_b32 s12, s4, s34
	s_add_i32 s37, 0, 0x14000
	ds_read_b128 v[146:149], v145
	ds_read_b128 v[150:153], v145 offset:1024
	ds_read_b128 v[154:157], v145 offset:2048
	ds_read_b128 v[158:161], v145 offset:3072
	v_add_u32_e32 v145, s37, v143
	ds_read_b128 v[162:165], v145
	ds_read_b128 v[166:169], v145 offset:1024
	ds_read_b128 v[170:173], v145 offset:2048
	ds_read_b128 v[174:177], v145 offset:3072
	v_lshl_add_u64 v[186:187], v[138:139], 0, s[8:9]
	s_add_i32 m0, s21, 0xc000
	ds_read_b128 v[178:181], v144
	ds_read_b128 v[182:185], v144 offset:1024
	ds_read_b128 v[202:205], v144 offset:2048
	ds_read_b128 v[206:209], v144 offset:3072
	ds_read_b128 v[210:213], v144 offset:4096
	ds_read_b128 v[232:235], v144 offset:5120
	ds_read_b128 v[236:239], v144 offset:6144
	ds_read_b128 v[240:243], v144 offset:7168
	global_load_lds_dwordx4 v[186:187], off
	v_lshl_add_u64 v[186:187], v[140:141], 0, s[8:9]
	s_add_i32 m0, s21, 0xe000
	s_nop 0
	global_load_lds_dwordx4 v[186:187], off
	s_waitcnt vmcnt(8) lgkmcnt(0)
	s_setprio 1
	s_barrier
	v_mfma_f32_16x16x32_bf16 v[126:129], v[146:149], v[178:181], v[126:129]
	v_mfma_f32_16x16x32_bf16 v[122:125], v[154:157], v[178:181], v[122:125]
	v_mfma_f32_16x16x32_bf16 v[118:121], v[146:149], v[202:205], v[118:121]
	v_mfma_f32_16x16x32_bf16 v[114:117], v[154:157], v[202:205], v[114:117]
	v_mfma_f32_16x16x32_bf16 v[110:113], v[146:149], v[210:213], v[110:113]
	v_mfma_f32_16x16x32_bf16 v[106:109], v[154:157], v[210:213], v[106:109]
	v_mfma_f32_16x16x32_bf16 v[102:105], v[146:149], v[236:239], v[102:105]
	v_mfma_f32_16x16x32_bf16 v[98:101], v[154:157], v[236:239], v[98:101]
	v_mfma_f32_16x16x32_bf16 v[126:129], v[150:153], v[182:185], v[126:129]
	v_mfma_f32_16x16x32_bf16 v[122:125], v[158:161], v[182:185], v[122:125]
	v_mfma_f32_16x16x32_bf16 v[118:121], v[150:153], v[206:209], v[118:121]
	v_mfma_f32_16x16x32_bf16 v[114:117], v[158:161], v[206:209], v[114:117]
	v_mfma_f32_16x16x32_bf16 v[110:113], v[150:153], v[232:235], v[110:113]
	v_mfma_f32_16x16x32_bf16 v[106:109], v[158:161], v[232:235], v[106:109]
	v_mfma_f32_16x16x32_bf16 v[102:105], v[150:153], v[240:243], v[102:105]
	v_mfma_f32_16x16x32_bf16 v[98:101], v[158:161], v[240:243], v[98:101]
	s_setprio 0
	s_setprio 1
	v_mfma_f32_16x16x32_bf16 v[94:97], v[162:165], v[178:181], v[94:97]
	v_mfma_f32_16x16x32_bf16 v[86:89], v[170:173], v[178:181], v[86:89]
	v_mfma_f32_16x16x32_bf16 v[78:81], v[162:165], v[202:205], v[78:81]
	v_mfma_f32_16x16x32_bf16 v[74:77], v[170:173], v[202:205], v[74:77]
	v_mfma_f32_16x16x32_bf16 v[70:73], v[162:165], v[210:213], v[70:73]
	v_mfma_f32_16x16x32_bf16 v[62:65], v[170:173], v[210:213], v[62:65]
	v_mfma_f32_16x16x32_bf16 v[54:57], v[162:165], v[236:239], v[54:57]
	v_mfma_f32_16x16x32_bf16 v[50:53], v[170:173], v[236:239], v[50:53]
	v_mfma_f32_16x16x32_bf16 v[94:97], v[166:169], v[182:185], v[94:97]
	v_mfma_f32_16x16x32_bf16 v[86:89], v[174:177], v[182:185], v[86:89]
	v_mfma_f32_16x16x32_bf16 v[78:81], v[166:169], v[206:209], v[78:81]
	v_mfma_f32_16x16x32_bf16 v[74:77], v[174:177], v[206:209], v[74:77]
	v_mfma_f32_16x16x32_bf16 v[70:73], v[166:169], v[232:235], v[70:73]
	v_mfma_f32_16x16x32_bf16 v[62:65], v[174:177], v[232:235], v[62:65]
	v_mfma_f32_16x16x32_bf16 v[54:57], v[166:169], v[240:243], v[54:57]
	v_mfma_f32_16x16x32_bf16 v[50:53], v[174:177], v[240:243], v[50:53]
	s_setprio 0
	s_barrier
	s_add_i32 s34, s36, s20
	s_mov_b32 m0, s34
	ds_read_b128 v[178:181], v144 offset:16384
	ds_read_b128 v[182:185], v144 offset:17408
	ds_read_b128 v[202:205], v144 offset:18432
	ds_read_b128 v[206:209], v144 offset:19456
	ds_read_b128 v[210:213], v144 offset:20480
	ds_read_b128 v[232:235], v144 offset:21504
	ds_read_b128 v[236:239], v144 offset:22528
	ds_read_b128 v[240:243], v144 offset:23552
	s_add_u32 s60, s12, 0x80
	s_addc_u32 s61, s13, 0
	s_add_u32 s62, s14, 0x80
	s_addc_u32 s63, s15, 0
	global_load_lds_dwordx4 v134, s[12:13]
	s_add_i32 m0, s34, 0x2000
	s_add_u32 s34, s12, 0x80000
	s_addc_u32 s35, s13, 0
	s_add_i32 s36, s37, s20
	global_load_lds_dwordx4 v130, s[12:13]
	s_mov_b32 m0, s36
	s_nop 0
	global_load_lds_dwordx4 v134, s[34:35]
	s_add_i32 m0, s36, 0x2000
	s_nop 0
	global_load_lds_dwordx4 v130, s[34:35]
	s_mov_b32 m0, s21
	s_nop 0
	global_load_lds_dwordx4 v136, s[14:15]
	s_mov_b32 m0, s22
	s_nop 0
	global_load_lds_dwordx4 v132, s[14:15]
	s_waitcnt vmcnt(8) lgkmcnt(0)
	s_setprio 1
	s_barrier
; #define PG8_STAGE(bufoff, gbase, voff) do { _Pragma("unroll") for (int _i = 0; _i < 2; ++_i) \
;         __builtin_amdgcn_global_load_lds((const unsigned*)((const char*)(gbase) + (voff)[_i]), (PG8_LAS unsigned*)(lds + (bufoff) + ldsw + _i * 8192), 16, 0, 0); } while (0)
; #define PG8_LDA(dst, b, h) do { _Pragma("unroll") for (int m = 0; m < 4; ++m) _Pragma("unroll") for (int k = 0; k < 2; ++k) dst[m][k] = *(const PG8_LAS bf16x8*)(lds + PG8_SA(b, h) + aoff + m * 2048 + k * 1024); } while (0)
; #define PG8_LDB(dst, b, h) do { _Pragma("unroll") for (int n = 0; n < 2; ++n) _Pragma("unroll") for (int k = 0; k < 2; ++k) dst[n][k] = *(const PG8_LAS bf16x8*)(lds + PG8_SB(b, h) + boff + n * 2048 + k * 1024); } while (0)
; #define PG8_MMA(ai, bj, At, Bt) do { __builtin_amdgcn_s_setprio(1); _Pragma("unroll") for (int m = 0; m < 4; ++m) _Pragma("unroll") for (int n = 0; n < 2; ++n) _Pragma("unroll") for (int k = 0; k < 2; ++k) \
;         acc[ai][bj][m][n] = __builtin_amdgcn_mfma_f32_16x16x32_bf16(Bt[n][k], At[m][k], acc[ai][bj][m][n], 0, 0, 0); __builtin_amdgcn_s_setprio(0); } while (0)
; #define PG8_WAIT_V(n) asm volatile("s_waitcnt vmcnt(" #n ")" ::: "memory")
; #define PG8_WAIT_L(n) asm volatile("s_waitcnt lgkmcnt(" #n ")" ::: "memory")
; #define PG8_BAR __builtin_amdgcn_s_barrier()
; #define PG8_SCHED __builtin_amdgcn_sched_barrier(0)
; template <class Epi, class Sched, bool ALIGN_EPI = false, bool SP2 = false>
; __device__ __forceinline__ void gemm_phase(PG8_LAS unsigned char* lds, const Gemm g, const Sched& S, const Epi& E) {
;     ...
;             PG8_WAIT_V(8); PG8_WAIT_L(0); PG8_BAR; PG8_MMA(1, 0, At, B0); PG8_MMA(1, 1, At, B1); PG8_BAR; PG8_SCHED;
;             PG8_LDB(B0, 1, 0); PG8_LDB(B1, 1, 1); PG8_SCHED; PG8_LDA(At, 1, 0); PG8_STAGE(PG8_SA(0, 1), a2 + hstepA, voffA);
;             PG8_WAIT_V(8); PG8_WAIT_L(0); PG8_BAR; PG8_MMA(0, 0, At, B0); PG8_MMA(0, 1, At, B1); PG8_BAR; PG8_SCHED;
	v_mfma_f32_16x16x32_bf16 v[90:93], v[146:149], v[178:181], v[90:93]
	v_mfma_f32_16x16x32_bf16 v[82:85], v[154:157], v[178:181], v[82:85]
	v_mfma_f32_16x16x32_bf16 v[66:69], v[146:149], v[202:205], v[66:69]
	v_mfma_f32_16x16x32_bf16 v[58:61], v[154:157], v[202:205], v[58:61]
	v_mfma_f32_16x16x32_bf16 v[46:49], v[146:149], v[210:213], v[46:49]
	v_mfma_f32_16x16x32_bf16 v[42:45], v[154:157], v[210:213], v[42:45]
	v_mfma_f32_16x16x32_bf16 v[38:41], v[146:149], v[236:239], v[38:41]
	v_mfma_f32_16x16x32_bf16 v[34:37], v[154:157], v[236:239], v[34:37]
	v_mfma_f32_16x16x32_bf16 v[90:93], v[150:153], v[182:185], v[90:93]
	v_mfma_f32_16x16x32_bf16 v[82:85], v[158:161], v[182:185], v[82:85]
	v_mfma_f32_16x16x32_bf16 v[66:69], v[150:153], v[206:209], v[66:69]
	v_mfma_f32_16x16x32_bf16 v[58:61], v[158:161], v[206:209], v[58:61]
	v_mfma_f32_16x16x32_bf16 v[46:49], v[150:153], v[232:235], v[46:49]
	v_mfma_f32_16x16x32_bf16 v[42:45], v[158:161], v[232:235], v[42:45]
	v_mfma_f32_16x16x32_bf16 v[38:41], v[150:153], v[240:243], v[38:41]
	v_mfma_f32_16x16x32_bf16 v[34:37], v[158:161], v[240:243], v[34:37]
	s_setprio 0
	s_setprio 1
	v_mfma_f32_16x16x32_bf16 v[30:33], v[162:165], v[178:181], v[30:33]
	v_mfma_f32_16x16x32_bf16 v[26:29], v[170:173], v[178:181], v[26:29]
	v_mfma_f32_16x16x32_bf16 v[22:25], v[162:165], v[202:205], v[22:25]
	v_mfma_f32_16x16x32_bf16 v[18:21], v[170:173], v[202:205], v[18:21]
	v_mfma_f32_16x16x32_bf16 v[14:17], v[162:165], v[210:213], v[14:17]
	v_mfma_f32_16x16x32_bf16 v[10:13], v[170:173], v[210:213], v[10:13]
	v_mfma_f32_16x16x32_bf16 v[6:9], v[162:165], v[236:239], v[6:9]
	v_mfma_f32_16x16x32_bf16 v[2:5], v[170:173], v[236:239], v[2:5]
	v_mfma_f32_16x16x32_bf16 v[30:33], v[166:169], v[182:185], v[30:33]
	v_mfma_f32_16x16x32_bf16 v[26:29], v[174:177], v[182:185], v[26:29]
	v_mfma_f32_16x16x32_bf16 v[22:25], v[166:169], v[206:209], v[22:25]
	v_mfma_f32_16x16x32_bf16 v[18:21], v[174:177], v[206:209], v[18:21]
	v_mfma_f32_16x16x32_bf16 v[14:17], v[166:169], v[232:235], v[14:17]
	v_mfma_f32_16x16x32_bf16 v[10:13], v[174:177], v[232:235], v[10:13]
	v_mfma_f32_16x16x32_bf16 v[6:9], v[166:169], v[240:243], v[6:9]
	v_mfma_f32_16x16x32_bf16 v[2:5], v[174:177], v[240:243], v[2:5]
	s_setprio 0
	s_barrier
	s_add_i32 s34, 0, 0x18000
	v_add_u32_e32 v145, s34, v143
	s_add_i32 s35, 0, 0x1c000
	ds_read_b128 v[146:149], v145
	ds_read_b128 v[150:153], v145 offset:1024
	ds_read_b128 v[154:157], v145 offset:2048
	ds_read_b128 v[158:161], v145 offset:3072
	v_add_u32_e32 v145, s35, v143
	ds_read_b128 v[162:165], v145
	ds_read_b128 v[166:169], v145 offset:1024
	ds_read_b128 v[170:173], v145 offset:2048
	ds_read_b128 v[174:177], v145 offset:3072
	s_add_u32 s14, s14, 0x40000
	s_addc_u32 s15, s15, 0
	s_mov_b32 m0, s23
	ds_read_b128 v[178:181], v144 offset:32768
	ds_read_b128 v[182:185], v144 offset:33792
	ds_read_b128 v[202:205], v144 offset:34816
	ds_read_b128 v[206:209], v144 offset:35840
	ds_read_b128 v[210:213], v144 offset:36864
	ds_read_b128 v[232:235], v144 offset:37888
	ds_read_b128 v[236:239], v144 offset:38912
	ds_read_b128 v[240:243], v144 offset:39936
	global_load_lds_dwordx4 v136, s[14:15]
	s_mov_b32 m0, s24
	s_nop 0
	global_load_lds_dwordx4 v132, s[14:15]
	s_waitcnt vmcnt(8) lgkmcnt(0)
	s_setprio 1
	s_barrier
	v_mfma_f32_16x16x32_bf16 v[126:129], v[146:149], v[178:181], v[126:129]
	v_mfma_f32_16x16x32_bf16 v[122:125], v[154:157], v[178:181], v[122:125]
	v_mfma_f32_16x16x32_bf16 v[118:121], v[146:149], v[202:205], v[118:121]
	v_mfma_f32_16x16x32_bf16 v[114:117], v[154:157], v[202:205], v[114:117]
	v_mfma_f32_16x16x32_bf16 v[110:113], v[146:149], v[210:213], v[110:113]
	v_mfma_f32_16x16x32_bf16 v[106:109], v[154:157], v[210:213], v[106:109]
	v_mfma_f32_16x16x32_bf16 v[102:105], v[146:149], v[236:239], v[102:105]
	v_mfma_f32_16x16x32_bf16 v[98:101], v[154:157], v[236:239], v[98:101]
	v_mfma_f32_16x16x32_bf16 v[126:129], v[150:153], v[182:185], v[126:129]
	v_mfma_f32_16x16x32_bf16 v[122:125], v[158:161], v[182:185], v[122:125]
	v_mfma_f32_16x16x32_bf16 v[118:121], v[150:153], v[206:209], v[118:121]
	v_mfma_f32_16x16x32_bf16 v[114:117], v[158:161], v[206:209], v[114:117]
	v_mfma_f32_16x16x32_bf16 v[110:113], v[150:153], v[232:235], v[110:113]
	v_mfma_f32_16x16x32_bf16 v[106:109], v[158:161], v[232:235], v[106:109]
	v_mfma_f32_16x16x32_bf16 v[102:105], v[150:153], v[240:243], v[102:105]
	v_mfma_f32_16x16x32_bf16 v[98:101], v[158:161], v[240:243], v[98:101]
	s_setprio 0
	s_setprio 1
	v_mfma_f32_16x16x32_bf16 v[94:97], v[162:165], v[178:181], v[94:97]
	v_mfma_f32_16x16x32_bf16 v[86:89], v[170:173], v[178:181], v[86:89]
	v_mfma_f32_16x16x32_bf16 v[78:81], v[162:165], v[202:205], v[78:81]
	v_mfma_f32_16x16x32_bf16 v[74:77], v[170:173], v[202:205], v[74:77]
	v_mfma_f32_16x16x32_bf16 v[70:73], v[162:165], v[210:213], v[70:73]
	v_mfma_f32_16x16x32_bf16 v[62:65], v[170:173], v[210:213], v[62:65]
	v_mfma_f32_16x16x32_bf16 v[54:57], v[162:165], v[236:239], v[54:57]
	v_mfma_f32_16x16x32_bf16 v[50:53], v[170:173], v[236:239], v[50:53]
	v_mfma_f32_16x16x32_bf16 v[94:97], v[166:169], v[182:185], v[94:97]
	v_mfma_f32_16x16x32_bf16 v[86:89], v[174:177], v[182:185], v[86:89]
	v_mfma_f32_16x16x32_bf16 v[78:81], v[166:169], v[206:209], v[78:81]
	v_mfma_f32_16x16x32_bf16 v[74:77], v[174:177], v[206:209], v[74:77]
	v_mfma_f32_16x16x32_bf16 v[70:73], v[166:169], v[232:235], v[70:73]
	v_mfma_f32_16x16x32_bf16 v[62:65], v[174:177], v[232:235], v[62:65]
	v_mfma_f32_16x16x32_bf16 v[54:57], v[166:169], v[240:243], v[54:57]
	v_mfma_f32_16x16x32_bf16 v[50:53], v[174:177], v[240:243], v[50:53]
	s_setprio 0
	s_barrier
; #define PG8_STAGE(bufoff, gbase, voff) do { _Pragma("unroll") for (int _i = 0; _i < 2; ++_i) \
;         __builtin_amdgcn_global_load_lds((const unsigned*)((const char*)(gbase) + (voff)[_i]), (PG8_LAS unsigned*)(lds + (bufoff) + ldsw + _i * 8192), 16, 0, 0); } while (0)
; #define PG8_LDA(dst, b, h) do { _Pragma("unroll") for (int m = 0; m < 4; ++m) _Pragma("unroll") for (int k = 0; k < 2; ++k) dst[m][k] = *(const PG8_LAS bf16x8*)(lds + PG8_SA(b, h) + aoff + m * 2048 + k * 1024); } while (0)
; #define PG8_MMA(ai, bj, At, Bt) do { __builtin_amdgcn_s_setprio(1); _Pragma("unroll") for (int m = 0; m < 4; ++m) _Pragma("unroll") for (int n = 0; n < 2; ++n) _Pragma("unroll") for (int k = 0; k < 2; ++k) \
;         acc[ai][bj][m][n] = __builtin_amdgcn_mfma_f32_16x16x32_bf16(Bt[n][k], At[m][k], acc[ai][bj][m][n], 0, 0, 0); __builtin_amdgcn_s_setprio(0); } while (0)
; #define PG8_WAIT_V(n) asm volatile("s_waitcnt vmcnt(" #n ")" ::: "memory")
; #define PG8_WAIT_L(n) asm volatile("s_waitcnt lgkmcnt(" #n ")" ::: "memory")
; #define PG8_BAR __builtin_amdgcn_s_barrier()
; #define PG8_SCHED __builtin_amdgcn_sched_barrier(0)
; template <class Epi, class Sched, bool ALIGN_EPI = false, bool SP2 = false>
; __device__ __forceinline__ void gemm_phase(PG8_LAS unsigned char* lds, const Gemm g, const Sched& S, const Epi& E) {
;     ...
;             PG8_LDA(At, 1, 1); PG8_STAGE(PG8_SB(1, 0), b3, voffB); PG8_STAGE(PG8_SB(1, 1), b3 + hstepB, voffB); PG8_STAGE(PG8_SA(1, 0), a3, voffA);
;             PG8_WAIT_V(8); PG8_WAIT_L(0); PG8_BAR; PG8_MMA(1, 0, At, B0); PG8_MMA(1, 1, At, B1); PG8_BAR; PG8_SCHED;
;     ...
;         }
;         if constexpr (ALIGN_EPI) { if (wr == 0) PG8_BAR; }
	s_add_i32 s14, s34, s20
	s_mov_b32 m0, s14
	ds_read_b128 v[178:181], v144 offset:49152
	ds_read_b128 v[182:185], v144 offset:50176
	ds_read_b128 v[202:205], v144 offset:51200
	ds_read_b128 v[206:209], v144 offset:52224
	ds_read_b128 v[210:213], v144 offset:53248
	ds_read_b128 v[232:235], v144 offset:54272
	ds_read_b128 v[236:239], v144 offset:55296
	ds_read_b128 v[240:243], v144 offset:56320
	global_load_lds_dwordx4 v134, s[60:61]
	s_add_i32 m0, s14, 0x2000
	s_add_u32 s12, s12, 0x80080
	s_addc_u32 s13, s13, 0
	s_add_i32 s14, s35, s20
	global_load_lds_dwordx4 v130, s[60:61]
	s_mov_b32 m0, s14
	s_nop 0
	global_load_lds_dwordx4 v134, s[12:13]
	s_add_i32 m0, s14, 0x2000
	s_nop 0
	global_load_lds_dwordx4 v130, s[12:13]
	s_mov_b32 m0, s26
	s_nop 0
	global_load_lds_dwordx4 v136, s[62:63]
	s_mov_b32 m0, s27
	s_nop 0
	global_load_lds_dwordx4 v132, s[62:63]
	s_waitcnt vmcnt(8) lgkmcnt(0)
	s_setprio 1
	s_barrier
	v_mfma_f32_16x16x32_bf16 v[90:93], v[146:149], v[178:181], v[90:93]
	v_mfma_f32_16x16x32_bf16 v[82:85], v[154:157], v[178:181], v[82:85]
	v_mfma_f32_16x16x32_bf16 v[66:69], v[146:149], v[202:205], v[66:69]
	v_mfma_f32_16x16x32_bf16 v[58:61], v[154:157], v[202:205], v[58:61]
	v_mfma_f32_16x16x32_bf16 v[46:49], v[146:149], v[210:213], v[46:49]
	v_mfma_f32_16x16x32_bf16 v[42:45], v[154:157], v[210:213], v[42:45]
	v_mfma_f32_16x16x32_bf16 v[38:41], v[146:149], v[236:239], v[38:41]
	v_mfma_f32_16x16x32_bf16 v[34:37], v[154:157], v[236:239], v[34:37]
	v_mfma_f32_16x16x32_bf16 v[90:93], v[150:153], v[182:185], v[90:93]
	v_mfma_f32_16x16x32_bf16 v[82:85], v[158:161], v[182:185], v[82:85]
	v_mfma_f32_16x16x32_bf16 v[66:69], v[150:153], v[206:209], v[66:69]
	v_mfma_f32_16x16x32_bf16 v[58:61], v[158:161], v[206:209], v[58:61]
	v_mfma_f32_16x16x32_bf16 v[46:49], v[150:153], v[232:235], v[46:49]
	v_mfma_f32_16x16x32_bf16 v[42:45], v[158:161], v[232:235], v[42:45]
	v_mfma_f32_16x16x32_bf16 v[38:41], v[150:153], v[240:243], v[38:41]
	v_mfma_f32_16x16x32_bf16 v[34:37], v[158:161], v[240:243], v[34:37]
	s_setprio 0
	s_setprio 1
	v_mfma_f32_16x16x32_bf16 v[30:33], v[162:165], v[178:181], v[30:33]
	v_mfma_f32_16x16x32_bf16 v[26:29], v[170:173], v[178:181], v[26:29]
	v_mfma_f32_16x16x32_bf16 v[22:25], v[162:165], v[202:205], v[22:25]
	v_mfma_f32_16x16x32_bf16 v[18:21], v[170:173], v[202:205], v[18:21]
	v_mfma_f32_16x16x32_bf16 v[14:17], v[162:165], v[210:213], v[14:17]
	v_mfma_f32_16x16x32_bf16 v[10:13], v[170:173], v[210:213], v[10:13]
	v_mfma_f32_16x16x32_bf16 v[6:9], v[162:165], v[236:239], v[6:9]
	v_mfma_f32_16x16x32_bf16 v[2:5], v[170:173], v[236:239], v[2:5]
	v_mfma_f32_16x16x32_bf16 v[30:33], v[166:169], v[182:185], v[30:33]
	v_mfma_f32_16x16x32_bf16 v[26:29], v[174:177], v[182:185], v[26:29]
	v_mfma_f32_16x16x32_bf16 v[22:25], v[166:169], v[206:209], v[22:25]
	v_mfma_f32_16x16x32_bf16 v[18:21], v[174:177], v[206:209], v[18:21]
	v_mfma_f32_16x16x32_bf16 v[14:17], v[166:169], v[232:235], v[14:17]
	v_mfma_f32_16x16x32_bf16 v[10:13], v[174:177], v[232:235], v[10:13]
	v_mfma_f32_16x16x32_bf16 v[6:9], v[166:169], v[240:243], v[6:9]
	v_mfma_f32_16x16x32_bf16 v[2:5], v[174:177], v[240:243], v[2:5]
	s_setprio 0
	s_barrier
	s_add_i32 s31, s31, 2
	s_add_u32 s8, s8, 0x100
	s_addc_u32 s9, s9, 0
	s_cmp_gt_u32 s31, 13
	s_cbranch_scc0 .LBB0_530
	s_cmpk_lt_u32 s19, 0x100
	s_cbranch_scc0 .LBB0_533
	s_barrier

; #define PG8_STAGE(bufoff, gbase, voff) do { _Pragma("unroll") for (int _i = 0; _i < 2; ++_i) \
;         __builtin_amdgcn_global_load_lds((const unsigned*)((const char*)(gbase) + (voff)[_i]), (PG8_LAS unsigned*)(lds + (bufoff) + ldsw + _i * 8192), 16, 0, 0); } while (0)
; #define PG8_LDA(dst, b, h) do { _Pragma("unroll") for (int m = 0; m < 4; ++m) _Pragma("unroll") for (int k = 0; k < 2; ++k) dst[m][k] = *(const PG8_LAS bf16x8*)(lds + PG8_SA(b, h) + aoff + m * 2048 + k * 1024); } while (0)
; #define PG8_LDB(dst, b, h) do { _Pragma("unroll") for (int n = 0; n < 2; ++n) _Pragma("unroll") for (int k = 0; k < 2; ++k) dst[n][k] = *(const PG8_LAS bf16x8*)(lds + PG8_SB(b, h) + boff + n * 2048 + k * 1024); } while (0)
; #define PG8_MMA(ai, bj, At, Bt) do { __builtin_amdgcn_s_setprio(1); _Pragma("unroll") for (int m = 0; m < 4; ++m) _Pragma("unroll") for (int n = 0; n < 2; ++n) _Pragma("unroll") for (int k = 0; k < 2; ++k) \
;         acc[ai][bj][m][n] = __builtin_amdgcn_mfma_f32_16x16x32_bf16(Bt[n][k], At[m][k], acc[ai][bj][m][n], 0, 0, 0); __builtin_amdgcn_s_setprio(0); } while (0)
; #define PG8_WAIT_V(n) asm volatile("s_waitcnt vmcnt(" #n ")" ::: "memory")
; #define PG8_WAIT_L(n) asm volatile("s_waitcnt lgkmcnt(" #n ")" ::: "memory")
; #define PG8_BAR __builtin_amdgcn_s_barrier()
; #define PG8_SCHED __builtin_amdgcn_sched_barrier(0)
; template <class Epi, class Sched, bool ALIGN_EPI = false, bool SP2 = false>
; __device__ __forceinline__ void gemm_phase(PG8_LAS unsigned char* lds, const Gemm g, const Sched& S, const Epi& E) {
;     ...
;         PG8_WAIT_V(2); PG8_BAR;
;         PG8_STAGE(PG8_SB(1, 0), cB + kstep, voffB); PG8_STAGE(PG8_SA(1, 0), cA + kstep, voffA); PG8_STAGE(PG8_SB(1, 1), cB + hstepB + kstep, voffB);
;         PG8_WAIT_V(6); PG8_BAR;
;     ...
;             PG8_LDB(B0, 0, 0); PG8_LDB(B1, 0, 1); PG8_SCHED; PG8_LDA(At, 0, 0); PG8_STAGE(PG8_SA(1, 1), a1 + hstepA, voffA);
;             PG8_WAIT_V(8); PG8_WAIT_L(0); PG8_BAR; PG8_MMA(0, 0, At, B0); PG8_MMA(0, 1, At, B1); PG8_BAR; PG8_SCHED;
;             PG8_LDA(At, 0, 1); PG8_STAGE(PG8_SB(0, 0), b2, voffB); PG8_STAGE(PG8_SB(0, 1), b2 + hstepB, voffB); PG8_STAGE(PG8_SA(0, 0), a2, voffA);
;             PG8_WAIT_V(8); PG8_WAIT_L(0); PG8_BAR; PG8_MMA(1, 0, At, B0); PG8_MMA(1, 1, At, B1); PG8_BAR; PG8_SCHED;
.LBB0_592:
	s_add_i32 s44, 0, 0x18000
	s_add_i32 s36, s44, s14
	s_and_b32 s28, s15, 3
	v_lshl_add_u64 v[26:27], v[4:5], 0, s[96:97]
	s_mov_b32 m0, s36
	s_add_i32 s38, s36, 0x2000
	s_lshl_b32 s15, s26, 13
	s_lshl_b32 s43, s28, 12
	s_waitcnt vmcnt(2)
	s_barrier
	global_load_lds_dwordx4 v[26:27], off
	v_lshl_add_u64 v[28:29], v[6:7], 0, s[96:97]
	s_mov_b32 m0, s38
	s_add_i32 s37, s27, 0x8000
	s_add_i32 s39, s27, 0xa000
	global_load_lds_dwordx4 v[28:29], off
	v_lshl_add_u64 v[24:25], v[18:19], 0, s[96:97]
	s_mov_b32 m0, s37
	s_add_u32 s16, s8, 0x10080
	global_load_lds_dwordx4 v[24:25], off
	v_lshl_add_u64 v[30:31], v[22:23], 0, s[96:97]
	s_mov_b32 m0, s39
	s_addc_u32 s17, s9, 0
	s_add_i32 s40, s27, 0x1c000
	global_load_lds_dwordx4 v[30:31], off
	v_lshl_add_u64 v[68:69], s[16:17], 0, v[32:33]
	s_mov_b32 m0, s40
	s_add_i32 s41, s27, 0x1e000
	global_load_lds_dwordx4 v[68:69], off
	v_lshl_add_u64 v[70:71], s[16:17], 0, v[20:21]
	s_mov_b32 m0, s41
	v_lshrrev_b32_e32 v35, 1, v34
	global_load_lds_dwordx4 v[70:71], off
	v_and_b32_e32 v72, 24, v35
	v_and_b32_e32 v67, 15, v34
	v_lshlrev_b32_e32 v35, 1, v72
	v_lshlrev_b32_e32 v34, 2, v34
	v_lshl_or_b32 v35, v67, 6, v35
	v_and_b32_e32 v34, 32, v34
	v_bitop3_b32 v36, v35, s15, v34 bitop3:0xde
	s_add_i32 s15, 0, 0x10000
	v_bitop3_b32 v34, v35, s43, v34 bitop3:0xde
	s_add_u32 s48, s12, 0x10080
	v_add_u32_e32 v157, s44, v34
	s_addc_u32 s49, s13, 0
	s_add_i32 s44, s15, s14
	s_add_i32 s46, s27, 0xc000
	s_add_i32 s45, s27, 0xe000
	s_add_i32 s43, s44, 0x2000
	v_add_u32_e32 v73, s15, v34
	s_add_u32 s50, s8, 0x10100
	s_waitcnt vmcnt(6)
	s_barrier
	v_add_u32_e32 v156, 0, v36
	s_addc_u32 s51, s9, 0
	ds_read_b128 v[34:37], v73
	ds_read_b128 v[38:41], v73 offset:1024
	ds_read_b128 v[42:45], v73 offset:2048
	ds_read_b128 v[46:49], v73 offset:3072
	s_add_u32 s16, s12, 0x10100
	s_addc_u32 s17, s13, 0
	s_add_u32 s14, s8, 0x10180
	s_addc_u32 s15, s9, 0
	s_add_u32 s8, s12, 0x10180
	s_addc_u32 s9, s13, 0
	s_cmpk_gt_u32 s42, 0xff
	s_mov_b32 m0, s46
	v_lshl_add_u64 v[90:91], s[48:49], 0, v[14:15]
	ds_read_b128 v[50:53], v156
	ds_read_b128 v[54:57], v156 offset:1024
	ds_read_b128 v[58:61], v156 offset:2048
	ds_read_b128 v[62:65], v156 offset:3072
	ds_read_b128 v[74:77], v156 offset:4096
	ds_read_b128 v[78:81], v156 offset:5120
	ds_read_b128 v[82:85], v156 offset:6144
	ds_read_b128 v[86:89], v156 offset:7168
	global_load_lds_dwordx4 v[90:91], off
	v_lshl_add_u64 v[90:91], s[48:49], 0, v[2:3]
	s_mov_b32 m0, s45
	s_nop 0
	global_load_lds_dwordx4 v[90:91], off
	s_waitcnt vmcnt(8) lgkmcnt(0)
	s_setprio 1
	s_barrier
	v_mfma_f32_16x16x32_bf16 v[90:93], v[34:37], v[50:53], 0
	v_mfma_f32_16x16x32_bf16 v[50:53], v[42:45], v[50:53], 0
	v_mfma_f32_16x16x32_bf16 v[90:93], v[38:41], v[54:57], v[90:93]
	v_mfma_f32_16x16x32_bf16 v[50:53], v[46:49], v[54:57], v[50:53]
	v_mfma_f32_16x16x32_bf16 v[54:57], v[34:37], v[58:61], 0
	v_mfma_f32_16x16x32_bf16 v[58:61], v[42:45], v[58:61], 0
	v_mfma_f32_16x16x32_bf16 v[54:57], v[38:41], v[62:65], v[54:57]
	v_mfma_f32_16x16x32_bf16 v[58:61], v[46:49], v[62:65], v[58:61]
	v_mfma_f32_16x16x32_bf16 v[62:65], v[34:37], v[74:77], 0
	v_mfma_f32_16x16x32_bf16 v[74:77], v[42:45], v[74:77], 0
	v_mfma_f32_16x16x32_bf16 v[62:65], v[38:41], v[78:81], v[62:65]
	v_mfma_f32_16x16x32_bf16 v[74:77], v[46:49], v[78:81], v[74:77]
	v_mfma_f32_16x16x32_bf16 v[78:81], v[34:37], v[82:85], 0
	v_mfma_f32_16x16x32_bf16 v[82:85], v[42:45], v[82:85], 0
	v_mfma_f32_16x16x32_bf16 v[78:81], v[38:41], v[86:89], v[78:81]
	v_mfma_f32_16x16x32_bf16 v[82:85], v[46:49], v[86:89], v[82:85]
	s_setprio 0
	s_setprio 1
	s_setprio 0
	s_barrier
	s_mov_b64 s[12:13], 0x100
	s_mov_b32 m0, s44
	v_lshl_add_u64 v[122:123], v[4:5], 0, s[12:13]
	ds_read_b128 v[86:89], v156 offset:16384
	ds_read_b128 v[94:97], v156 offset:17408
	ds_read_b128 v[98:101], v156 offset:18432
	ds_read_b128 v[102:105], v156 offset:19456
	ds_read_b128 v[106:109], v156 offset:20480
	ds_read_b128 v[110:113], v156 offset:21504
	ds_read_b128 v[114:117], v156 offset:22528
	ds_read_b128 v[118:121], v156 offset:23552
	global_load_lds_dwordx4 v[122:123], off
	v_lshl_add_u64 v[122:123], v[6:7], 0, s[12:13]
	s_mov_b32 m0, s43
	s_nop 0
	global_load_lds_dwordx4 v[122:123], off
	v_lshl_add_u64 v[122:123], s[50:51], 0, v[32:33]
	s_mov_b32 m0, s29
	s_nop 0
	global_load_lds_dwordx4 v[122:123], off
	v_lshl_add_u64 v[122:123], s[50:51], 0, v[20:21]
	s_mov_b32 m0, s31
	s_nop 0
	global_load_lds_dwordx4 v[122:123], off
	v_lshl_add_u64 v[122:123], v[18:19], 0, s[12:13]
	s_mov_b32 m0, s27
	s_nop 0
	global_load_lds_dwordx4 v[122:123], off
	v_lshl_add_u64 v[122:123], v[22:23], 0, s[12:13]
	s_mov_b32 m0, s35
	s_nop 0
	global_load_lds_dwordx4 v[122:123], off
	s_waitcnt vmcnt(8) lgkmcnt(0)
	s_setprio 1
	s_barrier
	v_mfma_f32_16x16x32_bf16 v[122:125], v[34:37], v[86:89], 0
	v_mfma_f32_16x16x32_bf16 v[86:89], v[42:45], v[86:89], 0
	v_mfma_f32_16x16x32_bf16 v[122:125], v[38:41], v[94:97], v[122:125]
	v_mfma_f32_16x16x32_bf16 v[86:89], v[46:49], v[94:97], v[86:89]
	v_mfma_f32_16x16x32_bf16 v[94:97], v[34:37], v[98:101], 0
	v_mfma_f32_16x16x32_bf16 v[98:101], v[42:45], v[98:101], 0
	v_mfma_f32_16x16x32_bf16 v[94:97], v[38:41], v[102:105], v[94:97]
	v_mfma_f32_16x16x32_bf16 v[98:101], v[46:49], v[102:105], v[98:101]
	v_mfma_f32_16x16x32_bf16 v[102:105], v[34:37], v[106:109], 0
	v_mfma_f32_16x16x32_bf16 v[34:37], v[34:37], v[114:117], 0
	v_mfma_f32_16x16x32_bf16 v[102:105], v[38:41], v[110:113], v[102:105]
	v_mfma_f32_16x16x32_bf16 v[34:37], v[38:41], v[118:121], v[34:37]
	v_mfma_f32_16x16x32_bf16 v[38:41], v[42:45], v[114:117], 0
	v_mfma_f32_16x16x32_bf16 v[106:109], v[42:45], v[106:109], 0
	v_mfma_f32_16x16x32_bf16 v[38:41], v[46:49], v[118:121], v[38:41]
	v_mfma_f32_16x16x32_bf16 v[106:109], v[46:49], v[110:113], v[106:109]
	s_setprio 0
	s_setprio 1
	s_setprio 0
	s_barrier
; #define PG8_STAGE(bufoff, gbase, voff) do { _Pragma("unroll") for (int _i = 0; _i < 2; ++_i) \
;         __builtin_amdgcn_global_load_lds((const unsigned*)((const char*)(gbase) + (voff)[_i]), (PG8_LAS unsigned*)(lds + (bufoff) + ldsw + _i * 8192), 16, 0, 0); } while (0)
; #define PG8_LDA(dst, b, h) do { _Pragma("unroll") for (int m = 0; m < 4; ++m) _Pragma("unroll") for (int k = 0; k < 2; ++k) dst[m][k] = *(const PG8_LAS bf16x8*)(lds + PG8_SA(b, h) + aoff + m * 2048 + k * 1024); } while (0)
; #define PG8_LDB(dst, b, h) do { _Pragma("unroll") for (int n = 0; n < 2; ++n) _Pragma("unroll") for (int k = 0; k < 2; ++k) dst[n][k] = *(const PG8_LAS bf16x8*)(lds + PG8_SB(b, h) + boff + n * 2048 + k * 1024); } while (0)
; #define PG8_MMA(ai, bj, At, Bt) do { __builtin_amdgcn_s_setprio(1); _Pragma("unroll") for (int m = 0; m < 4; ++m) _Pragma("unroll") for (int n = 0; n < 2; ++n) _Pragma("unroll") for (int k = 0; k < 2; ++k) \
;         acc[ai][bj][m][n] = __builtin_amdgcn_mfma_f32_16x16x32_bf16(Bt[n][k], At[m][k], acc[ai][bj][m][n], 0, 0, 0); __builtin_amdgcn_s_setprio(0); } while (0)
; #define PG8_WAIT_V(n) asm volatile("s_waitcnt vmcnt(" #n ")" ::: "memory")
; #define PG8_WAIT_L(n) asm volatile("s_waitcnt lgkmcnt(" #n ")" ::: "memory")
; #define PG8_BAR __builtin_amdgcn_s_barrier()
; #define PG8_SCHED __builtin_amdgcn_sched_barrier(0)
; template <class Epi, class Sched, bool ALIGN_EPI = false, bool SP2 = false>
; __device__ __forceinline__ void gemm_phase(PG8_LAS unsigned char* lds, const Gemm g, const Sched& S, const Epi& E) {
;     ...
;             PG8_LDB(B0, 0, 0); PG8_LDB(B1, 0, 1); PG8_SCHED; PG8_LDA(At, 0, 0); PG8_STAGE(PG8_SA(1, 1), a1 + hstepA, voffA);
;             PG8_WAIT_V(8); PG8_WAIT_L(0); PG8_BAR; PG8_MMA(0, 0, At, B0); PG8_MMA(0, 1, At, B1); PG8_BAR; PG8_SCHED;
;     ...
;             PG8_LDB(B0, 1, 0); PG8_LDB(B1, 1, 1); PG8_SCHED; PG8_LDA(At, 1, 0); PG8_STAGE(PG8_SA(0, 1), a2 + hstepA, voffA);
;             PG8_WAIT_V(8); PG8_WAIT_L(0); PG8_BAR; PG8_MMA(0, 0, At, B0); PG8_MMA(0, 1, At, B1); PG8_BAR; PG8_SCHED;
;             PG8_LDA(At, 1, 1); PG8_STAGE(PG8_SB(1, 0), b3, voffB); PG8_STAGE(PG8_SB(1, 1), b3 + hstepB, voffB); PG8_STAGE(PG8_SA(1, 0), a3, voffA);
;             PG8_WAIT_V(8); PG8_WAIT_L(0); PG8_BAR; PG8_MMA(1, 0, At, B0); PG8_MMA(1, 1, At, B1); PG8_BAR; PG8_SCHED;
	ds_read_b128 v[42:45], v157
	ds_read_b128 v[46:49], v157 offset:1024
	ds_read_b128 v[110:113], v157 offset:2048
	ds_read_b128 v[114:117], v157 offset:3072
	s_mov_b32 m0, s30
	v_lshl_add_u64 v[154:155], s[16:17], 0, v[14:15]
	ds_read_b128 v[118:121], v156 offset:32768
	ds_read_b128 v[126:129], v156 offset:33792
	ds_read_b128 v[130:133], v156 offset:34816
	ds_read_b128 v[134:137], v156 offset:35840
	ds_read_b128 v[138:141], v156 offset:36864
	ds_read_b128 v[142:145], v156 offset:37888
	ds_read_b128 v[146:149], v156 offset:38912
	ds_read_b128 v[150:153], v156 offset:39936
	global_load_lds_dwordx4 v[154:155], off
	v_lshl_add_u64 v[154:155], s[16:17], 0, v[2:3]
	s_mov_b32 m0, s34
	s_nop 0
	global_load_lds_dwordx4 v[154:155], off
	s_waitcnt vmcnt(8) lgkmcnt(0)
	s_setprio 1
	s_barrier
	v_mfma_f32_16x16x32_bf16 v[50:53], v[110:113], v[118:121], v[50:53]
	v_mfma_f32_16x16x32_bf16 v[54:57], v[42:45], v[130:133], v[54:57]
	v_mfma_f32_16x16x32_bf16 v[58:61], v[110:113], v[130:133], v[58:61]
	v_mfma_f32_16x16x32_bf16 v[62:65], v[42:45], v[138:141], v[62:65]
	v_mfma_f32_16x16x32_bf16 v[90:93], v[42:45], v[118:121], v[90:93]
	v_mfma_f32_16x16x32_bf16 v[50:53], v[114:117], v[126:129], v[50:53]
	v_mfma_f32_16x16x32_bf16 v[54:57], v[46:49], v[134:137], v[54:57]
	v_mfma_f32_16x16x32_bf16 v[58:61], v[114:117], v[134:137], v[58:61]
	v_mfma_f32_16x16x32_bf16 v[62:65], v[46:49], v[142:145], v[62:65]
	v_mfma_f32_16x16x32_bf16 v[74:77], v[110:113], v[138:141], v[74:77]
	v_mfma_f32_16x16x32_bf16 v[78:81], v[42:45], v[146:149], v[78:81]
	v_mfma_f32_16x16x32_bf16 v[82:85], v[110:113], v[146:149], v[82:85]
	v_mfma_f32_16x16x32_bf16 v[90:93], v[46:49], v[126:129], v[90:93]
	v_mfma_f32_16x16x32_bf16 v[74:77], v[114:117], v[142:145], v[74:77]
	v_mfma_f32_16x16x32_bf16 v[78:81], v[46:49], v[150:153], v[78:81]
	v_mfma_f32_16x16x32_bf16 v[82:85], v[114:117], v[150:153], v[82:85]
	s_setprio 0
	s_setprio 1
	s_setprio 0
	s_barrier
	s_mov_b64 s[12:13], 0x180
	s_mov_b32 m0, s36
	v_lshl_add_u64 v[154:155], v[4:5], 0, s[12:13]
	ds_read_b128 v[118:121], v156 offset:49152
	ds_read_b128 v[126:129], v156 offset:50176
	ds_read_b128 v[130:133], v156 offset:51200
	ds_read_b128 v[134:137], v156 offset:52224
	ds_read_b128 v[138:141], v156 offset:53248
	ds_read_b128 v[142:145], v156 offset:54272
	ds_read_b128 v[146:149], v156 offset:55296
	ds_read_b128 v[150:153], v156 offset:56320
	global_load_lds_dwordx4 v[154:155], off
	v_lshl_add_u64 v[154:155], v[6:7], 0, s[12:13]
	s_mov_b32 m0, s38
	v_lshl_add_u64 v[32:33], s[14:15], 0, v[32:33]
	global_load_lds_dwordx4 v[154:155], off
	s_mov_b32 m0, s40
	v_lshl_add_u64 v[20:21], s[14:15], 0, v[20:21]
	global_load_lds_dwordx4 v[32:33], off
	s_mov_b32 m0, s41
	s_nop 0
	global_load_lds_dwordx4 v[20:21], off
	v_lshl_add_u64 v[20:21], v[18:19], 0, s[12:13]
	s_mov_b32 m0, s37
	s_nop 0
	global_load_lds_dwordx4 v[20:21], off
	v_lshl_add_u64 v[20:21], v[22:23], 0, s[12:13]
	s_mov_b32 m0, s39
	s_nop 0
	global_load_lds_dwordx4 v[20:21], off
	s_waitcnt vmcnt(8) lgkmcnt(0)
	s_setprio 1
	s_barrier
	v_mfma_f32_16x16x32_bf16 v[32:35], v[42:45], v[146:149], v[34:37]
	v_mfma_f32_16x16x32_bf16 v[36:39], v[110:113], v[146:149], v[38:41]
	v_mfma_f32_16x16x32_bf16 v[122:125], v[42:45], v[118:121], v[122:125]
	v_mfma_f32_16x16x32_bf16 v[86:89], v[110:113], v[118:121], v[86:89]
	v_mfma_f32_16x16x32_bf16 v[94:97], v[42:45], v[130:133], v[94:97]
	v_mfma_f32_16x16x32_bf16 v[98:101], v[110:113], v[130:133], v[98:101]
	v_mfma_f32_16x16x32_bf16 v[102:105], v[42:45], v[138:141], v[102:105]
	v_mfma_f32_16x16x32_bf16 v[106:109], v[110:113], v[138:141], v[106:109]
	v_mfma_f32_16x16x32_bf16 v[32:35], v[46:49], v[150:153], v[32:35]
	v_mfma_f32_16x16x32_bf16 v[36:39], v[114:117], v[150:153], v[36:39]
	v_mfma_f32_16x16x32_bf16 v[122:125], v[46:49], v[126:129], v[122:125]
	v_mfma_f32_16x16x32_bf16 v[86:89], v[114:117], v[126:129], v[86:89]
	v_mfma_f32_16x16x32_bf16 v[94:97], v[46:49], v[134:137], v[94:97]
	v_mfma_f32_16x16x32_bf16 v[98:101], v[114:117], v[134:137], v[98:101]
	v_mfma_f32_16x16x32_bf16 v[102:105], v[46:49], v[142:145], v[102:105]
	v_mfma_f32_16x16x32_bf16 v[106:109], v[114:117], v[142:145], v[106:109]
	s_setprio 0
	s_setprio 1
	s_setprio 0
	s_barrier
	ds_read_b128 v[40:43], v73
	ds_read_b128 v[44:47], v73 offset:1024
	ds_read_b128 v[110:113], v73 offset:2048
	ds_read_b128 v[114:117], v73 offset:3072
	s_mov_b32 m0, s46
	v_lshl_add_u64 v[14:15], s[8:9], 0, v[14:15]
	ds_read_b128 v[118:121], v156
	ds_read_b128 v[126:129], v156 offset:1024
	ds_read_b128 v[130:133], v156 offset:2048
	ds_read_b128 v[134:137], v156 offset:3072
	ds_read_b128 v[138:141], v156 offset:4096
	ds_read_b128 v[142:145], v156 offset:5120
	ds_read_b128 v[146:149], v156 offset:6144
	ds_read_b128 v[150:153], v156 offset:7168
	global_load_lds_dwordx4 v[14:15], off
	v_lshl_add_u64 v[2:3], s[8:9], 0, v[2:3]
	s_mov_b32 m0, s45
	s_nop 0
	global_load_lds_dwordx4 v[2:3], off
	s_waitcnt vmcnt(8) lgkmcnt(0)
	s_setprio 1
	s_barrier
	v_mfma_f32_16x16x32_bf16 v[48:51], v[110:113], v[118:121], v[50:53]
	v_mfma_f32_16x16x32_bf16 v[52:55], v[40:43], v[130:133], v[54:57]
	v_mfma_f32_16x16x32_bf16 v[56:59], v[110:113], v[130:133], v[58:61]
	v_mfma_f32_16x16x32_bf16 v[90:93], v[40:43], v[118:121], v[90:93]
	v_mfma_f32_16x16x32_bf16 v[118:121], v[114:117], v[134:137], v[56:59]
	v_mfma_f32_16x16x32_bf16 v[56:59], v[40:43], v[138:141], v[62:65]
	v_mfma_f32_16x16x32_bf16 v[90:93], v[44:47], v[126:129], v[90:93]
	v_mfma_f32_16x16x32_bf16 v[48:51], v[114:117], v[126:129], v[48:51]
	v_mfma_f32_16x16x32_bf16 v[126:129], v[44:47], v[142:145], v[56:59]
	v_mfma_f32_16x16x32_bf16 v[56:59], v[110:113], v[138:141], v[74:77]
	v_mfma_f32_16x16x32_bf16 v[74:77], v[114:117], v[142:145], v[56:59]
	v_mfma_f32_16x16x32_bf16 v[56:59], v[40:43], v[146:149], v[78:81]
	v_mfma_f32_16x16x32_bf16 v[52:55], v[44:47], v[134:137], v[52:55]
	v_mfma_f32_16x16x32_bf16 v[78:81], v[44:47], v[150:153], v[56:59]
	v_mfma_f32_16x16x32_bf16 v[56:59], v[110:113], v[146:149], v[82:85]
	v_mfma_f32_16x16x32_bf16 v[82:85], v[114:117], v[150:153], v[56:59]
	s_setprio 0
	s_setprio 1
	s_setprio 0
	s_barrier
; #define PG8_STAGE(bufoff, gbase, voff) do { _Pragma("unroll") for (int _i = 0; _i < 2; ++_i) \
;         __builtin_amdgcn_global_load_lds((const unsigned*)((const char*)(gbase) + (voff)[_i]), (PG8_LAS unsigned*)(lds + (bufoff) + ldsw + _i * 8192), 16, 0, 0); } while (0)
; #define PG8_LDA(dst, b, h) do { _Pragma("unroll") for (int m = 0; m < 4; ++m) _Pragma("unroll") for (int k = 0; k < 2; ++k) dst[m][k] = *(const PG8_LAS bf16x8*)(lds + PG8_SA(b, h) + aoff + m * 2048 + k * 1024); } while (0)
; #define PG8_LDB(dst, b, h) do { _Pragma("unroll") for (int n = 0; n < 2; ++n) _Pragma("unroll") for (int k = 0; k < 2; ++k) dst[n][k] = *(const PG8_LAS bf16x8*)(lds + PG8_SB(b, h) + boff + n * 2048 + k * 1024); } while (0)
; #define PG8_MMA(ai, bj, At, Bt) do { __builtin_amdgcn_s_setprio(1); _Pragma("unroll") for (int m = 0; m < 4; ++m) _Pragma("unroll") for (int n = 0; n < 2; ++n) _Pragma("unroll") for (int k = 0; k < 2; ++k) \
;         acc[ai][bj][m][n] = __builtin_amdgcn_mfma_f32_16x16x32_bf16(Bt[n][k], At[m][k], acc[ai][bj][m][n], 0, 0, 0); __builtin_amdgcn_s_setprio(0); } while (0)
; #define PG8_WAIT_V(n) asm volatile("s_waitcnt vmcnt(" #n ")" ::: "memory")
; #define PG8_WAIT_L(n) asm volatile("s_waitcnt lgkmcnt(" #n ")" ::: "memory")
; #define PG8_BAR __builtin_amdgcn_s_barrier()
; #define PG8_SCHED __builtin_amdgcn_sched_barrier(0)
; template <class Epi, class Sched, bool ALIGN_EPI = false, bool SP2 = false>
; __device__ __forceinline__ void gemm_phase(PG8_LAS unsigned char* lds, const Gemm g, const Sched& S, const Epi& E) {
;     ...
;             PG8_LDA(At, 0, 1); PG8_STAGE(PG8_SB(0, 0), b2, voffB); PG8_STAGE(PG8_SB(0, 1), b2 + hstepB, voffB); PG8_STAGE(PG8_SA(0, 0), a2, voffA);
;             PG8_WAIT_V(8); PG8_WAIT_L(0); PG8_BAR; PG8_MMA(1, 0, At, B0); PG8_MMA(1, 1, At, B1); PG8_BAR; PG8_SCHED;
;             PG8_LDB(B0, 1, 0); PG8_LDB(B1, 1, 1); PG8_SCHED; PG8_LDA(At, 1, 0); PG8_STAGE(PG8_SA(0, 1), a2 + hstepA, voffA);
;             PG8_WAIT_V(8); PG8_WAIT_L(0); PG8_BAR; PG8_MMA(0, 0, At, B0); PG8_MMA(0, 1, At, B1); PG8_BAR; PG8_SCHED;
;             PG8_LDA(At, 1, 1); PG8_STAGE(PG8_SB(1, 0), b3, voffB); PG8_STAGE(PG8_SB(1, 1), b3 + hstepB, voffB); PG8_STAGE(PG8_SA(1, 0), a3, voffA);
;             PG8_WAIT_V(8); PG8_WAIT_L(0); PG8_BAR; PG8_MMA(1, 0, At, B0); PG8_MMA(1, 1, At, B1); PG8_BAR; PG8_SCHED;
;     ...
;         if constexpr (ALIGN_EPI) { if (wr == 0) PG8_BAR; }
	s_mov_b32 m0, s44
	s_nop 1
	ds_read_b128 v[56:59], v156 offset:16384
	ds_read_b128 v[60:63], v156 offset:17408
	ds_read_b128 v[130:133], v156 offset:18432
	ds_read_b128 v[134:137], v156 offset:19456
	ds_read_b128 v[138:141], v156 offset:20480
	ds_read_b128 v[142:145], v156 offset:21504
	ds_read_b128 v[146:149], v156 offset:22528
	ds_read_b128 v[150:153], v156 offset:23552
	global_load_lds_dwordx4 v[4:5], off
	s_mov_b32 m0, s43
	s_nop 0
	global_load_lds_dwordx4 v[6:7], off
	s_mov_b32 m0, s29
	s_nop 0
	global_load_lds_dwordx4 v[8:9], off
	s_mov_b32 m0, s31
	s_nop 0
	global_load_lds_dwordx4 v[10:11], off
	s_mov_b32 m0, s27
	s_nop 0
	global_load_lds_dwordx4 v[18:19], off
	s_mov_b32 m0, s35
	s_nop 0
	global_load_lds_dwordx4 v[22:23], off
	s_waitcnt vmcnt(8) lgkmcnt(0)
	s_setprio 1
	s_barrier
	v_mfma_f32_16x16x32_bf16 v[2:5], v[40:43], v[56:59], v[122:125]
	v_mfma_f32_16x16x32_bf16 v[6:9], v[110:113], v[56:59], v[86:89]
	v_mfma_f32_16x16x32_bf16 v[56:59], v[110:113], v[130:133], v[98:101]
	v_mfma_f32_16x16x32_bf16 v[18:21], v[40:43], v[130:133], v[94:97]
	v_mfma_f32_16x16x32_bf16 v[86:89], v[114:117], v[134:137], v[56:59]
	v_mfma_f32_16x16x32_bf16 v[56:59], v[40:43], v[138:141], v[102:105]
	v_mfma_f32_16x16x32_bf16 v[32:35], v[40:43], v[146:149], v[32:35]
	v_mfma_f32_16x16x32_bf16 v[2:5], v[44:47], v[60:63], v[2:5]
	v_mfma_f32_16x16x32_bf16 v[6:9], v[114:117], v[60:63], v[6:9]
	v_mfma_f32_16x16x32_bf16 v[18:21], v[44:47], v[134:137], v[18:21]
	v_mfma_f32_16x16x32_bf16 v[94:97], v[44:47], v[142:145], v[56:59]
	v_mfma_f32_16x16x32_bf16 v[56:59], v[110:113], v[138:141], v[106:109]
	v_mfma_f32_16x16x32_bf16 v[102:105], v[44:47], v[150:153], v[32:35]
	v_mfma_f32_16x16x32_bf16 v[32:35], v[110:113], v[146:149], v[36:39]
	v_mfma_f32_16x16x32_bf16 v[98:101], v[114:117], v[142:145], v[56:59]
	v_mfma_f32_16x16x32_bf16 v[106:109], v[114:117], v[150:153], v[32:35]
	s_setprio 0
	s_setprio 1
	s_setprio 0
	s_barrier
	ds_read_b128 v[110:113], v157
	ds_read_b128 v[114:117], v157 offset:1024
	ds_read_b128 v[122:125], v157 offset:2048
	ds_read_b128 v[130:133], v157 offset:3072
	s_mov_b32 m0, s30
	ds_read_b128 v[32:35], v156 offset:32768
	ds_read_b128 v[36:39], v156 offset:33792
	ds_read_b128 v[40:43], v156 offset:34816
	ds_read_b128 v[44:47], v156 offset:35840
	ds_read_b128 v[134:137], v156 offset:36864
	ds_read_b128 v[138:141], v156 offset:37888
	ds_read_b128 v[142:145], v156 offset:38912
	ds_read_b128 v[146:149], v156 offset:39936
	global_load_lds_dwordx4 v[12:13], off
	s_mov_b32 m0, s34
	s_nop 0
	global_load_lds_dwordx4 v[16:17], off
	s_waitcnt vmcnt(8) lgkmcnt(0)
	s_setprio 1
	s_barrier
	v_mfma_f32_16x16x32_bf16 v[10:13], v[110:113], v[32:35], v[90:93]
	v_mfma_f32_16x16x32_bf16 v[58:61], v[114:117], v[36:39], v[10:13]
	v_mfma_f32_16x16x32_bf16 v[10:13], v[122:125], v[32:35], v[48:51]
	v_mfma_f32_16x16x32_bf16 v[62:65], v[130:133], v[36:39], v[10:13]
	v_mfma_f32_16x16x32_bf16 v[10:13], v[110:113], v[40:43], v[52:55]
	v_mfma_f32_16x16x32_bf16 v[50:53], v[114:117], v[44:47], v[10:13]
	v_mfma_f32_16x16x32_bf16 v[10:13], v[122:125], v[40:43], v[118:121]
	v_mfma_f32_16x16x32_bf16 v[54:57], v[130:133], v[44:47], v[10:13]
	v_mfma_f32_16x16x32_bf16 v[10:13], v[110:113], v[134:137], v[126:129]
	v_mfma_f32_16x16x32_bf16 v[42:45], v[114:117], v[138:141], v[10:13]
	v_mfma_f32_16x16x32_bf16 v[10:13], v[122:125], v[134:137], v[74:77]
	v_mfma_f32_16x16x32_bf16 v[46:49], v[130:133], v[138:141], v[10:13]
	v_mfma_f32_16x16x32_bf16 v[10:13], v[110:113], v[142:145], v[78:81]
	v_mfma_f32_16x16x32_bf16 v[34:37], v[114:117], v[146:149], v[10:13]
	v_mfma_f32_16x16x32_bf16 v[10:13], v[122:125], v[142:145], v[82:85]
	v_mfma_f32_16x16x32_bf16 v[38:41], v[130:133], v[146:149], v[10:13]
	s_setprio 0
	s_setprio 1
	s_setprio 0
	s_barrier
	s_mov_b32 m0, s36
	s_nop 1
	ds_read_b128 v[10:13], v156 offset:49152
	ds_read_b128 v[14:17], v156 offset:50176
	ds_read_b128 v[74:77], v156 offset:51200
	ds_read_b128 v[78:81], v156 offset:52224
	ds_read_b128 v[82:85], v156 offset:53248
	ds_read_b128 v[90:93], v156 offset:54272
	ds_read_b128 v[118:121], v156 offset:55296
	ds_read_b128 v[126:129], v156 offset:56320
	global_load_lds_dwordx4 v[26:27], off
	s_mov_b32 m0, s38
	s_nop 0
	global_load_lds_dwordx4 v[28:29], off
	s_mov_b32 m0, s40
	s_nop 0
	global_load_lds_dwordx4 v[68:69], off
	s_mov_b32 m0, s41
	s_nop 0
	global_load_lds_dwordx4 v[70:71], off
	s_mov_b32 m0, s37
	s_nop 0
	global_load_lds_dwordx4 v[24:25], off
	s_mov_b32 m0, s39
	s_nop 0
	global_load_lds_dwordx4 v[30:31], off
	s_waitcnt vmcnt(8) lgkmcnt(0)
	s_setprio 1
	s_barrier
	v_mfma_f32_16x16x32_bf16 v[2:5], v[110:113], v[10:13], v[2:5]
	v_mfma_f32_16x16x32_bf16 v[26:29], v[114:117], v[14:17], v[2:5]
	v_mfma_f32_16x16x32_bf16 v[2:5], v[122:125], v[10:13], v[6:9]
	v_mfma_f32_16x16x32_bf16 v[30:33], v[130:133], v[14:17], v[2:5]
	v_mfma_f32_16x16x32_bf16 v[2:5], v[110:113], v[74:77], v[18:21]
	v_mfma_f32_16x16x32_bf16 v[18:21], v[114:117], v[78:81], v[2:5]
	v_mfma_f32_16x16x32_bf16 v[2:5], v[122:125], v[74:77], v[86:89]
	v_mfma_f32_16x16x32_bf16 v[22:25], v[130:133], v[78:81], v[2:5]
	v_mfma_f32_16x16x32_bf16 v[2:5], v[110:113], v[82:85], v[94:97]
	v_mfma_f32_16x16x32_bf16 v[10:13], v[114:117], v[90:93], v[2:5]
	v_mfma_f32_16x16x32_bf16 v[2:5], v[122:125], v[82:85], v[98:101]
	v_mfma_f32_16x16x32_bf16 v[14:17], v[130:133], v[90:93], v[2:5]
	v_mfma_f32_16x16x32_bf16 v[2:5], v[110:113], v[118:121], v[102:105]
	v_mfma_f32_16x16x32_bf16 v[6:9], v[122:125], v[118:121], v[106:109]
	v_mfma_f32_16x16x32_bf16 v[2:5], v[114:117], v[126:129], v[2:5]
	v_mfma_f32_16x16x32_bf16 v[6:9], v[130:133], v[126:129], v[6:9]
	s_setprio 0
	s_setprio 1
	s_setprio 0
	s_barrier
	s_cbranch_scc1 .LBB0_594
	s_barrier

; #define PG8_STAGE(bufoff, gbase, voff) do { _Pragma("unroll") for (int _i = 0; _i < 2; ++_i) \
;         __builtin_amdgcn_global_load_lds((const unsigned*)((const char*)(gbase) + (voff)[_i]), (PG8_LAS unsigned*)(lds + (bufoff) + ldsw + _i * 8192), 16, 0, 0); } while (0)
; #define PG8_LDA(dst, b, h) do { _Pragma("unroll") for (int m = 0; m < 4; ++m) _Pragma("unroll") for (int k = 0; k < 2; ++k) dst[m][k] = *(const PG8_LAS bf16x8*)(lds + PG8_SA(b, h) + aoff + m * 2048 + k * 1024); } while (0)
; #define PG8_LDB(dst, b, h) do { _Pragma("unroll") for (int n = 0; n < 2; ++n) _Pragma("unroll") for (int k = 0; k < 2; ++k) dst[n][k] = *(const PG8_LAS bf16x8*)(lds + PG8_SB(b, h) + boff + n * 2048 + k * 1024); } while (0)
; #define PG8_MMA(ai, bj, At, Bt) do { __builtin_amdgcn_s_setprio(1); _Pragma("unroll") for (int m = 0; m < 4; ++m) _Pragma("unroll") for (int n = 0; n < 2; ++n) _Pragma("unroll") for (int k = 0; k < 2; ++k) \
;         acc[ai][bj][m][n] = __builtin_amdgcn_mfma_f32_16x16x32_bf16(Bt[n][k], At[m][k], acc[ai][bj][m][n], 0, 0, 0); __builtin_amdgcn_s_setprio(0); } while (0)
; #define PG8_WAIT_V(n) asm volatile("s_waitcnt vmcnt(" #n ")" ::: "memory")
; #define PG8_BAR __builtin_amdgcn_s_barrier()
; template <class Epi, class Sched, bool ALIGN_EPI = false, bool SP2 = false>
; __device__ __forceinline__ void gemm_phase(PG8_LAS unsigned char* lds, const Gemm g, const Sched& S, const Epi& E) {
;     ...
;         for (int t = 0; t < nt; t += 2) {
;             const bool last = (t == nt - 2);
;             const char* a1 = cA + (size_t)(t + 1) * kstep;
;             const char* a2 = last ? nA : cA + (size_t)(t + 2) * kstep; const char* b2 = last ? nB : cB + (size_t)(t + 2) * kstep;
;             const char* a3 = a2 + kstep; const char* b3 = b2 + kstep;
;             if (last && has_next) S.a_ready(nxt);
;             if constexpr (SP2) {
;             PG8_LDB(B0, 0, 0); PG8_LDB(B1, 0, 1); PG8_SCHED; PG8_LDA(At, 0, 0); PG8_STAGE(PG8_SA(1, 1), a1 + hstepA, voffA);
;             PG8_WAIT_V(8); PG8_WAIT_L(0); PG8_BAR; PG8_MMA(0, 0, At, B0); PG8_MMA(0, 1, At, B1); PG8_BAR; PG8_SCHED;
;             PG8_LDA(At, 0, 1); PG8_STAGE(PG8_SB(0, 0), b2, voffB); PG8_STAGE(PG8_SB(0, 1), b2 + hstepB, voffB); PG8_STAGE(PG8_SA(0, 0), a2, voffA);
;             PG8_WAIT_V(8); PG8_WAIT_L(0); PG8_BAR; PG8_MMA(1, 0, At, B0); PG8_MMA(1, 1, At, B1); PG8_BAR; PG8_SCHED;
.LBB0_1160:
	s_add_u32 s24, s22, 0x100
	s_addc_u32 s25, s23, 0
	s_add_i32 s57, 0, 0x10000
	s_cmp_eq_u32 s56, 4
	s_cselect_b32 s29, s17, s25
	s_cselect_b32 s28, s16, s24
	v_add_u32_e32 v145, s57, v142
	s_cselect_b32 s27, s52, s55
	s_cselect_b32 s26, s53, s54
	s_add_i32 s58, 0, 0x14000
	ds_read_b128 v[146:149], v145
	ds_read_b128 v[150:153], v145 offset:1024
	ds_read_b128 v[154:157], v145 offset:2048
	ds_read_b128 v[158:161], v145 offset:3072
	v_add_u32_e32 v145, s58, v142
	ds_read_b128 v[162:165], v145
	ds_read_b128 v[166:169], v145 offset:1024
	ds_read_b128 v[170:173], v145 offset:2048
	ds_read_b128 v[174:177], v145 offset:3072
	s_add_i32 m0, s39, 0xc000
	ds_read_b128 v[178:181], v143
	ds_read_b128 v[182:185], v143 offset:1024
	ds_read_b128 v[202:205], v143 offset:2048
	ds_read_b128 v[206:209], v143 offset:3072
	ds_read_b128 v[210:213], v143 offset:4096
	ds_read_b128 v[232:235], v143 offset:5120
	ds_read_b128 v[236:239], v143 offset:6144
	ds_read_b128 v[240:243], v143 offset:7168
	global_load_lds_dwordx4 v138, s[22:23]
	s_add_i32 m0, s39, 0xe000
	s_nop 0
	global_load_lds_dwordx4 v140, s[22:23]
	s_waitcnt vmcnt(8) lgkmcnt(0)
	s_setprio 1
	s_barrier
	v_mfma_f32_16x16x32_bf16 v[126:129], v[146:149], v[178:181], v[126:129]
	v_mfma_f32_16x16x32_bf16 v[122:125], v[154:157], v[178:181], v[122:125]
	v_mfma_f32_16x16x32_bf16 v[118:121], v[146:149], v[202:205], v[118:121]
	v_mfma_f32_16x16x32_bf16 v[114:117], v[154:157], v[202:205], v[114:117]
	v_mfma_f32_16x16x32_bf16 v[110:113], v[146:149], v[210:213], v[110:113]
	v_mfma_f32_16x16x32_bf16 v[106:109], v[154:157], v[210:213], v[106:109]
	v_mfma_f32_16x16x32_bf16 v[102:105], v[146:149], v[236:239], v[102:105]
	v_mfma_f32_16x16x32_bf16 v[98:101], v[154:157], v[236:239], v[98:101]
	v_mfma_f32_16x16x32_bf16 v[126:129], v[150:153], v[182:185], v[126:129]
	v_mfma_f32_16x16x32_bf16 v[122:125], v[158:161], v[182:185], v[122:125]
	v_mfma_f32_16x16x32_bf16 v[118:121], v[150:153], v[206:209], v[118:121]
	v_mfma_f32_16x16x32_bf16 v[114:117], v[158:161], v[206:209], v[114:117]
	v_mfma_f32_16x16x32_bf16 v[110:113], v[150:153], v[232:235], v[110:113]
	v_mfma_f32_16x16x32_bf16 v[106:109], v[158:161], v[232:235], v[106:109]
	v_mfma_f32_16x16x32_bf16 v[102:105], v[150:153], v[240:243], v[102:105]
	v_mfma_f32_16x16x32_bf16 v[98:101], v[158:161], v[240:243], v[98:101]
	s_setprio 0
	s_setprio 1
	v_mfma_f32_16x16x32_bf16 v[78:81], v[162:165], v[178:181], v[78:81]
	v_mfma_f32_16x16x32_bf16 v[70:73], v[170:173], v[178:181], v[70:73]
	v_mfma_f32_16x16x32_bf16 v[62:65], v[162:165], v[202:205], v[62:65]
	v_mfma_f32_16x16x32_bf16 v[54:57], v[170:173], v[202:205], v[54:57]
	v_mfma_f32_16x16x32_bf16 v[46:49], v[162:165], v[210:213], v[46:49]
	v_mfma_f32_16x16x32_bf16 v[42:45], v[170:173], v[210:213], v[42:45]
	v_mfma_f32_16x16x32_bf16 v[38:41], v[162:165], v[236:239], v[38:41]
	v_mfma_f32_16x16x32_bf16 v[34:37], v[170:173], v[236:239], v[34:37]
	v_mfma_f32_16x16x32_bf16 v[78:81], v[166:169], v[182:185], v[78:81]
	v_mfma_f32_16x16x32_bf16 v[70:73], v[174:177], v[182:185], v[70:73]
	v_mfma_f32_16x16x32_bf16 v[62:65], v[166:169], v[206:209], v[62:65]
	v_mfma_f32_16x16x32_bf16 v[54:57], v[174:177], v[206:209], v[54:57]
	v_mfma_f32_16x16x32_bf16 v[46:49], v[166:169], v[232:235], v[46:49]
	v_mfma_f32_16x16x32_bf16 v[42:45], v[174:177], v[232:235], v[42:45]
	v_mfma_f32_16x16x32_bf16 v[38:41], v[166:169], v[240:243], v[38:41]
	v_mfma_f32_16x16x32_bf16 v[34:37], v[174:177], v[240:243], v[34:37]
	s_setprio 0
	s_barrier
	s_add_i32 s22, s57, s38
	s_mov_b32 m0, s22
	ds_read_b128 v[178:181], v143 offset:16384
	ds_read_b128 v[182:185], v143 offset:17408
	ds_read_b128 v[202:205], v143 offset:18432
	ds_read_b128 v[206:209], v143 offset:19456
	ds_read_b128 v[210:213], v143 offset:20480
	ds_read_b128 v[232:235], v143 offset:21504
	ds_read_b128 v[236:239], v143 offset:22528
	ds_read_b128 v[240:243], v143 offset:23552
	s_add_u32 s60, s26, 0x80
	s_addc_u32 s61, s27, 0
	s_add_u32 s62, s28, 0x80
	s_addc_u32 s63, s29, 0
	global_load_lds_dwordx4 v134, s[26:27]
	s_add_i32 m0, s22, 0x2000
	s_add_u32 s22, s26, 0x20000
	s_addc_u32 s23, s27, 0
	s_add_i32 s57, s58, s38
	global_load_lds_dwordx4 v130, s[26:27]
	s_mov_b32 m0, s57
	s_nop 0
	global_load_lds_dwordx4 v134, s[22:23]
	s_add_i32 m0, s57, 0x2000
	s_nop 0
	global_load_lds_dwordx4 v130, s[22:23]
	s_mov_b32 m0, s39
	s_nop 0
	global_load_lds_dwordx4 v136, s[28:29]
	s_mov_b32 m0, s40
	s_nop 0
	global_load_lds_dwordx4 v132, s[28:29]
	s_waitcnt vmcnt(8) lgkmcnt(0)
	s_setprio 1
	s_barrier
	v_mfma_f32_16x16x32_bf16 v[94:97], v[146:149], v[178:181], v[94:97]
	v_mfma_f32_16x16x32_bf16 v[90:93], v[154:157], v[178:181], v[90:93]
	v_mfma_f32_16x16x32_bf16 v[86:89], v[146:149], v[202:205], v[86:89]
	v_mfma_f32_16x16x32_bf16 v[82:85], v[154:157], v[202:205], v[82:85]
	v_mfma_f32_16x16x32_bf16 v[74:77], v[146:149], v[210:213], v[74:77]
	v_mfma_f32_16x16x32_bf16 v[66:69], v[154:157], v[210:213], v[66:69]
	v_mfma_f32_16x16x32_bf16 v[58:61], v[146:149], v[236:239], v[58:61]
	v_mfma_f32_16x16x32_bf16 v[50:53], v[154:157], v[236:239], v[50:53]
	v_mfma_f32_16x16x32_bf16 v[94:97], v[150:153], v[182:185], v[94:97]
	v_mfma_f32_16x16x32_bf16 v[90:93], v[158:161], v[182:185], v[90:93]
	v_mfma_f32_16x16x32_bf16 v[86:89], v[150:153], v[206:209], v[86:89]
	v_mfma_f32_16x16x32_bf16 v[82:85], v[158:161], v[206:209], v[82:85]
	v_mfma_f32_16x16x32_bf16 v[74:77], v[150:153], v[232:235], v[74:77]
	v_mfma_f32_16x16x32_bf16 v[66:69], v[158:161], v[232:235], v[66:69]
	v_mfma_f32_16x16x32_bf16 v[58:61], v[150:153], v[240:243], v[58:61]
	v_mfma_f32_16x16x32_bf16 v[50:53], v[158:161], v[240:243], v[50:53]
	s_setprio 0
	s_setprio 1
	v_mfma_f32_16x16x32_bf16 v[30:33], v[162:165], v[178:181], v[30:33]
	v_mfma_f32_16x16x32_bf16 v[26:29], v[170:173], v[178:181], v[26:29]
	v_mfma_f32_16x16x32_bf16 v[22:25], v[162:165], v[202:205], v[22:25]
	v_mfma_f32_16x16x32_bf16 v[18:21], v[170:173], v[202:205], v[18:21]
	v_mfma_f32_16x16x32_bf16 v[14:17], v[162:165], v[210:213], v[14:17]
	v_mfma_f32_16x16x32_bf16 v[10:13], v[170:173], v[210:213], v[10:13]
	v_mfma_f32_16x16x32_bf16 v[6:9], v[162:165], v[236:239], v[6:9]
	v_mfma_f32_16x16x32_bf16 v[2:5], v[170:173], v[236:239], v[2:5]
	v_mfma_f32_16x16x32_bf16 v[30:33], v[166:169], v[182:185], v[30:33]
	v_mfma_f32_16x16x32_bf16 v[26:29], v[174:177], v[182:185], v[26:29]
	v_mfma_f32_16x16x32_bf16 v[22:25], v[166:169], v[206:209], v[22:25]
	v_mfma_f32_16x16x32_bf16 v[18:21], v[174:177], v[206:209], v[18:21]
	v_mfma_f32_16x16x32_bf16 v[14:17], v[166:169], v[232:235], v[14:17]
	v_mfma_f32_16x16x32_bf16 v[10:13], v[174:177], v[232:235], v[10:13]
	v_mfma_f32_16x16x32_bf16 v[6:9], v[166:169], v[240:243], v[6:9]
	v_mfma_f32_16x16x32_bf16 v[2:5], v[174:177], v[240:243], v[2:5]
	s_setprio 0
	s_barrier
; #define PG8_STAGE(bufoff, gbase, voff) do { _Pragma("unroll") for (int _i = 0; _i < 2; ++_i) \
;         __builtin_amdgcn_global_load_lds((const unsigned*)((const char*)(gbase) + (voff)[_i]), (PG8_LAS unsigned*)(lds + (bufoff) + ldsw + _i * 8192), 16, 0, 0); } while (0)
; #define PG8_LDA(dst, b, h) do { _Pragma("unroll") for (int m = 0; m < 4; ++m) _Pragma("unroll") for (int k = 0; k < 2; ++k) dst[m][k] = *(const PG8_LAS bf16x8*)(lds + PG8_SA(b, h) + aoff + m * 2048 + k * 1024); } while (0)
; #define PG8_LDB(dst, b, h) do { _Pragma("unroll") for (int n = 0; n < 2; ++n) _Pragma("unroll") for (int k = 0; k < 2; ++k) dst[n][k] = *(const PG8_LAS bf16x8*)(lds + PG8_SB(b, h) + boff + n * 2048 + k * 1024); } while (0)
; #define PG8_MMA(ai, bj, At, Bt) do { __builtin_amdgcn_s_setprio(1); _Pragma("unroll") for (int m = 0; m < 4; ++m) _Pragma("unroll") for (int n = 0; n < 2; ++n) _Pragma("unroll") for (int k = 0; k < 2; ++k) \
;         acc[ai][bj][m][n] = __builtin_amdgcn_mfma_f32_16x16x32_bf16(Bt[n][k], At[m][k], acc[ai][bj][m][n], 0, 0, 0); __builtin_amdgcn_s_setprio(0); } while (0)
; #define PG8_WAIT_V(n) asm volatile("s_waitcnt vmcnt(" #n ")" ::: "memory")
; #define PG8_WAIT_L(n) asm volatile("s_waitcnt lgkmcnt(" #n ")" ::: "memory")
; #define PG8_BAR __builtin_amdgcn_s_barrier()
; #define PG8_SCHED __builtin_amdgcn_sched_barrier(0)
; template <class Epi, class Sched, bool ALIGN_EPI = false, bool SP2 = false>
; __device__ __forceinline__ void gemm_phase(PG8_LAS unsigned char* lds, const Gemm g, const Sched& S, const Epi& E) {
;     ...
;             PG8_LDB(B0, 1, 0); PG8_LDB(B1, 1, 1); PG8_SCHED; PG8_LDA(At, 1, 0); PG8_STAGE(PG8_SA(0, 1), a2 + hstepA, voffA);
;             PG8_WAIT_V(8); PG8_WAIT_L(0); PG8_BAR; PG8_MMA(0, 0, At, B0); PG8_MMA(0, 1, At, B1); PG8_BAR; PG8_SCHED;
;             PG8_LDA(At, 1, 1); PG8_STAGE(PG8_SB(1, 0), b3, voffB); PG8_STAGE(PG8_SB(1, 1), b3 + hstepB, voffB); PG8_STAGE(PG8_SA(1, 0), a3, voffA);
;             PG8_WAIT_V(8); PG8_WAIT_L(0); PG8_BAR; PG8_MMA(1, 0, At, B0); PG8_MMA(1, 1, At, B1); PG8_BAR; PG8_SCHED;
;     ...
;         }
;         if constexpr (ALIGN_EPI) { if (wr == 0) PG8_BAR; }
	s_add_i32 s57, 0, 0x18000
	v_add_u32_e32 v145, s57, v142
	s_add_i32 s58, 0, 0x1c000
	ds_read_b128 v[146:149], v145
	ds_read_b128 v[150:153], v145 offset:1024
	ds_read_b128 v[154:157], v145 offset:2048
	ds_read_b128 v[158:161], v145 offset:3072
	v_add_u32_e32 v145, s58, v142
	ds_read_b128 v[162:165], v145
	ds_read_b128 v[166:169], v145 offset:1024
	ds_read_b128 v[170:173], v145 offset:2048
	ds_read_b128 v[174:177], v145 offset:3072
	s_add_u32 s22, s28, 0x30000
	s_addc_u32 s23, s29, 0
	s_mov_b32 m0, s41
	ds_read_b128 v[178:181], v143 offset:32768
	ds_read_b128 v[182:185], v143 offset:33792
	ds_read_b128 v[202:205], v143 offset:34816
	ds_read_b128 v[206:209], v143 offset:35840
	ds_read_b128 v[210:213], v143 offset:36864
	ds_read_b128 v[232:235], v143 offset:37888
	ds_read_b128 v[236:239], v143 offset:38912
	ds_read_b128 v[240:243], v143 offset:39936
	global_load_lds_dwordx4 v136, s[22:23]
	s_mov_b32 m0, s42
	s_nop 0
	global_load_lds_dwordx4 v132, s[22:23]
	s_waitcnt vmcnt(8) lgkmcnt(0)
	s_setprio 1
	s_barrier
	v_mfma_f32_16x16x32_bf16 v[126:129], v[146:149], v[178:181], v[126:129]
	v_mfma_f32_16x16x32_bf16 v[122:125], v[154:157], v[178:181], v[122:125]
	v_mfma_f32_16x16x32_bf16 v[118:121], v[146:149], v[202:205], v[118:121]
	v_mfma_f32_16x16x32_bf16 v[114:117], v[154:157], v[202:205], v[114:117]
	v_mfma_f32_16x16x32_bf16 v[110:113], v[146:149], v[210:213], v[110:113]
	v_mfma_f32_16x16x32_bf16 v[106:109], v[154:157], v[210:213], v[106:109]
	v_mfma_f32_16x16x32_bf16 v[102:105], v[146:149], v[236:239], v[102:105]
	v_mfma_f32_16x16x32_bf16 v[98:101], v[154:157], v[236:239], v[98:101]
	v_mfma_f32_16x16x32_bf16 v[126:129], v[150:153], v[182:185], v[126:129]
	v_mfma_f32_16x16x32_bf16 v[122:125], v[158:161], v[182:185], v[122:125]
	v_mfma_f32_16x16x32_bf16 v[118:121], v[150:153], v[206:209], v[118:121]
	v_mfma_f32_16x16x32_bf16 v[114:117], v[158:161], v[206:209], v[114:117]
	v_mfma_f32_16x16x32_bf16 v[110:113], v[150:153], v[232:235], v[110:113]
	v_mfma_f32_16x16x32_bf16 v[106:109], v[158:161], v[232:235], v[106:109]
	v_mfma_f32_16x16x32_bf16 v[102:105], v[150:153], v[240:243], v[102:105]
	v_mfma_f32_16x16x32_bf16 v[98:101], v[158:161], v[240:243], v[98:101]
	s_setprio 0
	s_setprio 1
	v_mfma_f32_16x16x32_bf16 v[78:81], v[162:165], v[178:181], v[78:81]
	v_mfma_f32_16x16x32_bf16 v[70:73], v[170:173], v[178:181], v[70:73]
	v_mfma_f32_16x16x32_bf16 v[62:65], v[162:165], v[202:205], v[62:65]
	v_mfma_f32_16x16x32_bf16 v[54:57], v[170:173], v[202:205], v[54:57]
	v_mfma_f32_16x16x32_bf16 v[46:49], v[162:165], v[210:213], v[46:49]
	v_mfma_f32_16x16x32_bf16 v[42:45], v[170:173], v[210:213], v[42:45]
	v_mfma_f32_16x16x32_bf16 v[38:41], v[162:165], v[236:239], v[38:41]
	v_mfma_f32_16x16x32_bf16 v[34:37], v[170:173], v[236:239], v[34:37]
	v_mfma_f32_16x16x32_bf16 v[78:81], v[166:169], v[182:185], v[78:81]
	v_mfma_f32_16x16x32_bf16 v[70:73], v[174:177], v[182:185], v[70:73]
	v_mfma_f32_16x16x32_bf16 v[62:65], v[166:169], v[206:209], v[62:65]
	v_mfma_f32_16x16x32_bf16 v[54:57], v[174:177], v[206:209], v[54:57]
	v_mfma_f32_16x16x32_bf16 v[46:49], v[166:169], v[232:235], v[46:49]
	v_mfma_f32_16x16x32_bf16 v[42:45], v[174:177], v[232:235], v[42:45]
	v_mfma_f32_16x16x32_bf16 v[38:41], v[166:169], v[240:243], v[38:41]
	v_mfma_f32_16x16x32_bf16 v[34:37], v[174:177], v[240:243], v[34:37]
	s_setprio 0
	s_barrier
	s_add_i32 s22, s57, s38
	s_mov_b32 m0, s22
	ds_read_b128 v[178:181], v143 offset:49152
	ds_read_b128 v[182:185], v143 offset:50176
	ds_read_b128 v[202:205], v143 offset:51200
	ds_read_b128 v[206:209], v143 offset:52224
	ds_read_b128 v[210:213], v143 offset:53248
	ds_read_b128 v[232:235], v143 offset:54272
	ds_read_b128 v[236:239], v143 offset:55296
	ds_read_b128 v[240:243], v143 offset:56320
	global_load_lds_dwordx4 v134, s[60:61]
	s_add_i32 m0, s22, 0x2000
	s_add_u32 s22, s26, 0x20080
	s_addc_u32 s23, s27, 0
	s_add_i32 s26, s58, s38
	global_load_lds_dwordx4 v130, s[60:61]
	s_mov_b32 m0, s26
	s_nop 0
	global_load_lds_dwordx4 v134, s[22:23]
	s_add_i32 m0, s26, 0x2000
	s_nop 0
	global_load_lds_dwordx4 v130, s[22:23]
	s_mov_b32 m0, s43
	s_nop 0
	global_load_lds_dwordx4 v136, s[62:63]
	s_mov_b32 m0, s46
	s_nop 0
	global_load_lds_dwordx4 v132, s[62:63]
	s_waitcnt vmcnt(8) lgkmcnt(0)
	s_setprio 1
	s_barrier
	v_mfma_f32_16x16x32_bf16 v[94:97], v[146:149], v[178:181], v[94:97]
	v_mfma_f32_16x16x32_bf16 v[90:93], v[154:157], v[178:181], v[90:93]
	v_mfma_f32_16x16x32_bf16 v[86:89], v[146:149], v[202:205], v[86:89]
	v_mfma_f32_16x16x32_bf16 v[82:85], v[154:157], v[202:205], v[82:85]
	v_mfma_f32_16x16x32_bf16 v[74:77], v[146:149], v[210:213], v[74:77]
	v_mfma_f32_16x16x32_bf16 v[66:69], v[154:157], v[210:213], v[66:69]
	v_mfma_f32_16x16x32_bf16 v[58:61], v[146:149], v[236:239], v[58:61]
	v_mfma_f32_16x16x32_bf16 v[50:53], v[154:157], v[236:239], v[50:53]
	v_mfma_f32_16x16x32_bf16 v[94:97], v[150:153], v[182:185], v[94:97]
	v_mfma_f32_16x16x32_bf16 v[90:93], v[158:161], v[182:185], v[90:93]
	v_mfma_f32_16x16x32_bf16 v[86:89], v[150:153], v[206:209], v[86:89]
	v_mfma_f32_16x16x32_bf16 v[82:85], v[158:161], v[206:209], v[82:85]
	v_mfma_f32_16x16x32_bf16 v[74:77], v[150:153], v[232:235], v[74:77]
	v_mfma_f32_16x16x32_bf16 v[66:69], v[158:161], v[232:235], v[66:69]
	v_mfma_f32_16x16x32_bf16 v[58:61], v[150:153], v[240:243], v[58:61]
	v_mfma_f32_16x16x32_bf16 v[50:53], v[158:161], v[240:243], v[50:53]
	s_setprio 0
	s_setprio 1
	v_mfma_f32_16x16x32_bf16 v[30:33], v[162:165], v[178:181], v[30:33]
	v_mfma_f32_16x16x32_bf16 v[26:29], v[170:173], v[178:181], v[26:29]
	v_mfma_f32_16x16x32_bf16 v[22:25], v[162:165], v[202:205], v[22:25]
	v_mfma_f32_16x16x32_bf16 v[18:21], v[170:173], v[202:205], v[18:21]
	v_mfma_f32_16x16x32_bf16 v[14:17], v[162:165], v[210:213], v[14:17]
	v_mfma_f32_16x16x32_bf16 v[10:13], v[170:173], v[210:213], v[10:13]
	v_mfma_f32_16x16x32_bf16 v[6:9], v[162:165], v[236:239], v[6:9]
	v_mfma_f32_16x16x32_bf16 v[2:5], v[170:173], v[236:239], v[2:5]
	v_mfma_f32_16x16x32_bf16 v[30:33], v[166:169], v[182:185], v[30:33]
	v_mfma_f32_16x16x32_bf16 v[26:29], v[174:177], v[182:185], v[26:29]
	v_mfma_f32_16x16x32_bf16 v[22:25], v[166:169], v[206:209], v[22:25]
	v_mfma_f32_16x16x32_bf16 v[18:21], v[174:177], v[206:209], v[18:21]
	v_mfma_f32_16x16x32_bf16 v[14:17], v[166:169], v[232:235], v[14:17]
	v_mfma_f32_16x16x32_bf16 v[10:13], v[174:177], v[232:235], v[10:13]
	v_mfma_f32_16x16x32_bf16 v[6:9], v[166:169], v[240:243], v[6:9]
	v_mfma_f32_16x16x32_bf16 v[2:5], v[174:177], v[240:243], v[2:5]
	s_setprio 0
	s_barrier
	s_add_i32 s56, s56, 2
	s_add_u32 s54, s54, 0x100
	s_addc_u32 s55, s55, 0
	s_cmp_gt_u32 s56, 5
	s_mov_b64 s[22:23], s[24:25]
	s_cbranch_scc0 .LBB0_1160
	s_and_b64 vcc, exec, s[8:9]
	s_cbranch_vccz .LBB0_1163
	s_barrier

; #define PG8_STAGE(bufoff, gbase, voff) do { _Pragma("unroll") for (int _i = 0; _i < 2; ++_i) \
;         __builtin_amdgcn_global_load_lds((const unsigned*)((const char*)(gbase) + (voff)[_i]), (PG8_LAS unsigned*)(lds + (bufoff) + ldsw + _i * 8192), 16, 0, 0); } while (0)
; #define PG8_LDA(dst, b, h) do { _Pragma("unroll") for (int m = 0; m < 4; ++m) _Pragma("unroll") for (int k = 0; k < 2; ++k) dst[m][k] = *(const PG8_LAS bf16x8*)(lds + PG8_SA(b, h) + aoff + m * 2048 + k * 1024); } while (0)
; #define PG8_LDB(dst, b, h) do { _Pragma("unroll") for (int n = 0; n < 2; ++n) _Pragma("unroll") for (int k = 0; k < 2; ++k) dst[n][k] = *(const PG8_LAS bf16x8*)(lds + PG8_SB(b, h) + boff + n * 2048 + k * 1024); } while (0)
; #define PG8_MMA(ai, bj, At, Bt) do { __builtin_amdgcn_s_setprio(1); _Pragma("unroll") for (int m = 0; m < 4; ++m) _Pragma("unroll") for (int n = 0; n < 2; ++n) _Pragma("unroll") for (int k = 0; k < 2; ++k) \
;         acc[ai][bj][m][n] = __builtin_amdgcn_mfma_f32_16x16x32_bf16(Bt[n][k], At[m][k], acc[ai][bj][m][n], 0, 0, 0); __builtin_amdgcn_s_setprio(0); } while (0)
; #define PG8_WAIT_V(n) asm volatile("s_waitcnt vmcnt(" #n ")" ::: "memory")
; #define PG8_BAR __builtin_amdgcn_s_barrier()
; template <class Epi, class Sched, bool ALIGN_EPI = false, bool SP2 = false>
; __device__ __forceinline__ void gemm_phase(PG8_LAS unsigned char* lds, const Gemm g, const Sched& S, const Epi& E) {
;     ...
;         for (int t = 0; t < nt; t += 2) {
;             const bool last = (t == nt - 2);
;             const char* a1 = cA + (size_t)(t + 1) * kstep;
;             const char* a2 = last ? nA : cA + (size_t)(t + 2) * kstep; const char* b2 = last ? nB : cB + (size_t)(t + 2) * kstep;
;             const char* a3 = a2 + kstep; const char* b3 = b2 + kstep;
;             if (last && has_next) S.a_ready(nxt);
;             if constexpr (SP2) {
;             PG8_LDB(B0, 0, 0); PG8_LDB(B1, 0, 1); PG8_SCHED; PG8_LDA(At, 0, 0); PG8_STAGE(PG8_SA(1, 1), a1 + hstepA, voffA);
;             PG8_WAIT_V(8); PG8_WAIT_L(0); PG8_BAR; PG8_MMA(0, 0, At, B0); PG8_MMA(0, 1, At, B1); PG8_BAR; PG8_SCHED;
;             PG8_LDA(At, 0, 1); PG8_STAGE(PG8_SB(0, 0), b2, voffB); PG8_STAGE(PG8_SB(0, 1), b2 + hstepB, voffB); PG8_STAGE(PG8_SA(0, 0), a2, voffA);
;             PG8_WAIT_V(8); PG8_WAIT_L(0); PG8_BAR; PG8_MMA(1, 0, At, B0); PG8_MMA(1, 1, At, B1); PG8_BAR; PG8_SCHED;
.LBB0_1176:
	s_add_u32 s35, s26, s34
	s_addc_u32 s40, s27, 0
	s_add_u32 s38, s35, 0x100
	s_addc_u32 s39, s40, 0
	s_and_b64 s[36:37], s[30:31], exec
	s_cselect_b32 s37, s19, s39
	s_cselect_b32 s36, s18, s38
	s_add_u32 s34, s24, s34
	s_addc_u32 s38, s25, 0
	s_add_u32 s34, s34, 0x100
	s_addc_u32 s38, s38, 0
	s_add_i32 s72, 0, 0x10000
	s_and_b64 s[30:31], s[30:31], exec
	s_cselect_b32 s39, s61, s38
	s_cselect_b32 s38, s62, s34
	s_add_i32 s31, 0, 0x14000
	s_add_u32 s42, s35, 0x30080
	s_addc_u32 s43, s40, 0
	s_add_i32 s71, s72, s50
	s_add_i32 m0, s51, 0xc000
	s_add_i32 s74, s51, 0xe000
	s_add_i32 s67, s71, 0x2000
	v_add_u32_e32 v141, s72, v138
	s_add_u32 s40, s38, 0x10000
	ds_read_b128 v[142:145], v141
	ds_read_b128 v[146:149], v141 offset:1024
	ds_read_b128 v[150:153], v141 offset:2048
	ds_read_b128 v[154:157], v141 offset:3072
	v_add_u32_e32 v141, s31, v138
	s_addc_u32 s41, s39, 0
	s_add_i32 s69, s31, s50
	ds_read_b128 v[158:161], v141
	ds_read_b128 v[162:165], v141 offset:1024
	ds_read_b128 v[166:169], v141 offset:2048
	ds_read_b128 v[170:173], v141 offset:3072
	s_add_i32 s68, s69, 0x2000
	s_add_i32 s66, 0, 0x18000
	s_add_i32 s65, 0, 0x1c000
	s_add_u32 s34, s36, 0x30000
	s_addc_u32 s35, s37, 0
	s_add_i32 s64, s66, s50
	s_add_i32 s63, s64, 0x2000
	s_add_u32 s30, s38, 0x10080
	s_addc_u32 s31, s39, 0
	s_add_i32 s73, s65, s50
	s_add_i32 s72, s73, 0x2000
	v_lshl_add_u64 v[186:187], s[42:43], 0, v[136:137]
	ds_read_b128 v[174:177], v140
	ds_read_b128 v[178:181], v140 offset:1024
	ds_read_b128 v[182:185], v140 offset:2048
	ds_read_b128 v[202:205], v140 offset:3072
	ds_read_b128 v[206:209], v140 offset:4096
	ds_read_b128 v[210:213], v140 offset:5120
	ds_read_b128 v[232:235], v140 offset:6144
	ds_read_b128 v[236:239], v140 offset:7168
	global_load_lds_dwordx4 v[186:187], off
	v_lshl_add_u64 v[186:187], s[42:43], 0, v[132:133]
	s_mov_b32 m0, s74
	s_nop 0
	global_load_lds_dwordx4 v[186:187], off
	s_waitcnt vmcnt(8) lgkmcnt(0)
	s_setprio 1
	s_barrier
	v_mfma_f32_16x16x32_bf16 v[126:129], v[142:145], v[174:177], v[126:129]
	v_mfma_f32_16x16x32_bf16 v[122:125], v[150:153], v[174:177], v[122:125]
	v_mfma_f32_16x16x32_bf16 v[118:121], v[142:145], v[182:185], v[118:121]
	v_mfma_f32_16x16x32_bf16 v[114:117], v[150:153], v[182:185], v[114:117]
	v_mfma_f32_16x16x32_bf16 v[110:113], v[142:145], v[206:209], v[110:113]
	v_mfma_f32_16x16x32_bf16 v[106:109], v[150:153], v[206:209], v[106:109]
	v_mfma_f32_16x16x32_bf16 v[102:105], v[142:145], v[232:235], v[102:105]
	v_mfma_f32_16x16x32_bf16 v[98:101], v[150:153], v[232:235], v[98:101]
	v_mfma_f32_16x16x32_bf16 v[126:129], v[146:149], v[178:181], v[126:129]
	v_mfma_f32_16x16x32_bf16 v[122:125], v[154:157], v[178:181], v[122:125]
	v_mfma_f32_16x16x32_bf16 v[118:121], v[146:149], v[202:205], v[118:121]
	v_mfma_f32_16x16x32_bf16 v[114:117], v[154:157], v[202:205], v[114:117]
	v_mfma_f32_16x16x32_bf16 v[110:113], v[146:149], v[210:213], v[110:113]
	v_mfma_f32_16x16x32_bf16 v[106:109], v[154:157], v[210:213], v[106:109]
	v_mfma_f32_16x16x32_bf16 v[102:105], v[146:149], v[236:239], v[102:105]
	v_mfma_f32_16x16x32_bf16 v[98:101], v[154:157], v[236:239], v[98:101]
	s_setprio 0
	s_setprio 1
	v_mfma_f32_16x16x32_bf16 v[78:81], v[158:161], v[174:177], v[78:81]
	v_mfma_f32_16x16x32_bf16 v[70:73], v[166:169], v[174:177], v[70:73]
	v_mfma_f32_16x16x32_bf16 v[62:65], v[158:161], v[182:185], v[62:65]
	v_mfma_f32_16x16x32_bf16 v[54:57], v[166:169], v[182:185], v[54:57]
	v_mfma_f32_16x16x32_bf16 v[46:49], v[158:161], v[206:209], v[46:49]
	v_mfma_f32_16x16x32_bf16 v[42:45], v[166:169], v[206:209], v[42:45]
	v_mfma_f32_16x16x32_bf16 v[38:41], v[158:161], v[232:235], v[38:41]
	v_mfma_f32_16x16x32_bf16 v[34:37], v[166:169], v[232:235], v[34:37]
	v_mfma_f32_16x16x32_bf16 v[78:81], v[162:165], v[178:181], v[78:81]
	v_mfma_f32_16x16x32_bf16 v[70:73], v[170:173], v[178:181], v[70:73]
	v_mfma_f32_16x16x32_bf16 v[62:65], v[162:165], v[202:205], v[62:65]
	v_mfma_f32_16x16x32_bf16 v[54:57], v[170:173], v[202:205], v[54:57]
	v_mfma_f32_16x16x32_bf16 v[46:49], v[162:165], v[210:213], v[46:49]
	v_mfma_f32_16x16x32_bf16 v[42:45], v[170:173], v[210:213], v[42:45]
	v_mfma_f32_16x16x32_bf16 v[38:41], v[162:165], v[236:239], v[38:41]
	v_mfma_f32_16x16x32_bf16 v[34:37], v[170:173], v[236:239], v[34:37]
	s_setprio 0
	s_barrier
	s_mov_b32 m0, s71
	v_lshl_add_u64 v[186:187], s[38:39], 0, v[134:135]
	ds_read_b128 v[174:177], v140 offset:16384
	ds_read_b128 v[178:181], v140 offset:17408
	ds_read_b128 v[182:185], v140 offset:18432
	ds_read_b128 v[202:205], v140 offset:19456
	ds_read_b128 v[206:209], v140 offset:20480
	ds_read_b128 v[210:213], v140 offset:21504
	ds_read_b128 v[232:235], v140 offset:22528
	ds_read_b128 v[236:239], v140 offset:23552
	global_load_lds_dwordx4 v[186:187], off
	v_lshl_add_u64 v[214:215], s[38:39], 0, v[130:131]
	s_mov_b32 m0, s67
	v_lshl_add_u64 v[240:241], s[40:41], 0, v[134:135]
	global_load_lds_dwordx4 v[214:215], off
	s_mov_b32 m0, s69
	v_lshl_add_u64 v[242:243], s[36:37], 0, v[132:133]
	global_load_lds_dwordx4 v[240:241], off
	v_lshl_add_u64 v[240:241], s[40:41], 0, v[130:131]
	s_mov_b32 m0, s68
	s_nop 0
	global_load_lds_dwordx4 v[240:241], off
	v_lshl_add_u64 v[240:241], s[36:37], 0, v[136:137]
	s_mov_b32 m0, s51
	s_nop 0
	global_load_lds_dwordx4 v[240:241], off
	s_mov_b32 m0, s52
	s_nop 0
	global_load_lds_dwordx4 v[242:243], off
	s_waitcnt vmcnt(8) lgkmcnt(0)
	s_setprio 1
	s_barrier
; #define PG8_STAGE(bufoff, gbase, voff) do { _Pragma("unroll") for (int _i = 0; _i < 2; ++_i) \
;         __builtin_amdgcn_global_load_lds((const unsigned*)((const char*)(gbase) + (voff)[_i]), (PG8_LAS unsigned*)(lds + (bufoff) + ldsw + _i * 8192), 16, 0, 0); } while (0)
; #define PG8_LDA(dst, b, h) do { _Pragma("unroll") for (int m = 0; m < 4; ++m) _Pragma("unroll") for (int k = 0; k < 2; ++k) dst[m][k] = *(const PG8_LAS bf16x8*)(lds + PG8_SA(b, h) + aoff + m * 2048 + k * 1024); } while (0)
; #define PG8_LDB(dst, b, h) do { _Pragma("unroll") for (int n = 0; n < 2; ++n) _Pragma("unroll") for (int k = 0; k < 2; ++k) dst[n][k] = *(const PG8_LAS bf16x8*)(lds + PG8_SB(b, h) + boff + n * 2048 + k * 1024); } while (0)
; #define PG8_MMA(ai, bj, At, Bt) do { __builtin_amdgcn_s_setprio(1); _Pragma("unroll") for (int m = 0; m < 4; ++m) _Pragma("unroll") for (int n = 0; n < 2; ++n) _Pragma("unroll") for (int k = 0; k < 2; ++k) \
;         acc[ai][bj][m][n] = __builtin_amdgcn_mfma_f32_16x16x32_bf16(Bt[n][k], At[m][k], acc[ai][bj][m][n], 0, 0, 0); __builtin_amdgcn_s_setprio(0); } while (0)
; #define PG8_WAIT_V(n) asm volatile("s_waitcnt vmcnt(" #n ")" ::: "memory")
; #define PG8_WAIT_L(n) asm volatile("s_waitcnt lgkmcnt(" #n ")" ::: "memory")
; #define PG8_BAR __builtin_amdgcn_s_barrier()
; #define PG8_SCHED __builtin_amdgcn_sched_barrier(0)
; template <class Epi, class Sched, bool ALIGN_EPI = false, bool SP2 = false>
; __device__ __forceinline__ void gemm_phase(PG8_LAS unsigned char* lds, const Gemm g, const Sched& S, const Epi& E) {
;     ...
;             PG8_WAIT_V(8); PG8_WAIT_L(0); PG8_BAR; PG8_MMA(1, 0, At, B0); PG8_MMA(1, 1, At, B1); PG8_BAR; PG8_SCHED;
;             PG8_LDB(B0, 1, 0); PG8_LDB(B1, 1, 1); PG8_SCHED; PG8_LDA(At, 1, 0); PG8_STAGE(PG8_SA(0, 1), a2 + hstepA, voffA);
;             PG8_WAIT_V(8); PG8_WAIT_L(0); PG8_BAR; PG8_MMA(0, 0, At, B0); PG8_MMA(0, 1, At, B1); PG8_BAR; PG8_SCHED;
	v_mfma_f32_16x16x32_bf16 v[94:97], v[142:145], v[174:177], v[94:97]
	v_mfma_f32_16x16x32_bf16 v[90:93], v[150:153], v[174:177], v[90:93]
	v_mfma_f32_16x16x32_bf16 v[86:89], v[142:145], v[182:185], v[86:89]
	v_mfma_f32_16x16x32_bf16 v[82:85], v[150:153], v[182:185], v[82:85]
	v_mfma_f32_16x16x32_bf16 v[74:77], v[142:145], v[206:209], v[74:77]
	v_mfma_f32_16x16x32_bf16 v[66:69], v[150:153], v[206:209], v[66:69]
	v_mfma_f32_16x16x32_bf16 v[58:61], v[142:145], v[232:235], v[58:61]
	v_mfma_f32_16x16x32_bf16 v[50:53], v[150:153], v[232:235], v[50:53]
	v_mfma_f32_16x16x32_bf16 v[94:97], v[146:149], v[178:181], v[94:97]
	v_mfma_f32_16x16x32_bf16 v[90:93], v[154:157], v[178:181], v[90:93]
	v_mfma_f32_16x16x32_bf16 v[86:89], v[146:149], v[202:205], v[86:89]
	v_mfma_f32_16x16x32_bf16 v[82:85], v[154:157], v[202:205], v[82:85]
	v_mfma_f32_16x16x32_bf16 v[74:77], v[146:149], v[210:213], v[74:77]
	v_mfma_f32_16x16x32_bf16 v[66:69], v[154:157], v[210:213], v[66:69]
	v_mfma_f32_16x16x32_bf16 v[58:61], v[146:149], v[236:239], v[58:61]
	v_mfma_f32_16x16x32_bf16 v[50:53], v[154:157], v[236:239], v[50:53]
	s_setprio 0
	s_setprio 1
	v_mfma_f32_16x16x32_bf16 v[30:33], v[158:161], v[174:177], v[30:33]
	v_mfma_f32_16x16x32_bf16 v[26:29], v[166:169], v[174:177], v[26:29]
	v_mfma_f32_16x16x32_bf16 v[22:25], v[158:161], v[182:185], v[22:25]
	v_mfma_f32_16x16x32_bf16 v[18:21], v[166:169], v[182:185], v[18:21]
	v_mfma_f32_16x16x32_bf16 v[14:17], v[158:161], v[206:209], v[14:17]
	v_mfma_f32_16x16x32_bf16 v[10:13], v[166:169], v[206:209], v[10:13]
	v_mfma_f32_16x16x32_bf16 v[6:9], v[158:161], v[232:235], v[6:9]
	v_mfma_f32_16x16x32_bf16 v[2:5], v[166:169], v[232:235], v[2:5]
	v_mfma_f32_16x16x32_bf16 v[30:33], v[162:165], v[178:181], v[30:33]
	v_mfma_f32_16x16x32_bf16 v[26:29], v[170:173], v[178:181], v[26:29]
	v_mfma_f32_16x16x32_bf16 v[22:25], v[162:165], v[202:205], v[22:25]
	v_mfma_f32_16x16x32_bf16 v[18:21], v[170:173], v[202:205], v[18:21]
	v_mfma_f32_16x16x32_bf16 v[14:17], v[162:165], v[210:213], v[14:17]
	v_mfma_f32_16x16x32_bf16 v[10:13], v[170:173], v[210:213], v[10:13]
	v_mfma_f32_16x16x32_bf16 v[6:9], v[162:165], v[236:239], v[6:9]
	v_mfma_f32_16x16x32_bf16 v[2:5], v[170:173], v[236:239], v[2:5]
	s_setprio 0
	s_barrier
	v_add_u32_e32 v141, s66, v138
	ds_read_b128 v[142:145], v141
	ds_read_b128 v[146:149], v141 offset:1024
	ds_read_b128 v[150:153], v141 offset:2048
	ds_read_b128 v[154:157], v141 offset:3072
	v_add_u32_e32 v141, s65, v138
	ds_read_b128 v[158:161], v141
	ds_read_b128 v[162:165], v141 offset:1024
	ds_read_b128 v[166:169], v141 offset:2048
	ds_read_b128 v[170:173], v141 offset:3072
	s_mov_b32 m0, s53
	v_lshl_add_u64 v[244:245], s[34:35], 0, v[136:137]
	ds_read_b128 v[174:177], v140 offset:32768
	ds_read_b128 v[178:181], v140 offset:33792
	ds_read_b128 v[182:185], v140 offset:34816
	ds_read_b128 v[202:205], v140 offset:35840
	ds_read_b128 v[206:209], v140 offset:36864
	ds_read_b128 v[210:213], v140 offset:37888
	ds_read_b128 v[232:235], v140 offset:38912
	ds_read_b128 v[236:239], v140 offset:39936
	global_load_lds_dwordx4 v[244:245], off
	v_lshl_add_u64 v[244:245], s[34:35], 0, v[132:133]
	s_mov_b32 m0, s54
	s_nop 0
	global_load_lds_dwordx4 v[244:245], off
	s_waitcnt vmcnt(8) lgkmcnt(0)
	s_setprio 1
	s_barrier
	v_mfma_f32_16x16x32_bf16 v[126:129], v[142:145], v[174:177], v[126:129]
	v_mfma_f32_16x16x32_bf16 v[122:125], v[150:153], v[174:177], v[122:125]
	v_mfma_f32_16x16x32_bf16 v[118:121], v[142:145], v[182:185], v[118:121]
	v_mfma_f32_16x16x32_bf16 v[114:117], v[150:153], v[182:185], v[114:117]
	v_mfma_f32_16x16x32_bf16 v[110:113], v[142:145], v[206:209], v[110:113]
	v_mfma_f32_16x16x32_bf16 v[106:109], v[150:153], v[206:209], v[106:109]
	v_mfma_f32_16x16x32_bf16 v[102:105], v[142:145], v[232:235], v[102:105]
	v_mfma_f32_16x16x32_bf16 v[98:101], v[150:153], v[232:235], v[98:101]
	v_mfma_f32_16x16x32_bf16 v[126:129], v[146:149], v[178:181], v[126:129]
	v_mfma_f32_16x16x32_bf16 v[122:125], v[154:157], v[178:181], v[122:125]
	v_mfma_f32_16x16x32_bf16 v[118:121], v[146:149], v[202:205], v[118:121]
	v_mfma_f32_16x16x32_bf16 v[114:117], v[154:157], v[202:205], v[114:117]
	v_mfma_f32_16x16x32_bf16 v[110:113], v[146:149], v[210:213], v[110:113]
	v_mfma_f32_16x16x32_bf16 v[106:109], v[154:157], v[210:213], v[106:109]
	v_mfma_f32_16x16x32_bf16 v[102:105], v[146:149], v[236:239], v[102:105]
	v_mfma_f32_16x16x32_bf16 v[98:101], v[154:157], v[236:239], v[98:101]
	s_setprio 0
	s_setprio 1
	v_mfma_f32_16x16x32_bf16 v[78:81], v[158:161], v[174:177], v[78:81]
	v_mfma_f32_16x16x32_bf16 v[70:73], v[166:169], v[174:177], v[70:73]
	v_mfma_f32_16x16x32_bf16 v[62:65], v[158:161], v[182:185], v[62:65]
	v_mfma_f32_16x16x32_bf16 v[54:57], v[166:169], v[182:185], v[54:57]
	v_mfma_f32_16x16x32_bf16 v[46:49], v[158:161], v[206:209], v[46:49]
	v_mfma_f32_16x16x32_bf16 v[42:45], v[166:169], v[206:209], v[42:45]
	v_mfma_f32_16x16x32_bf16 v[38:41], v[158:161], v[232:235], v[38:41]
	v_mfma_f32_16x16x32_bf16 v[34:37], v[166:169], v[232:235], v[34:37]
	v_mfma_f32_16x16x32_bf16 v[78:81], v[162:165], v[178:181], v[78:81]
	v_mfma_f32_16x16x32_bf16 v[70:73], v[170:173], v[178:181], v[70:73]
	v_mfma_f32_16x16x32_bf16 v[62:65], v[162:165], v[202:205], v[62:65]
	v_mfma_f32_16x16x32_bf16 v[54:57], v[170:173], v[202:205], v[54:57]
	v_mfma_f32_16x16x32_bf16 v[46:49], v[162:165], v[210:213], v[46:49]
	v_mfma_f32_16x16x32_bf16 v[42:45], v[170:173], v[210:213], v[42:45]
	v_mfma_f32_16x16x32_bf16 v[38:41], v[162:165], v[236:239], v[38:41]
	v_mfma_f32_16x16x32_bf16 v[34:37], v[170:173], v[236:239], v[34:37]
	s_setprio 0
	s_barrier
; #define PG8_STAGE(bufoff, gbase, voff) do { _Pragma("unroll") for (int _i = 0; _i < 2; ++_i) \
;         __builtin_amdgcn_global_load_lds((const unsigned*)((const char*)(gbase) + (voff)[_i]), (PG8_LAS unsigned*)(lds + (bufoff) + ldsw + _i * 8192), 16, 0, 0); } while (0)
; #define PG8_LDA(dst, b, h) do { _Pragma("unroll") for (int m = 0; m < 4; ++m) _Pragma("unroll") for (int k = 0; k < 2; ++k) dst[m][k] = *(const PG8_LAS bf16x8*)(lds + PG8_SA(b, h) + aoff + m * 2048 + k * 1024); } while (0)
; #define PG8_MMA(ai, bj, At, Bt) do { __builtin_amdgcn_s_setprio(1); _Pragma("unroll") for (int m = 0; m < 4; ++m) _Pragma("unroll") for (int n = 0; n < 2; ++n) _Pragma("unroll") for (int k = 0; k < 2; ++k) \
;         acc[ai][bj][m][n] = __builtin_amdgcn_mfma_f32_16x16x32_bf16(Bt[n][k], At[m][k], acc[ai][bj][m][n], 0, 0, 0); __builtin_amdgcn_s_setprio(0); } while (0)
; #define PG8_WAIT_V(n) asm volatile("s_waitcnt vmcnt(" #n ")" ::: "memory")
; #define PG8_WAIT_L(n) asm volatile("s_waitcnt lgkmcnt(" #n ")" ::: "memory")
; #define PG8_BAR __builtin_amdgcn_s_barrier()
; #define PG8_SCHED __builtin_amdgcn_sched_barrier(0)
; template <class Epi, class Sched, bool ALIGN_EPI = false, bool SP2 = false>
; __device__ __forceinline__ void gemm_phase(PG8_LAS unsigned char* lds, const Gemm g, const Sched& S, const Epi& E) {
;     ...
;             PG8_LDA(At, 1, 1); PG8_STAGE(PG8_SB(1, 0), b3, voffB); PG8_STAGE(PG8_SB(1, 1), b3 + hstepB, voffB); PG8_STAGE(PG8_SA(1, 0), a3, voffA);
;             PG8_WAIT_V(8); PG8_WAIT_L(0); PG8_BAR; PG8_MMA(1, 0, At, B0); PG8_MMA(1, 1, At, B1); PG8_BAR; PG8_SCHED;
;     ...
;         }
;         if constexpr (ALIGN_EPI) { if (wr == 0) PG8_BAR; }
	s_mov_b32 m0, s64
	v_lshl_add_u64 v[186:187], v[186:187], 0, s[96:97]
	ds_read_b128 v[174:177], v140 offset:49152
	ds_read_b128 v[178:181], v140 offset:50176
	ds_read_b128 v[182:185], v140 offset:51200
	ds_read_b128 v[202:205], v140 offset:52224
	ds_read_b128 v[206:209], v140 offset:53248
	ds_read_b128 v[210:213], v140 offset:54272
	ds_read_b128 v[232:235], v140 offset:55296
	ds_read_b128 v[236:239], v140 offset:56320
	global_load_lds_dwordx4 v[186:187], off
	v_lshl_add_u64 v[186:187], v[214:215], 0, s[96:97]
	s_mov_b32 m0, s63
	s_nop 0
	global_load_lds_dwordx4 v[186:187], off
	v_lshl_add_u64 v[186:187], s[30:31], 0, v[134:135]
	s_mov_b32 m0, s73
	s_nop 0
	global_load_lds_dwordx4 v[186:187], off
	v_lshl_add_u64 v[186:187], s[30:31], 0, v[130:131]
	s_mov_b32 m0, s72
	s_nop 0
	global_load_lds_dwordx4 v[186:187], off
	v_lshl_add_u64 v[186:187], v[240:241], 0, s[96:97]
	s_mov_b32 m0, s55
	s_nop 0
	global_load_lds_dwordx4 v[186:187], off
	v_lshl_add_u64 v[186:187], v[242:243], 0, s[96:97]
	s_mov_b32 m0, s56
	s_nop 0
	global_load_lds_dwordx4 v[186:187], off
	s_waitcnt vmcnt(8) lgkmcnt(0)
	s_setprio 1
	s_barrier
	v_mfma_f32_16x16x32_bf16 v[94:97], v[142:145], v[174:177], v[94:97]
	v_mfma_f32_16x16x32_bf16 v[90:93], v[150:153], v[174:177], v[90:93]
	v_mfma_f32_16x16x32_bf16 v[86:89], v[142:145], v[182:185], v[86:89]
	v_mfma_f32_16x16x32_bf16 v[82:85], v[150:153], v[182:185], v[82:85]
	v_mfma_f32_16x16x32_bf16 v[74:77], v[142:145], v[206:209], v[74:77]
	v_mfma_f32_16x16x32_bf16 v[66:69], v[150:153], v[206:209], v[66:69]
	v_mfma_f32_16x16x32_bf16 v[58:61], v[142:145], v[232:235], v[58:61]
	v_mfma_f32_16x16x32_bf16 v[50:53], v[150:153], v[232:235], v[50:53]
	v_mfma_f32_16x16x32_bf16 v[94:97], v[146:149], v[178:181], v[94:97]
	v_mfma_f32_16x16x32_bf16 v[90:93], v[154:157], v[178:181], v[90:93]
	v_mfma_f32_16x16x32_bf16 v[86:89], v[146:149], v[202:205], v[86:89]
	v_mfma_f32_16x16x32_bf16 v[82:85], v[154:157], v[202:205], v[82:85]
	v_mfma_f32_16x16x32_bf16 v[74:77], v[146:149], v[210:213], v[74:77]
	v_mfma_f32_16x16x32_bf16 v[66:69], v[154:157], v[210:213], v[66:69]
	v_mfma_f32_16x16x32_bf16 v[58:61], v[146:149], v[236:239], v[58:61]
	v_mfma_f32_16x16x32_bf16 v[50:53], v[154:157], v[236:239], v[50:53]
	s_setprio 0
	s_setprio 1
	v_mfma_f32_16x16x32_bf16 v[30:33], v[158:161], v[174:177], v[30:33]
	v_mfma_f32_16x16x32_bf16 v[26:29], v[166:169], v[174:177], v[26:29]
	v_mfma_f32_16x16x32_bf16 v[22:25], v[158:161], v[182:185], v[22:25]
	v_mfma_f32_16x16x32_bf16 v[18:21], v[166:169], v[182:185], v[18:21]
	v_mfma_f32_16x16x32_bf16 v[14:17], v[158:161], v[206:209], v[14:17]
	v_mfma_f32_16x16x32_bf16 v[10:13], v[166:169], v[206:209], v[10:13]
	v_mfma_f32_16x16x32_bf16 v[6:9], v[158:161], v[232:235], v[6:9]
	v_mfma_f32_16x16x32_bf16 v[2:5], v[166:169], v[232:235], v[2:5]
	v_mfma_f32_16x16x32_bf16 v[30:33], v[162:165], v[178:181], v[30:33]
	v_mfma_f32_16x16x32_bf16 v[26:29], v[170:173], v[178:181], v[26:29]
	v_mfma_f32_16x16x32_bf16 v[22:25], v[162:165], v[202:205], v[22:25]
	v_mfma_f32_16x16x32_bf16 v[18:21], v[170:173], v[202:205], v[18:21]
	v_mfma_f32_16x16x32_bf16 v[14:17], v[162:165], v[210:213], v[14:17]
	v_mfma_f32_16x16x32_bf16 v[10:13], v[170:173], v[210:213], v[10:13]
	v_mfma_f32_16x16x32_bf16 v[6:9], v[162:165], v[236:239], v[6:9]
	v_mfma_f32_16x16x32_bf16 v[2:5], v[170:173], v[236:239], v[2:5]
	s_setprio 0
	s_barrier
	s_movk_i32 s34, 0x100
	s_andn2_b64 vcc, exec, s[28:29]
	s_mov_b64 s[30:31], -1
	s_mov_b64 s[28:29], 0
	s_cbranch_vccz .LBB0_1176
	s_and_b64 vcc, exec, s[16:17]
	s_cbranch_vccz .LBB0_1179
	s_barrier

; #define PG8_STAGE(bufoff, gbase, voff) do { _Pragma("unroll") for (int _i = 0; _i < 2; ++_i) \
;         __builtin_amdgcn_global_load_lds((const unsigned*)((const char*)(gbase) + (voff)[_i]), (PG8_LAS unsigned*)(lds + (bufoff) + ldsw + _i * 8192), 16, 0, 0); } while (0)
; #define PG8_LDA(dst, b, h) do { _Pragma("unroll") for (int m = 0; m < 4; ++m) _Pragma("unroll") for (int k = 0; k < 2; ++k) dst[m][k] = *(const PG8_LAS bf16x8*)(lds + PG8_SA(b, h) + aoff + m * 2048 + k * 1024); } while (0)
; #define PG8_LDB(dst, b, h) do { _Pragma("unroll") for (int n = 0; n < 2; ++n) _Pragma("unroll") for (int k = 0; k < 2; ++k) dst[n][k] = *(const PG8_LAS bf16x8*)(lds + PG8_SB(b, h) + boff + n * 2048 + k * 1024); } while (0)
; #define PG8_MMA(ai, bj, At, Bt) do { __builtin_amdgcn_s_setprio(1); _Pragma("unroll") for (int m = 0; m < 4; ++m) _Pragma("unroll") for (int n = 0; n < 2; ++n) _Pragma("unroll") for (int k = 0; k < 2; ++k) \
;         acc[ai][bj][m][n] = __builtin_amdgcn_mfma_f32_16x16x32_bf16(Bt[n][k], At[m][k], acc[ai][bj][m][n], 0, 0, 0); __builtin_amdgcn_s_setprio(0); } while (0)
; #define PG8_WAIT_V(n) asm volatile("s_waitcnt vmcnt(" #n ")" ::: "memory")
; #define PG8_WAIT_L(n) asm volatile("s_waitcnt lgkmcnt(" #n ")" ::: "memory")
; template <class Epi, class Sched, bool ALIGN_EPI = false, bool SP2 = false>
; __device__ __forceinline__ void gemm_phase(PG8_LAS unsigned char* lds, const Gemm g, const Sched& S, const Epi& E) {
;     ...
;             const bool last = (t == nt - 2);
;             const char* a1 = cA + (size_t)(t + 1) * kstep;
;             const char* a2 = last ? nA : cA + (size_t)(t + 2) * kstep; const char* b2 = last ? nB : cB + (size_t)(t + 2) * kstep;
;             const char* a3 = a2 + kstep; const char* b3 = b2 + kstep;
;             if (last && has_next) S.a_ready(nxt);
;             if constexpr (SP2) {
;             PG8_LDB(B0, 0, 0); PG8_LDB(B1, 0, 1); PG8_SCHED; PG8_LDA(At, 0, 0); PG8_STAGE(PG8_SA(1, 1), a1 + hstepA, voffA);
;             PG8_WAIT_V(8); PG8_WAIT_L(0); PG8_BAR; PG8_MMA(0, 0, At, B0); PG8_MMA(0, 1, At, B1); PG8_BAR; PG8_SCHED;
;             PG8_LDA(At, 0, 1); PG8_STAGE(PG8_SB(0, 0), b2, voffB); PG8_STAGE(PG8_SB(0, 1), b2 + hstepB, voffB); PG8_STAGE(PG8_SA(0, 0), a2, voffA);
;             PG8_WAIT_V(8); PG8_WAIT_L(0); PG8_BAR; PG8_MMA(1, 0, At, B0); PG8_MMA(1, 1, At, B1); PG8_BAR; PG8_SCHED;
.LBB0_1190:
	s_add_u32 s24, s22, 0xfffc0080
	s_addc_u32 s25, s23, -1
	s_add_i32 s51, 0, 0x10000
	s_cmp_eq_u32 s50, 12
	s_cselect_b32 s27, s44, s25
	s_cselect_b32 s26, s45, s24
	s_cselect_b32 s25, s46, s49
	s_cselect_b32 s24, s47, s48
	s_add_i32 s54, 0, 0x14000
	v_add_u32_e32 v142, s51, v168
	v_add_u32_e32 v166, s54, v168
	ds_read_b128 v[130:133], v142
	ds_read_b128 v[134:137], v142 offset:1024
	ds_read_b128 v[138:141], v142 offset:2048
	ds_read_b128 v[142:145], v142 offset:3072
	ds_read_b128 v[158:161], v166
	ds_read_b128 v[162:165], v166 offset:1024
	ds_read_b128 v[172:175], v166 offset:2048
	ds_read_b128 v[176:179], v166 offset:3072
	s_add_i32 m0, s7, 0xc000
	ds_read_b128 v[180:183], v171
	ds_read_b128 v[184:187], v171 offset:1024
	ds_read_b128 v[202:205], v171 offset:2048
	ds_read_b128 v[206:209], v171 offset:3072
	ds_read_b128 v[210:213], v171 offset:4096
	ds_read_b128 v[232:235], v171 offset:5120
	ds_read_b128 v[236:239], v171 offset:6144
	ds_read_b128 v[240:243], v171 offset:7168
	global_load_lds_dwordx4 v154, s[22:23]
	s_add_i32 m0, s7, 0xe000
	s_nop 0
	global_load_lds_dwordx4 v156, s[22:23]
	s_waitcnt vmcnt(8) lgkmcnt(0)
	s_setprio 1
	s_barrier
	v_mfma_f32_16x16x32_bf16 v[126:129], v[130:133], v[180:183], v[126:129]
	v_mfma_f32_16x16x32_bf16 v[118:121], v[138:141], v[180:183], v[118:121]
	v_mfma_f32_16x16x32_bf16 v[110:113], v[130:133], v[202:205], v[110:113]
	v_mfma_f32_16x16x32_bf16 v[102:105], v[138:141], v[202:205], v[102:105]
	v_mfma_f32_16x16x32_bf16 v[94:97], v[130:133], v[210:213], v[94:97]
	v_mfma_f32_16x16x32_bf16 v[86:89], v[138:141], v[210:213], v[86:89]
	v_mfma_f32_16x16x32_bf16 v[78:81], v[130:133], v[236:239], v[78:81]
	v_mfma_f32_16x16x32_bf16 v[70:73], v[138:141], v[236:239], v[70:73]
	v_mfma_f32_16x16x32_bf16 v[126:129], v[134:137], v[184:187], v[126:129]
	v_mfma_f32_16x16x32_bf16 v[118:121], v[142:145], v[184:187], v[118:121]
	v_mfma_f32_16x16x32_bf16 v[110:113], v[134:137], v[206:209], v[110:113]
	v_mfma_f32_16x16x32_bf16 v[102:105], v[142:145], v[206:209], v[102:105]
	v_mfma_f32_16x16x32_bf16 v[94:97], v[134:137], v[232:235], v[94:97]
	v_mfma_f32_16x16x32_bf16 v[86:89], v[142:145], v[232:235], v[86:89]
	v_mfma_f32_16x16x32_bf16 v[78:81], v[134:137], v[240:243], v[78:81]
	v_mfma_f32_16x16x32_bf16 v[70:73], v[142:145], v[240:243], v[70:73]
	s_setprio 0
	s_setprio 1
	v_mfma_f32_16x16x32_bf16 v[122:125], v[158:161], v[180:183], v[122:125]
	v_mfma_f32_16x16x32_bf16 v[114:117], v[172:175], v[180:183], v[114:117]
	v_mfma_f32_16x16x32_bf16 v[106:109], v[158:161], v[202:205], v[106:109]
	v_mfma_f32_16x16x32_bf16 v[98:101], v[172:175], v[202:205], v[98:101]
	v_mfma_f32_16x16x32_bf16 v[90:93], v[158:161], v[210:213], v[90:93]
	v_mfma_f32_16x16x32_bf16 v[82:85], v[172:175], v[210:213], v[82:85]
	v_mfma_f32_16x16x32_bf16 v[74:77], v[158:161], v[236:239], v[74:77]
	v_mfma_f32_16x16x32_bf16 v[66:69], v[172:175], v[236:239], v[66:69]
	v_mfma_f32_16x16x32_bf16 v[122:125], v[162:165], v[184:187], v[122:125]
	v_mfma_f32_16x16x32_bf16 v[114:117], v[176:179], v[184:187], v[114:117]
	v_mfma_f32_16x16x32_bf16 v[106:109], v[162:165], v[206:209], v[106:109]
	v_mfma_f32_16x16x32_bf16 v[98:101], v[176:179], v[206:209], v[98:101]
	v_mfma_f32_16x16x32_bf16 v[90:93], v[162:165], v[232:235], v[90:93]
	v_mfma_f32_16x16x32_bf16 v[82:85], v[176:179], v[232:235], v[82:85]
	v_mfma_f32_16x16x32_bf16 v[74:77], v[162:165], v[240:243], v[74:77]
	v_mfma_f32_16x16x32_bf16 v[66:69], v[176:179], v[240:243], v[66:69]
	s_setprio 0
	s_barrier
	s_add_i32 s51, s51, s30
	s_mov_b32 m0, s51
	ds_read_b128 v[180:183], v171 offset:16384
	ds_read_b128 v[184:187], v171 offset:17408
	ds_read_b128 v[202:205], v171 offset:18432
	ds_read_b128 v[206:209], v171 offset:19456
	ds_read_b128 v[210:213], v171 offset:20480
	ds_read_b128 v[232:235], v171 offset:21504
	ds_read_b128 v[236:239], v171 offset:22528
	ds_read_b128 v[240:243], v171 offset:23552
	s_add_u32 s60, s24, 0x80
	s_addc_u32 s61, s25, 0
	s_add_u32 s62, s26, 0x80
	s_addc_u32 s63, s27, 0
	global_load_lds_dwordx4 v150, s[24:25]
	s_add_i32 m0, s51, 0x2000
	s_add_u32 s52, s24, 0x40000
	s_addc_u32 s53, s25, 0
	s_add_i32 s51, s54, s30
	global_load_lds_dwordx4 v146, s[24:25]
	s_mov_b32 m0, s51
	s_nop 0
	global_load_lds_dwordx4 v150, s[52:53]
	s_add_i32 m0, s51, 0x2000
	s_nop 0
	global_load_lds_dwordx4 v146, s[52:53]
	s_mov_b32 m0, s7
	s_nop 0
	global_load_lds_dwordx4 v152, s[26:27]
	s_mov_b32 m0, s36
	s_nop 0
	global_load_lds_dwordx4 v148, s[26:27]
	s_waitcnt vmcnt(8) lgkmcnt(0)
	s_setprio 1
	s_barrier
	v_mfma_f32_16x16x32_bf16 v[62:65], v[130:133], v[180:183], v[62:65]
	v_mfma_f32_16x16x32_bf16 v[54:57], v[138:141], v[180:183], v[54:57]
	v_mfma_f32_16x16x32_bf16 v[46:49], v[130:133], v[202:205], v[46:49]
	v_mfma_f32_16x16x32_bf16 v[38:41], v[138:141], v[202:205], v[38:41]
	v_mfma_f32_16x16x32_bf16 v[30:33], v[130:133], v[210:213], v[30:33]
	v_mfma_f32_16x16x32_bf16 v[22:25], v[138:141], v[210:213], v[22:25]
	v_mfma_f32_16x16x32_bf16 v[14:17], v[130:133], v[236:239], v[14:17]
	v_mfma_f32_16x16x32_bf16 v[6:9], v[138:141], v[236:239], v[6:9]
	v_mfma_f32_16x16x32_bf16 v[62:65], v[134:137], v[184:187], v[62:65]
	v_mfma_f32_16x16x32_bf16 v[54:57], v[142:145], v[184:187], v[54:57]
	v_mfma_f32_16x16x32_bf16 v[46:49], v[134:137], v[206:209], v[46:49]
	v_mfma_f32_16x16x32_bf16 v[38:41], v[142:145], v[206:209], v[38:41]
	v_mfma_f32_16x16x32_bf16 v[30:33], v[134:137], v[232:235], v[30:33]
	v_mfma_f32_16x16x32_bf16 v[22:25], v[142:145], v[232:235], v[22:25]
	v_mfma_f32_16x16x32_bf16 v[14:17], v[134:137], v[240:243], v[14:17]
	v_mfma_f32_16x16x32_bf16 v[6:9], v[142:145], v[240:243], v[6:9]
	s_setprio 0
	s_setprio 1
	v_mfma_f32_16x16x32_bf16 v[58:61], v[158:161], v[180:183], v[58:61]
	v_mfma_f32_16x16x32_bf16 v[50:53], v[172:175], v[180:183], v[50:53]
	v_mfma_f32_16x16x32_bf16 v[42:45], v[158:161], v[202:205], v[42:45]
	v_mfma_f32_16x16x32_bf16 v[34:37], v[172:175], v[202:205], v[34:37]
	v_mfma_f32_16x16x32_bf16 v[26:29], v[158:161], v[210:213], v[26:29]
	v_mfma_f32_16x16x32_bf16 v[18:21], v[172:175], v[210:213], v[18:21]
	v_mfma_f32_16x16x32_bf16 v[10:13], v[158:161], v[236:239], v[10:13]
	v_mfma_f32_16x16x32_bf16 v[2:5], v[172:175], v[236:239], v[2:5]
	v_mfma_f32_16x16x32_bf16 v[58:61], v[162:165], v[184:187], v[58:61]
	v_mfma_f32_16x16x32_bf16 v[50:53], v[176:179], v[184:187], v[50:53]
	v_mfma_f32_16x16x32_bf16 v[42:45], v[162:165], v[206:209], v[42:45]
	v_mfma_f32_16x16x32_bf16 v[34:37], v[176:179], v[206:209], v[34:37]
	v_mfma_f32_16x16x32_bf16 v[26:29], v[162:165], v[232:235], v[26:29]
	v_mfma_f32_16x16x32_bf16 v[18:21], v[176:179], v[232:235], v[18:21]
	v_mfma_f32_16x16x32_bf16 v[10:13], v[162:165], v[240:243], v[10:13]
	v_mfma_f32_16x16x32_bf16 v[2:5], v[176:179], v[240:243], v[2:5]
	s_setprio 0
	s_barrier
; #define PG8_STAGE(bufoff, gbase, voff) do { _Pragma("unroll") for (int _i = 0; _i < 2; ++_i) \
;         __builtin_amdgcn_global_load_lds((const unsigned*)((const char*)(gbase) + (voff)[_i]), (PG8_LAS unsigned*)(lds + (bufoff) + ldsw + _i * 8192), 16, 0, 0); } while (0)
; #define PG8_LDA(dst, b, h) do { _Pragma("unroll") for (int m = 0; m < 4; ++m) _Pragma("unroll") for (int k = 0; k < 2; ++k) dst[m][k] = *(const PG8_LAS bf16x8*)(lds + PG8_SA(b, h) + aoff + m * 2048 + k * 1024); } while (0)
; #define PG8_LDB(dst, b, h) do { _Pragma("unroll") for (int n = 0; n < 2; ++n) _Pragma("unroll") for (int k = 0; k < 2; ++k) dst[n][k] = *(const PG8_LAS bf16x8*)(lds + PG8_SB(b, h) + boff + n * 2048 + k * 1024); } while (0)
; #define PG8_MMA(ai, bj, At, Bt) do { __builtin_amdgcn_s_setprio(1); _Pragma("unroll") for (int m = 0; m < 4; ++m) _Pragma("unroll") for (int n = 0; n < 2; ++n) _Pragma("unroll") for (int k = 0; k < 2; ++k) \
;         acc[ai][bj][m][n] = __builtin_amdgcn_mfma_f32_16x16x32_bf16(Bt[n][k], At[m][k], acc[ai][bj][m][n], 0, 0, 0); __builtin_amdgcn_s_setprio(0); } while (0)
; #define PG8_WAIT_V(n) asm volatile("s_waitcnt vmcnt(" #n ")" ::: "memory")
; #define PG8_WAIT_L(n) asm volatile("s_waitcnt lgkmcnt(" #n ")" ::: "memory")
; #define PG8_BAR __builtin_amdgcn_s_barrier()
; #define PG8_SCHED __builtin_amdgcn_sched_barrier(0)
; template <class Epi, class Sched, bool ALIGN_EPI = false, bool SP2 = false>
; __device__ __forceinline__ void gemm_phase(PG8_LAS unsigned char* lds, const Gemm g, const Sched& S, const Epi& E) {
;     ...
;         for (int t = 0; t < nt; t += 2) {
;     ...
;             PG8_LDB(B0, 1, 0); PG8_LDB(B1, 1, 1); PG8_SCHED; PG8_LDA(At, 1, 0); PG8_STAGE(PG8_SA(0, 1), a2 + hstepA, voffA);
;             PG8_WAIT_V(8); PG8_WAIT_L(0); PG8_BAR; PG8_MMA(0, 0, At, B0); PG8_MMA(0, 1, At, B1); PG8_BAR; PG8_SCHED;
;             PG8_LDA(At, 1, 1); PG8_STAGE(PG8_SB(1, 0), b3, voffB); PG8_STAGE(PG8_SB(1, 1), b3 + hstepB, voffB); PG8_STAGE(PG8_SA(1, 0), a3, voffA);
;             PG8_WAIT_V(8); PG8_WAIT_L(0); PG8_BAR; PG8_MMA(1, 0, At, B0); PG8_MMA(1, 1, At, B1); PG8_BAR; PG8_SCHED;
;     ...
;         if constexpr (ALIGN_EPI) { if (wr == 0) PG8_BAR; }
	s_add_i32 s51, 0, 0x18000
	s_add_i32 s52, 0, 0x1c000
	v_add_u32_e32 v142, s51, v168
	v_add_u32_e32 v176, s52, v168
	ds_read_b128 v[130:133], v142
	ds_read_b128 v[134:137], v142 offset:1024
	ds_read_b128 v[138:141], v142 offset:2048
	ds_read_b128 v[142:145], v142 offset:3072
	ds_read_b128 v[158:161], v176
	ds_read_b128 v[162:165], v176 offset:1024
	ds_read_b128 v[172:175], v176 offset:2048
	ds_read_b128 v[176:179], v176 offset:3072
	s_add_u32 s26, s26, 0x40000
	s_addc_u32 s27, s27, 0
	s_mov_b32 m0, s37
	ds_read_b128 v[180:183], v171 offset:32768
	ds_read_b128 v[184:187], v171 offset:33792
	ds_read_b128 v[202:205], v171 offset:34816
	ds_read_b128 v[206:209], v171 offset:35840
	ds_read_b128 v[210:213], v171 offset:36864
	ds_read_b128 v[232:235], v171 offset:37888
	ds_read_b128 v[236:239], v171 offset:38912
	ds_read_b128 v[240:243], v171 offset:39936
	global_load_lds_dwordx4 v152, s[26:27]
	s_mov_b32 m0, s38
	s_nop 0
	global_load_lds_dwordx4 v148, s[26:27]
	s_waitcnt vmcnt(8) lgkmcnt(0)
	s_setprio 1
	s_barrier
	v_mfma_f32_16x16x32_bf16 v[126:129], v[130:133], v[180:183], v[126:129]
	v_mfma_f32_16x16x32_bf16 v[118:121], v[138:141], v[180:183], v[118:121]
	v_mfma_f32_16x16x32_bf16 v[110:113], v[130:133], v[202:205], v[110:113]
	v_mfma_f32_16x16x32_bf16 v[102:105], v[138:141], v[202:205], v[102:105]
	v_mfma_f32_16x16x32_bf16 v[94:97], v[130:133], v[210:213], v[94:97]
	v_mfma_f32_16x16x32_bf16 v[86:89], v[138:141], v[210:213], v[86:89]
	v_mfma_f32_16x16x32_bf16 v[78:81], v[130:133], v[236:239], v[78:81]
	v_mfma_f32_16x16x32_bf16 v[70:73], v[138:141], v[236:239], v[70:73]
	v_mfma_f32_16x16x32_bf16 v[126:129], v[134:137], v[184:187], v[126:129]
	v_mfma_f32_16x16x32_bf16 v[118:121], v[142:145], v[184:187], v[118:121]
	v_mfma_f32_16x16x32_bf16 v[110:113], v[134:137], v[206:209], v[110:113]
	v_mfma_f32_16x16x32_bf16 v[102:105], v[142:145], v[206:209], v[102:105]
	v_mfma_f32_16x16x32_bf16 v[94:97], v[134:137], v[232:235], v[94:97]
	v_mfma_f32_16x16x32_bf16 v[86:89], v[142:145], v[232:235], v[86:89]
	v_mfma_f32_16x16x32_bf16 v[78:81], v[134:137], v[240:243], v[78:81]
	v_mfma_f32_16x16x32_bf16 v[70:73], v[142:145], v[240:243], v[70:73]
	s_setprio 0
	s_setprio 1
	v_mfma_f32_16x16x32_bf16 v[122:125], v[158:161], v[180:183], v[122:125]
	v_mfma_f32_16x16x32_bf16 v[114:117], v[172:175], v[180:183], v[114:117]
	v_mfma_f32_16x16x32_bf16 v[106:109], v[158:161], v[202:205], v[106:109]
	v_mfma_f32_16x16x32_bf16 v[98:101], v[172:175], v[202:205], v[98:101]
	v_mfma_f32_16x16x32_bf16 v[90:93], v[158:161], v[210:213], v[90:93]
	v_mfma_f32_16x16x32_bf16 v[82:85], v[172:175], v[210:213], v[82:85]
	v_mfma_f32_16x16x32_bf16 v[74:77], v[158:161], v[236:239], v[74:77]
	v_mfma_f32_16x16x32_bf16 v[66:69], v[172:175], v[236:239], v[66:69]
	v_mfma_f32_16x16x32_bf16 v[122:125], v[162:165], v[184:187], v[122:125]
	v_mfma_f32_16x16x32_bf16 v[114:117], v[176:179], v[184:187], v[114:117]
	v_mfma_f32_16x16x32_bf16 v[106:109], v[162:165], v[206:209], v[106:109]
	v_mfma_f32_16x16x32_bf16 v[98:101], v[176:179], v[206:209], v[98:101]
	v_mfma_f32_16x16x32_bf16 v[90:93], v[162:165], v[232:235], v[90:93]
	v_mfma_f32_16x16x32_bf16 v[82:85], v[176:179], v[232:235], v[82:85]
	v_mfma_f32_16x16x32_bf16 v[74:77], v[162:165], v[240:243], v[74:77]
	v_mfma_f32_16x16x32_bf16 v[66:69], v[176:179], v[240:243], v[66:69]
	s_setprio 0
	s_barrier
	s_add_i32 s26, s51, s30
	s_mov_b32 m0, s26
	ds_read_b128 v[180:183], v171 offset:49152
	ds_read_b128 v[184:187], v171 offset:50176
	ds_read_b128 v[202:205], v171 offset:51200
	ds_read_b128 v[206:209], v171 offset:52224
	ds_read_b128 v[210:213], v171 offset:53248
	ds_read_b128 v[232:235], v171 offset:54272
	ds_read_b128 v[236:239], v171 offset:55296
	ds_read_b128 v[240:243], v171 offset:56320
	global_load_lds_dwordx4 v150, s[60:61]
	s_add_i32 m0, s26, 0x2000
	s_add_u32 s24, s24, 0x40080
	s_addc_u32 s25, s25, 0
	s_add_i32 s26, s52, s30
	global_load_lds_dwordx4 v146, s[60:61]
	s_mov_b32 m0, s26
	s_nop 0
	global_load_lds_dwordx4 v150, s[24:25]
	s_add_i32 m0, s26, 0x2000
	s_nop 0
	global_load_lds_dwordx4 v146, s[24:25]
	s_mov_b32 m0, s39
	s_nop 0
	global_load_lds_dwordx4 v152, s[62:63]
	s_mov_b32 m0, s40
	s_nop 0
	global_load_lds_dwordx4 v148, s[62:63]
	s_waitcnt vmcnt(8) lgkmcnt(0)
	s_setprio 1
	s_barrier
	v_mfma_f32_16x16x32_bf16 v[62:65], v[130:133], v[180:183], v[62:65]
	v_mfma_f32_16x16x32_bf16 v[54:57], v[138:141], v[180:183], v[54:57]
	v_mfma_f32_16x16x32_bf16 v[46:49], v[130:133], v[202:205], v[46:49]
	v_mfma_f32_16x16x32_bf16 v[38:41], v[138:141], v[202:205], v[38:41]
	v_mfma_f32_16x16x32_bf16 v[30:33], v[130:133], v[210:213], v[30:33]
	v_mfma_f32_16x16x32_bf16 v[22:25], v[138:141], v[210:213], v[22:25]
	v_mfma_f32_16x16x32_bf16 v[14:17], v[130:133], v[236:239], v[14:17]
	v_mfma_f32_16x16x32_bf16 v[6:9], v[138:141], v[236:239], v[6:9]
	v_mfma_f32_16x16x32_bf16 v[62:65], v[134:137], v[184:187], v[62:65]
	v_mfma_f32_16x16x32_bf16 v[54:57], v[142:145], v[184:187], v[54:57]
	v_mfma_f32_16x16x32_bf16 v[46:49], v[134:137], v[206:209], v[46:49]
	v_mfma_f32_16x16x32_bf16 v[38:41], v[142:145], v[206:209], v[38:41]
	v_mfma_f32_16x16x32_bf16 v[30:33], v[134:137], v[232:235], v[30:33]
	v_mfma_f32_16x16x32_bf16 v[22:25], v[142:145], v[232:235], v[22:25]
	v_mfma_f32_16x16x32_bf16 v[14:17], v[134:137], v[240:243], v[14:17]
	v_mfma_f32_16x16x32_bf16 v[6:9], v[142:145], v[240:243], v[6:9]
	s_setprio 0
	s_setprio 1
	v_mfma_f32_16x16x32_bf16 v[58:61], v[158:161], v[180:183], v[58:61]
	v_mfma_f32_16x16x32_bf16 v[50:53], v[172:175], v[180:183], v[50:53]
	v_mfma_f32_16x16x32_bf16 v[42:45], v[158:161], v[202:205], v[42:45]
	v_mfma_f32_16x16x32_bf16 v[34:37], v[172:175], v[202:205], v[34:37]
	v_mfma_f32_16x16x32_bf16 v[26:29], v[158:161], v[210:213], v[26:29]
	v_mfma_f32_16x16x32_bf16 v[18:21], v[172:175], v[210:213], v[18:21]
	v_mfma_f32_16x16x32_bf16 v[10:13], v[158:161], v[236:239], v[10:13]
	v_mfma_f32_16x16x32_bf16 v[2:5], v[172:175], v[236:239], v[2:5]
	v_mfma_f32_16x16x32_bf16 v[58:61], v[162:165], v[184:187], v[58:61]
	v_mfma_f32_16x16x32_bf16 v[50:53], v[176:179], v[184:187], v[50:53]
	v_mfma_f32_16x16x32_bf16 v[42:45], v[162:165], v[206:209], v[42:45]
	v_mfma_f32_16x16x32_bf16 v[34:37], v[176:179], v[206:209], v[34:37]
	v_mfma_f32_16x16x32_bf16 v[26:29], v[162:165], v[232:235], v[26:29]
	v_mfma_f32_16x16x32_bf16 v[18:21], v[176:179], v[232:235], v[18:21]
	v_mfma_f32_16x16x32_bf16 v[10:13], v[162:165], v[240:243], v[10:13]
	v_mfma_f32_16x16x32_bf16 v[2:5], v[176:179], v[240:243], v[2:5]
	s_setprio 0
	s_barrier
	s_add_i32 s50, s50, 2
	s_add_u32 s22, s22, 0x100
	s_addc_u32 s23, s23, 0
	s_add_u32 s48, s48, 0x100
	s_addc_u32 s49, s49, 0
	s_cmp_gt_u32 s50, 13
	s_cbranch_scc0 .LBB0_1190
	s_and_b64 vcc, exec, s[18:19]
	s_cbranch_vccz .LBB0_1193
	s_barrier

; #define PG8_STAGE(bufoff, gbase, voff) do { _Pragma("unroll") for (int _i = 0; _i < 2; ++_i) \
;         __builtin_amdgcn_global_load_lds((const unsigned*)((const char*)(gbase) + (voff)[_i]), (PG8_LAS unsigned*)(lds + (bufoff) + ldsw + _i * 8192), 16, 0, 0); } while (0)
; #define PG8_LDA(dst, b, h) do { _Pragma("unroll") for (int m = 0; m < 4; ++m) _Pragma("unroll") for (int k = 0; k < 2; ++k) dst[m][k] = *(const PG8_LAS bf16x8*)(lds + PG8_SA(b, h) + aoff + m * 2048 + k * 1024); } while (0)
; #define PG8_LDB(dst, b, h) do { _Pragma("unroll") for (int n = 0; n < 2; ++n) _Pragma("unroll") for (int k = 0; k < 2; ++k) dst[n][k] = *(const PG8_LAS bf16x8*)(lds + PG8_SB(b, h) + boff + n * 2048 + k * 1024); } while (0)
; #define PG8_MMA(ai, bj, At, Bt) do { __builtin_amdgcn_s_setprio(1); _Pragma("unroll") for (int m = 0; m < 4; ++m) _Pragma("unroll") for (int n = 0; n < 2; ++n) _Pragma("unroll") for (int k = 0; k < 2; ++k) \
;         acc[ai][bj][m][n] = __builtin_amdgcn_mfma_f32_16x16x32_bf16(Bt[n][k], At[m][k], acc[ai][bj][m][n], 0, 0, 0); __builtin_amdgcn_s_setprio(0); } while (0)
; #define PG8_WAIT_V(n) asm volatile("s_waitcnt vmcnt(" #n ")" ::: "memory")
; #define PG8_WAIT_L(n) asm volatile("s_waitcnt lgkmcnt(" #n ")" ::: "memory")
; template <class Epi, class Sched, bool ALIGN_EPI = false, bool SP2 = false>
; __device__ __forceinline__ void gemm_phase(PG8_LAS unsigned char* lds, const Gemm g, const Sched& S, const Epi& E) {
;     ...
;             const bool last = (t == nt - 2);
;             const char* a1 = cA + (size_t)(t + 1) * kstep;
;             const char* a2 = last ? nA : cA + (size_t)(t + 2) * kstep; const char* b2 = last ? nB : cB + (size_t)(t + 2) * kstep;
;             const char* a3 = a2 + kstep; const char* b3 = b2 + kstep;
;             if (last && has_next) S.a_ready(nxt);
;             if constexpr (SP2) {
;             PG8_LDB(B0, 0, 0); PG8_LDB(B1, 0, 1); PG8_SCHED; PG8_LDA(At, 0, 0); PG8_STAGE(PG8_SA(1, 1), a1 + hstepA, voffA);
;             PG8_WAIT_V(8); PG8_WAIT_L(0); PG8_BAR; PG8_MMA(0, 0, At, B0); PG8_MMA(0, 1, At, B1); PG8_BAR; PG8_SCHED;
;             PG8_LDA(At, 0, 1); PG8_STAGE(PG8_SB(0, 0), b2, voffB); PG8_STAGE(PG8_SB(0, 1), b2 + hstepB, voffB); PG8_STAGE(PG8_SA(0, 0), a2, voffA);
;             PG8_WAIT_V(8); PG8_WAIT_L(0); PG8_BAR; PG8_MMA(1, 0, At, B0); PG8_MMA(1, 1, At, B1); PG8_BAR; PG8_SCHED;
.LBB0_1270:
	s_add_u32 s28, s26, 0xfffc0080
	s_addc_u32 s29, s27, -1
	s_add_i32 s52, 0, 0x10000
	s_cmp_eq_u32 s51, 12
	s_cselect_b32 s31, s17, s29
	s_cselect_b32 s30, s23, s28
	s_cselect_b32 s29, s15, s50
	s_cselect_b32 s28, s25, s49
	s_add_i32 s54, 0, 0x14000
	v_add_u32_e32 v142, s52, v186
	v_add_u32_e32 v172, s54, v186
	ds_read_b128 v[130:133], v142
	ds_read_b128 v[134:137], v142 offset:1024
	ds_read_b128 v[138:141], v142 offset:2048
	ds_read_b128 v[142:145], v142 offset:3072
	ds_read_b128 v[146:149], v172
	ds_read_b128 v[150:153], v172 offset:1024
	ds_read_b128 v[168:171], v172 offset:2048
	ds_read_b128 v[172:175], v172 offset:3072
	s_add_i32 m0, s39, 0xc000
	ds_read_b128 v[176:179], v200
	ds_read_b128 v[180:183], v200 offset:1024
	ds_read_b128 v[202:205], v200 offset:2048
	ds_read_b128 v[206:209], v200 offset:3072
	ds_read_b128 v[210:213], v200 offset:4096
	ds_read_b128 v[232:235], v200 offset:5120
	ds_read_b128 v[236:239], v200 offset:6144
	ds_read_b128 v[240:243], v200 offset:7168
	global_load_lds_dwordx4 v164, s[26:27]
	s_add_i32 m0, s39, 0xe000
	s_nop 0
	global_load_lds_dwordx4 v166, s[26:27]
	s_waitcnt vmcnt(8) lgkmcnt(0)
	s_setprio 1
	s_barrier
	v_mfma_f32_16x16x32_bf16 v[126:129], v[130:133], v[176:179], v[126:129]
	v_mfma_f32_16x16x32_bf16 v[122:125], v[138:141], v[176:179], v[122:125]
	v_mfma_f32_16x16x32_bf16 v[110:113], v[130:133], v[202:205], v[110:113]
	v_mfma_f32_16x16x32_bf16 v[106:109], v[138:141], v[202:205], v[106:109]
	v_mfma_f32_16x16x32_bf16 v[94:97], v[130:133], v[210:213], v[94:97]
	v_mfma_f32_16x16x32_bf16 v[90:93], v[138:141], v[210:213], v[90:93]
	v_mfma_f32_16x16x32_bf16 v[78:81], v[130:133], v[236:239], v[78:81]
	v_mfma_f32_16x16x32_bf16 v[74:77], v[138:141], v[236:239], v[74:77]
	v_mfma_f32_16x16x32_bf16 v[126:129], v[134:137], v[180:183], v[126:129]
	v_mfma_f32_16x16x32_bf16 v[122:125], v[142:145], v[180:183], v[122:125]
	v_mfma_f32_16x16x32_bf16 v[110:113], v[134:137], v[206:209], v[110:113]
	v_mfma_f32_16x16x32_bf16 v[106:109], v[142:145], v[206:209], v[106:109]
	v_mfma_f32_16x16x32_bf16 v[94:97], v[134:137], v[232:235], v[94:97]
	v_mfma_f32_16x16x32_bf16 v[90:93], v[142:145], v[232:235], v[90:93]
	v_mfma_f32_16x16x32_bf16 v[78:81], v[134:137], v[240:243], v[78:81]
	v_mfma_f32_16x16x32_bf16 v[74:77], v[142:145], v[240:243], v[74:77]
	s_setprio 0
	s_setprio 1
	v_mfma_f32_16x16x32_bf16 v[118:121], v[146:149], v[176:179], v[118:121]
	v_mfma_f32_16x16x32_bf16 v[114:117], v[168:171], v[176:179], v[114:117]
	v_mfma_f32_16x16x32_bf16 v[102:105], v[146:149], v[202:205], v[102:105]
	v_mfma_f32_16x16x32_bf16 v[98:101], v[168:171], v[202:205], v[98:101]
	v_mfma_f32_16x16x32_bf16 v[86:89], v[146:149], v[210:213], v[86:89]
	v_mfma_f32_16x16x32_bf16 v[82:85], v[168:171], v[210:213], v[82:85]
	v_mfma_f32_16x16x32_bf16 v[70:73], v[146:149], v[236:239], v[70:73]
	v_mfma_f32_16x16x32_bf16 v[66:69], v[168:171], v[236:239], v[66:69]
	v_mfma_f32_16x16x32_bf16 v[118:121], v[150:153], v[180:183], v[118:121]
	v_mfma_f32_16x16x32_bf16 v[114:117], v[172:175], v[180:183], v[114:117]
	v_mfma_f32_16x16x32_bf16 v[102:105], v[150:153], v[206:209], v[102:105]
	v_mfma_f32_16x16x32_bf16 v[98:101], v[172:175], v[206:209], v[98:101]
	v_mfma_f32_16x16x32_bf16 v[86:89], v[150:153], v[232:235], v[86:89]
	v_mfma_f32_16x16x32_bf16 v[82:85], v[172:175], v[232:235], v[82:85]
	v_mfma_f32_16x16x32_bf16 v[70:73], v[150:153], v[240:243], v[70:73]
	v_mfma_f32_16x16x32_bf16 v[66:69], v[172:175], v[240:243], v[66:69]
	s_setprio 0
	s_barrier
	s_add_i32 s52, s52, s38
	s_mov_b32 m0, s52
	ds_read_b128 v[176:179], v200 offset:16384
	ds_read_b128 v[180:183], v200 offset:17408
	ds_read_b128 v[202:205], v200 offset:18432
	ds_read_b128 v[206:209], v200 offset:19456
	ds_read_b128 v[210:213], v200 offset:20480
	ds_read_b128 v[232:235], v200 offset:21504
	ds_read_b128 v[236:239], v200 offset:22528
	ds_read_b128 v[240:243], v200 offset:23552
	s_add_u32 s60, s28, 0x80
	s_addc_u32 s61, s29, 0
	s_add_u32 s62, s30, 0x80
	s_addc_u32 s63, s31, 0
	global_load_lds_dwordx4 v156, s[28:29]
	s_add_i32 m0, s52, 0x2000
	s_add_u32 s52, s28, 0x40000
	s_addc_u32 s53, s29, 0
	s_add_i32 s54, s54, s38
	global_load_lds_dwordx4 v160, s[28:29]
	s_mov_b32 m0, s54
	s_nop 0
	global_load_lds_dwordx4 v156, s[52:53]
	s_add_i32 m0, s54, 0x2000
	s_nop 0
	global_load_lds_dwordx4 v160, s[52:53]
	s_mov_b32 m0, s39
	s_nop 0
	global_load_lds_dwordx4 v154, s[30:31]
	s_mov_b32 m0, s40
	s_nop 0
	global_load_lds_dwordx4 v158, s[30:31]
	s_waitcnt vmcnt(8) lgkmcnt(0)
	s_setprio 1
	s_barrier
	v_mfma_f32_16x16x32_bf16 v[62:65], v[130:133], v[176:179], v[62:65]
	v_mfma_f32_16x16x32_bf16 v[58:61], v[138:141], v[176:179], v[58:61]
	v_mfma_f32_16x16x32_bf16 v[46:49], v[130:133], v[202:205], v[46:49]
	v_mfma_f32_16x16x32_bf16 v[42:45], v[138:141], v[202:205], v[42:45]
	v_mfma_f32_16x16x32_bf16 v[30:33], v[130:133], v[210:213], v[30:33]
	v_mfma_f32_16x16x32_bf16 v[26:29], v[138:141], v[210:213], v[26:29]
	v_mfma_f32_16x16x32_bf16 v[14:17], v[130:133], v[236:239], v[14:17]
	v_mfma_f32_16x16x32_bf16 v[10:13], v[138:141], v[236:239], v[10:13]
	v_mfma_f32_16x16x32_bf16 v[62:65], v[134:137], v[180:183], v[62:65]
	v_mfma_f32_16x16x32_bf16 v[58:61], v[142:145], v[180:183], v[58:61]
	v_mfma_f32_16x16x32_bf16 v[46:49], v[134:137], v[206:209], v[46:49]
	v_mfma_f32_16x16x32_bf16 v[42:45], v[142:145], v[206:209], v[42:45]
	v_mfma_f32_16x16x32_bf16 v[30:33], v[134:137], v[232:235], v[30:33]
	v_mfma_f32_16x16x32_bf16 v[26:29], v[142:145], v[232:235], v[26:29]
	v_mfma_f32_16x16x32_bf16 v[14:17], v[134:137], v[240:243], v[14:17]
	v_mfma_f32_16x16x32_bf16 v[10:13], v[142:145], v[240:243], v[10:13]
	s_setprio 0
	s_setprio 1
	v_mfma_f32_16x16x32_bf16 v[54:57], v[146:149], v[176:179], v[54:57]
	v_mfma_f32_16x16x32_bf16 v[50:53], v[168:171], v[176:179], v[50:53]
	v_mfma_f32_16x16x32_bf16 v[38:41], v[146:149], v[202:205], v[38:41]
	v_mfma_f32_16x16x32_bf16 v[34:37], v[168:171], v[202:205], v[34:37]
	v_mfma_f32_16x16x32_bf16 v[22:25], v[146:149], v[210:213], v[22:25]
	v_mfma_f32_16x16x32_bf16 v[18:21], v[168:171], v[210:213], v[18:21]
	v_mfma_f32_16x16x32_bf16 v[6:9], v[146:149], v[236:239], v[6:9]
	v_mfma_f32_16x16x32_bf16 v[2:5], v[168:171], v[236:239], v[2:5]
	v_mfma_f32_16x16x32_bf16 v[54:57], v[150:153], v[180:183], v[54:57]
	v_mfma_f32_16x16x32_bf16 v[50:53], v[172:175], v[180:183], v[50:53]
	v_mfma_f32_16x16x32_bf16 v[38:41], v[150:153], v[206:209], v[38:41]
	v_mfma_f32_16x16x32_bf16 v[34:37], v[172:175], v[206:209], v[34:37]
	v_mfma_f32_16x16x32_bf16 v[22:25], v[150:153], v[232:235], v[22:25]
	v_mfma_f32_16x16x32_bf16 v[18:21], v[172:175], v[232:235], v[18:21]
	v_mfma_f32_16x16x32_bf16 v[6:9], v[150:153], v[240:243], v[6:9]
	v_mfma_f32_16x16x32_bf16 v[2:5], v[172:175], v[240:243], v[2:5]
	s_setprio 0
	s_barrier
; #define PG8_STAGE(bufoff, gbase, voff) do { _Pragma("unroll") for (int _i = 0; _i < 2; ++_i) \
;         __builtin_amdgcn_global_load_lds((const unsigned*)((const char*)(gbase) + (voff)[_i]), (PG8_LAS unsigned*)(lds + (bufoff) + ldsw + _i * 8192), 16, 0, 0); } while (0)
; #define PG8_LDA(dst, b, h) do { _Pragma("unroll") for (int m = 0; m < 4; ++m) _Pragma("unroll") for (int k = 0; k < 2; ++k) dst[m][k] = *(const PG8_LAS bf16x8*)(lds + PG8_SA(b, h) + aoff + m * 2048 + k * 1024); } while (0)
; #define PG8_LDB(dst, b, h) do { _Pragma("unroll") for (int n = 0; n < 2; ++n) _Pragma("unroll") for (int k = 0; k < 2; ++k) dst[n][k] = *(const PG8_LAS bf16x8*)(lds + PG8_SB(b, h) + boff + n * 2048 + k * 1024); } while (0)
; #define PG8_MMA(ai, bj, At, Bt) do { __builtin_amdgcn_s_setprio(1); _Pragma("unroll") for (int m = 0; m < 4; ++m) _Pragma("unroll") for (int n = 0; n < 2; ++n) _Pragma("unroll") for (int k = 0; k < 2; ++k) \
;         acc[ai][bj][m][n] = __builtin_amdgcn_mfma_f32_16x16x32_bf16(Bt[n][k], At[m][k], acc[ai][bj][m][n], 0, 0, 0); __builtin_amdgcn_s_setprio(0); } while (0)
; #define PG8_WAIT_V(n) asm volatile("s_waitcnt vmcnt(" #n ")" ::: "memory")
; #define PG8_WAIT_L(n) asm volatile("s_waitcnt lgkmcnt(" #n ")" ::: "memory")
; #define PG8_BAR __builtin_amdgcn_s_barrier()
; #define PG8_SCHED __builtin_amdgcn_sched_barrier(0)
; template <class Epi, class Sched, bool ALIGN_EPI = false, bool SP2 = false>
; __device__ __forceinline__ void gemm_phase(PG8_LAS unsigned char* lds, const Gemm g, const Sched& S, const Epi& E) {
;     ...
;         for (int t = 0; t < nt; t += 2) {
;     ...
;             PG8_LDB(B0, 1, 0); PG8_LDB(B1, 1, 1); PG8_SCHED; PG8_LDA(At, 1, 0); PG8_STAGE(PG8_SA(0, 1), a2 + hstepA, voffA);
;             PG8_WAIT_V(8); PG8_WAIT_L(0); PG8_BAR; PG8_MMA(0, 0, At, B0); PG8_MMA(0, 1, At, B1); PG8_BAR; PG8_SCHED;
;             PG8_LDA(At, 1, 1); PG8_STAGE(PG8_SB(1, 0), b3, voffB); PG8_STAGE(PG8_SB(1, 1), b3 + hstepB, voffB); PG8_STAGE(PG8_SA(1, 0), a3, voffA);
;             PG8_WAIT_V(8); PG8_WAIT_L(0); PG8_BAR; PG8_MMA(1, 0, At, B0); PG8_MMA(1, 1, At, B1); PG8_BAR; PG8_SCHED;
;     ...
;         if constexpr (ALIGN_EPI) { if (wr == 0) PG8_BAR; }
	s_add_i32 s52, 0, 0x18000
	s_add_i32 s53, 0, 0x1c000
	v_add_u32_e32 v142, s52, v186
	v_add_u32_e32 v172, s53, v186
	ds_read_b128 v[130:133], v142
	ds_read_b128 v[134:137], v142 offset:1024
	ds_read_b128 v[138:141], v142 offset:2048
	ds_read_b128 v[142:145], v142 offset:3072
	ds_read_b128 v[146:149], v172
	ds_read_b128 v[150:153], v172 offset:1024
	ds_read_b128 v[168:171], v172 offset:2048
	ds_read_b128 v[172:175], v172 offset:3072
	s_add_u32 s30, s30, 0x40000
	s_addc_u32 s31, s31, 0
	s_mov_b32 m0, s41
	ds_read_b128 v[176:179], v200 offset:32768
	ds_read_b128 v[180:183], v200 offset:33792
	ds_read_b128 v[202:205], v200 offset:34816
	ds_read_b128 v[206:209], v200 offset:35840
	ds_read_b128 v[210:213], v200 offset:36864
	ds_read_b128 v[232:235], v200 offset:37888
	ds_read_b128 v[236:239], v200 offset:38912
	ds_read_b128 v[240:243], v200 offset:39936
	global_load_lds_dwordx4 v154, s[30:31]
	s_mov_b32 m0, s42
	s_nop 0
	global_load_lds_dwordx4 v158, s[30:31]
	s_waitcnt vmcnt(8) lgkmcnt(0)
	s_setprio 1
	s_barrier
	v_mfma_f32_16x16x32_bf16 v[126:129], v[130:133], v[176:179], v[126:129]
	v_mfma_f32_16x16x32_bf16 v[122:125], v[138:141], v[176:179], v[122:125]
	v_mfma_f32_16x16x32_bf16 v[110:113], v[130:133], v[202:205], v[110:113]
	v_mfma_f32_16x16x32_bf16 v[106:109], v[138:141], v[202:205], v[106:109]
	v_mfma_f32_16x16x32_bf16 v[94:97], v[130:133], v[210:213], v[94:97]
	v_mfma_f32_16x16x32_bf16 v[90:93], v[138:141], v[210:213], v[90:93]
	v_mfma_f32_16x16x32_bf16 v[78:81], v[130:133], v[236:239], v[78:81]
	v_mfma_f32_16x16x32_bf16 v[74:77], v[138:141], v[236:239], v[74:77]
	v_mfma_f32_16x16x32_bf16 v[126:129], v[134:137], v[180:183], v[126:129]
	v_mfma_f32_16x16x32_bf16 v[122:125], v[142:145], v[180:183], v[122:125]
	v_mfma_f32_16x16x32_bf16 v[110:113], v[134:137], v[206:209], v[110:113]
	v_mfma_f32_16x16x32_bf16 v[106:109], v[142:145], v[206:209], v[106:109]
	v_mfma_f32_16x16x32_bf16 v[94:97], v[134:137], v[232:235], v[94:97]
	v_mfma_f32_16x16x32_bf16 v[90:93], v[142:145], v[232:235], v[90:93]
	v_mfma_f32_16x16x32_bf16 v[78:81], v[134:137], v[240:243], v[78:81]
	v_mfma_f32_16x16x32_bf16 v[74:77], v[142:145], v[240:243], v[74:77]
	s_setprio 0
	s_setprio 1
	v_mfma_f32_16x16x32_bf16 v[118:121], v[146:149], v[176:179], v[118:121]
	v_mfma_f32_16x16x32_bf16 v[114:117], v[168:171], v[176:179], v[114:117]
	v_mfma_f32_16x16x32_bf16 v[102:105], v[146:149], v[202:205], v[102:105]
	v_mfma_f32_16x16x32_bf16 v[98:101], v[168:171], v[202:205], v[98:101]
	v_mfma_f32_16x16x32_bf16 v[86:89], v[146:149], v[210:213], v[86:89]
	v_mfma_f32_16x16x32_bf16 v[82:85], v[168:171], v[210:213], v[82:85]
	v_mfma_f32_16x16x32_bf16 v[70:73], v[146:149], v[236:239], v[70:73]
	v_mfma_f32_16x16x32_bf16 v[66:69], v[168:171], v[236:239], v[66:69]
	v_mfma_f32_16x16x32_bf16 v[118:121], v[150:153], v[180:183], v[118:121]
	v_mfma_f32_16x16x32_bf16 v[114:117], v[172:175], v[180:183], v[114:117]
	v_mfma_f32_16x16x32_bf16 v[102:105], v[150:153], v[206:209], v[102:105]
	v_mfma_f32_16x16x32_bf16 v[98:101], v[172:175], v[206:209], v[98:101]
	v_mfma_f32_16x16x32_bf16 v[86:89], v[150:153], v[232:235], v[86:89]
	v_mfma_f32_16x16x32_bf16 v[82:85], v[172:175], v[232:235], v[82:85]
	v_mfma_f32_16x16x32_bf16 v[70:73], v[150:153], v[240:243], v[70:73]
	v_mfma_f32_16x16x32_bf16 v[66:69], v[172:175], v[240:243], v[66:69]
	s_setprio 0
	s_barrier
	s_add_i32 s30, s52, s38
	s_mov_b32 m0, s30
	ds_read_b128 v[176:179], v200 offset:49152
	ds_read_b128 v[180:183], v200 offset:50176
	ds_read_b128 v[202:205], v200 offset:51200
	ds_read_b128 v[206:209], v200 offset:52224
	ds_read_b128 v[210:213], v200 offset:53248
	ds_read_b128 v[232:235], v200 offset:54272
	ds_read_b128 v[236:239], v200 offset:55296
	ds_read_b128 v[240:243], v200 offset:56320
	global_load_lds_dwordx4 v156, s[60:61]
	s_add_i32 m0, s30, 0x2000
	s_add_u32 s28, s28, 0x40080
	s_addc_u32 s29, s29, 0
	s_add_i32 s30, s53, s38
	global_load_lds_dwordx4 v160, s[60:61]
	s_mov_b32 m0, s30
	s_nop 0
	global_load_lds_dwordx4 v156, s[28:29]
	s_add_i32 m0, s30, 0x2000
	s_nop 0
	global_load_lds_dwordx4 v160, s[28:29]
	s_mov_b32 m0, s44
	s_nop 0
	global_load_lds_dwordx4 v154, s[62:63]
	s_mov_b32 m0, s45
	s_nop 0
	global_load_lds_dwordx4 v158, s[62:63]
	s_waitcnt vmcnt(8) lgkmcnt(0)
	s_setprio 1
	s_barrier
	v_mfma_f32_16x16x32_bf16 v[62:65], v[130:133], v[176:179], v[62:65]
	v_mfma_f32_16x16x32_bf16 v[58:61], v[138:141], v[176:179], v[58:61]
	v_mfma_f32_16x16x32_bf16 v[46:49], v[130:133], v[202:205], v[46:49]
	v_mfma_f32_16x16x32_bf16 v[42:45], v[138:141], v[202:205], v[42:45]
	v_mfma_f32_16x16x32_bf16 v[30:33], v[130:133], v[210:213], v[30:33]
	v_mfma_f32_16x16x32_bf16 v[26:29], v[138:141], v[210:213], v[26:29]
	v_mfma_f32_16x16x32_bf16 v[14:17], v[130:133], v[236:239], v[14:17]
	v_mfma_f32_16x16x32_bf16 v[10:13], v[138:141], v[236:239], v[10:13]
	v_mfma_f32_16x16x32_bf16 v[62:65], v[134:137], v[180:183], v[62:65]
	v_mfma_f32_16x16x32_bf16 v[58:61], v[142:145], v[180:183], v[58:61]
	v_mfma_f32_16x16x32_bf16 v[46:49], v[134:137], v[206:209], v[46:49]
	v_mfma_f32_16x16x32_bf16 v[42:45], v[142:145], v[206:209], v[42:45]
	v_mfma_f32_16x16x32_bf16 v[30:33], v[134:137], v[232:235], v[30:33]
	v_mfma_f32_16x16x32_bf16 v[26:29], v[142:145], v[232:235], v[26:29]
	v_mfma_f32_16x16x32_bf16 v[14:17], v[134:137], v[240:243], v[14:17]
	v_mfma_f32_16x16x32_bf16 v[10:13], v[142:145], v[240:243], v[10:13]
	s_setprio 0
	s_setprio 1
	v_mfma_f32_16x16x32_bf16 v[54:57], v[146:149], v[176:179], v[54:57]
	v_mfma_f32_16x16x32_bf16 v[50:53], v[168:171], v[176:179], v[50:53]
	v_mfma_f32_16x16x32_bf16 v[38:41], v[146:149], v[202:205], v[38:41]
	v_mfma_f32_16x16x32_bf16 v[34:37], v[168:171], v[202:205], v[34:37]
	v_mfma_f32_16x16x32_bf16 v[22:25], v[146:149], v[210:213], v[22:25]
	v_mfma_f32_16x16x32_bf16 v[18:21], v[168:171], v[210:213], v[18:21]
	v_mfma_f32_16x16x32_bf16 v[6:9], v[146:149], v[236:239], v[6:9]
	v_mfma_f32_16x16x32_bf16 v[2:5], v[168:171], v[236:239], v[2:5]
	v_mfma_f32_16x16x32_bf16 v[54:57], v[150:153], v[180:183], v[54:57]
	v_mfma_f32_16x16x32_bf16 v[50:53], v[172:175], v[180:183], v[50:53]
	v_mfma_f32_16x16x32_bf16 v[38:41], v[150:153], v[206:209], v[38:41]
	v_mfma_f32_16x16x32_bf16 v[34:37], v[172:175], v[206:209], v[34:37]
	v_mfma_f32_16x16x32_bf16 v[22:25], v[150:153], v[232:235], v[22:25]
	v_mfma_f32_16x16x32_bf16 v[18:21], v[172:175], v[232:235], v[18:21]
	v_mfma_f32_16x16x32_bf16 v[6:9], v[150:153], v[240:243], v[6:9]
	v_mfma_f32_16x16x32_bf16 v[2:5], v[172:175], v[240:243], v[2:5]
	s_setprio 0
	s_barrier
	s_add_i32 s51, s51, 2
	s_add_u32 s26, s26, 0x100
	s_addc_u32 s27, s27, 0
	s_add_u32 s49, s49, 0x100
	s_addc_u32 s50, s50, 0
	s_cmp_gt_u32 s51, 13
	s_cbranch_scc0 .LBB0_1270
	s_and_b64 vcc, exec, s[12:13]
	s_cbranch_vccz .LBB0_1273
	s_barrier

; #define PG8_STAGE(bufoff, gbase, voff) do { _Pragma("unroll") for (int _i = 0; _i < 2; ++_i) \
;         __builtin_amdgcn_global_load_lds((const unsigned*)((const char*)(gbase) + (voff)[_i]), (PG8_LAS unsigned*)(lds + (bufoff) + ldsw + _i * 8192), 16, 0, 0); } while (0)
; #define PG8_LDA(dst, b, h) do { _Pragma("unroll") for (int m = 0; m < 4; ++m) _Pragma("unroll") for (int k = 0; k < 2; ++k) dst[m][k] = *(const PG8_LAS bf16x8*)(lds + PG8_SA(b, h) + aoff + m * 2048 + k * 1024); } while (0)
; #define PG8_LDB(dst, b, h) do { _Pragma("unroll") for (int n = 0; n < 2; ++n) _Pragma("unroll") for (int k = 0; k < 2; ++k) dst[n][k] = *(const PG8_LAS bf16x8*)(lds + PG8_SB(b, h) + boff + n * 2048 + k * 1024); } while (0)
; #define PG8_MMA(ai, bj, At, Bt) do { __builtin_amdgcn_s_setprio(1); _Pragma("unroll") for (int m = 0; m < 4; ++m) _Pragma("unroll") for (int n = 0; n < 2; ++n) _Pragma("unroll") for (int k = 0; k < 2; ++k) \
;         acc[ai][bj][m][n] = __builtin_amdgcn_mfma_f32_16x16x32_bf16(Bt[n][k], At[m][k], acc[ai][bj][m][n], 0, 0, 0); __builtin_amdgcn_s_setprio(0); } while (0)
; #define PG8_WAIT_V(n) asm volatile("s_waitcnt vmcnt(" #n ")" ::: "memory")
; #define PG8_WAIT_L(n) asm volatile("s_waitcnt lgkmcnt(" #n ")" ::: "memory")
; template <class Epi, class Sched, bool ALIGN_EPI = false, bool SP2 = false>
; __device__ __forceinline__ void gemm_phase(PG8_LAS unsigned char* lds, const Gemm g, const Sched& S, const Epi& E) {
;     ...
;             const bool last = (t == nt - 2);
;             const char* a1 = cA + (size_t)(t + 1) * kstep;
;             const char* a2 = last ? nA : cA + (size_t)(t + 2) * kstep; const char* b2 = last ? nB : cB + (size_t)(t + 2) * kstep;
;             const char* a3 = a2 + kstep; const char* b3 = b2 + kstep;
;             if (last && has_next) S.a_ready(nxt);
;             if constexpr (SP2) {
;             PG8_LDB(B0, 0, 0); PG8_LDB(B1, 0, 1); PG8_SCHED; PG8_LDA(At, 0, 0); PG8_STAGE(PG8_SA(1, 1), a1 + hstepA, voffA);
;             PG8_WAIT_V(8); PG8_WAIT_L(0); PG8_BAR; PG8_MMA(0, 0, At, B0); PG8_MMA(0, 1, At, B1); PG8_BAR; PG8_SCHED;
;             PG8_LDA(At, 0, 1); PG8_STAGE(PG8_SB(0, 0), b2, voffB); PG8_STAGE(PG8_SB(0, 1), b2 + hstepB, voffB); PG8_STAGE(PG8_SA(0, 0), a2, voffA);
;             PG8_WAIT_V(8); PG8_WAIT_L(0); PG8_BAR; PG8_MMA(1, 0, At, B0); PG8_MMA(1, 1, At, B1); PG8_BAR; PG8_SCHED;
.LBB0_1354:
	s_add_u32 s24, s22, 0xfffc0080
	s_addc_u32 s25, s23, -1
	s_add_i32 s49, 0, 0x10000
	s_cmp_eq_u32 s48, 12
	s_cselect_b32 s27, s15, s25
	s_cselect_b32 s26, s21, s24
	v_add_u32_e32 v142, s49, v145
	s_cselect_b32 s25, s13, s47
	s_cselect_b32 s24, s45, s46
	s_add_i32 s52, 0, 0x14000
	ds_read_b128 v[150:153], v142
	ds_read_b128 v[154:157], v142 offset:1024
	ds_read_b128 v[158:161], v142 offset:2048
	ds_read_b128 v[162:165], v142 offset:3072
	v_add_u32_e32 v142, s52, v145
	ds_read_b128 v[166:169], v142
	ds_read_b128 v[170:173], v142 offset:1024
	ds_read_b128 v[174:177], v142 offset:2048
	ds_read_b128 v[178:181], v142 offset:3072
	s_add_i32 m0, s36, 0xc000
	ds_read_b128 v[182:185], v148
	ds_read_b128 v[202:205], v148 offset:1024
	ds_read_b128 v[206:209], v148 offset:2048
	ds_read_b128 v[210:213], v148 offset:3072
	ds_read_b128 v[232:235], v148 offset:4096
	ds_read_b128 v[236:239], v148 offset:5120
	ds_read_b128 v[240:243], v148 offset:6144
	ds_read_b128 v[244:247], v148 offset:7168
	global_load_lds_dwordx4 v138, s[22:23]
	s_add_i32 m0, s36, 0xe000
	s_nop 0
	global_load_lds_dwordx4 v140, s[22:23]
	s_waitcnt vmcnt(8) lgkmcnt(0)
	s_setprio 1
	s_barrier
	v_mfma_f32_16x16x32_bf16 v[126:129], v[150:153], v[182:185], v[126:129]
	v_mfma_f32_16x16x32_bf16 v[122:125], v[158:161], v[182:185], v[122:125]
	v_mfma_f32_16x16x32_bf16 v[114:117], v[150:153], v[206:209], v[114:117]
	v_mfma_f32_16x16x32_bf16 v[106:109], v[158:161], v[206:209], v[106:109]
	v_mfma_f32_16x16x32_bf16 v[98:101], v[150:153], v[232:235], v[98:101]
	v_mfma_f32_16x16x32_bf16 v[90:93], v[158:161], v[232:235], v[90:93]
	v_mfma_f32_16x16x32_bf16 v[78:81], v[150:153], v[240:243], v[78:81]
	v_mfma_f32_16x16x32_bf16 v[74:77], v[158:161], v[240:243], v[74:77]
	v_mfma_f32_16x16x32_bf16 v[126:129], v[154:157], v[202:205], v[126:129]
	v_mfma_f32_16x16x32_bf16 v[122:125], v[162:165], v[202:205], v[122:125]
	v_mfma_f32_16x16x32_bf16 v[114:117], v[154:157], v[210:213], v[114:117]
	v_mfma_f32_16x16x32_bf16 v[106:109], v[162:165], v[210:213], v[106:109]
	v_mfma_f32_16x16x32_bf16 v[98:101], v[154:157], v[236:239], v[98:101]
	v_mfma_f32_16x16x32_bf16 v[90:93], v[162:165], v[236:239], v[90:93]
	v_mfma_f32_16x16x32_bf16 v[78:81], v[154:157], v[244:247], v[78:81]
	v_mfma_f32_16x16x32_bf16 v[74:77], v[162:165], v[244:247], v[74:77]
	s_setprio 0
	s_setprio 1
	v_mfma_f32_16x16x32_bf16 v[118:121], v[166:169], v[182:185], v[118:121]
	v_mfma_f32_16x16x32_bf16 v[110:113], v[174:177], v[182:185], v[110:113]
	v_mfma_f32_16x16x32_bf16 v[102:105], v[166:169], v[206:209], v[102:105]
	v_mfma_f32_16x16x32_bf16 v[94:97], v[174:177], v[206:209], v[94:97]
	v_mfma_f32_16x16x32_bf16 v[86:89], v[166:169], v[232:235], v[86:89]
	v_mfma_f32_16x16x32_bf16 v[82:85], v[174:177], v[232:235], v[82:85]
	v_mfma_f32_16x16x32_bf16 v[70:73], v[166:169], v[240:243], v[70:73]
	v_mfma_f32_16x16x32_bf16 v[66:69], v[174:177], v[240:243], v[66:69]
	v_mfma_f32_16x16x32_bf16 v[118:121], v[170:173], v[202:205], v[118:121]
	v_mfma_f32_16x16x32_bf16 v[110:113], v[178:181], v[202:205], v[110:113]
	v_mfma_f32_16x16x32_bf16 v[102:105], v[170:173], v[210:213], v[102:105]
	v_mfma_f32_16x16x32_bf16 v[94:97], v[178:181], v[210:213], v[94:97]
	v_mfma_f32_16x16x32_bf16 v[86:89], v[170:173], v[236:239], v[86:89]
	v_mfma_f32_16x16x32_bf16 v[82:85], v[178:181], v[236:239], v[82:85]
	v_mfma_f32_16x16x32_bf16 v[70:73], v[170:173], v[244:247], v[70:73]
	v_mfma_f32_16x16x32_bf16 v[66:69], v[178:181], v[244:247], v[66:69]
	s_setprio 0
	s_barrier
	s_add_i32 s49, s49, s34
	s_mov_b32 m0, s49
	ds_read_b128 v[182:185], v148 offset:16384
	ds_read_b128 v[202:205], v148 offset:17408
	ds_read_b128 v[206:209], v148 offset:18432
	ds_read_b128 v[210:213], v148 offset:19456
	ds_read_b128 v[232:235], v148 offset:20480
	ds_read_b128 v[236:239], v148 offset:21504
	ds_read_b128 v[240:243], v148 offset:22528
	ds_read_b128 v[244:247], v148 offset:23552
	s_add_u32 s60, s24, 0x80
	s_addc_u32 s61, s25, 0
	s_add_u32 s62, s26, 0x80
	s_addc_u32 s63, s27, 0
	global_load_lds_dwordx4 v134, s[24:25]
	s_add_i32 m0, s49, 0x2000
	s_add_u32 s50, s24, 0x40000
	s_addc_u32 s51, s25, 0
	s_add_i32 s49, s52, s34
	global_load_lds_dwordx4 v130, s[24:25]
	s_mov_b32 m0, s49
	s_nop 0
	global_load_lds_dwordx4 v134, s[50:51]
	s_add_i32 m0, s49, 0x2000
	s_nop 0
	global_load_lds_dwordx4 v130, s[50:51]
	s_mov_b32 m0, s36
	s_nop 0
	global_load_lds_dwordx4 v136, s[26:27]
	s_mov_b32 m0, s37
	s_nop 0
	global_load_lds_dwordx4 v132, s[26:27]
	s_waitcnt vmcnt(8) lgkmcnt(0)
	s_setprio 1
	s_barrier
	v_mfma_f32_16x16x32_bf16 v[62:65], v[150:153], v[182:185], v[62:65]
	v_mfma_f32_16x16x32_bf16 v[58:61], v[158:161], v[182:185], v[58:61]
	v_mfma_f32_16x16x32_bf16 v[46:49], v[150:153], v[206:209], v[46:49]
	v_mfma_f32_16x16x32_bf16 v[42:45], v[158:161], v[206:209], v[42:45]
	v_mfma_f32_16x16x32_bf16 v[30:33], v[150:153], v[232:235], v[30:33]
	v_mfma_f32_16x16x32_bf16 v[26:29], v[158:161], v[232:235], v[26:29]
	v_mfma_f32_16x16x32_bf16 v[14:17], v[150:153], v[240:243], v[14:17]
	v_mfma_f32_16x16x32_bf16 v[10:13], v[158:161], v[240:243], v[10:13]
	v_mfma_f32_16x16x32_bf16 v[62:65], v[154:157], v[202:205], v[62:65]
	v_mfma_f32_16x16x32_bf16 v[58:61], v[162:165], v[202:205], v[58:61]
	v_mfma_f32_16x16x32_bf16 v[46:49], v[154:157], v[210:213], v[46:49]
	v_mfma_f32_16x16x32_bf16 v[42:45], v[162:165], v[210:213], v[42:45]
	v_mfma_f32_16x16x32_bf16 v[30:33], v[154:157], v[236:239], v[30:33]
	v_mfma_f32_16x16x32_bf16 v[26:29], v[162:165], v[236:239], v[26:29]
	v_mfma_f32_16x16x32_bf16 v[14:17], v[154:157], v[244:247], v[14:17]
	v_mfma_f32_16x16x32_bf16 v[10:13], v[162:165], v[244:247], v[10:13]
	s_setprio 0
	s_setprio 1
	v_mfma_f32_16x16x32_bf16 v[54:57], v[166:169], v[182:185], v[54:57]
	v_mfma_f32_16x16x32_bf16 v[50:53], v[174:177], v[182:185], v[50:53]
	v_mfma_f32_16x16x32_bf16 v[38:41], v[166:169], v[206:209], v[38:41]
	v_mfma_f32_16x16x32_bf16 v[34:37], v[174:177], v[206:209], v[34:37]
	v_mfma_f32_16x16x32_bf16 v[22:25], v[166:169], v[232:235], v[22:25]
	v_mfma_f32_16x16x32_bf16 v[18:21], v[174:177], v[232:235], v[18:21]
	v_mfma_f32_16x16x32_bf16 v[6:9], v[166:169], v[240:243], v[6:9]
	v_mfma_f32_16x16x32_bf16 v[2:5], v[174:177], v[240:243], v[2:5]
	v_mfma_f32_16x16x32_bf16 v[54:57], v[170:173], v[202:205], v[54:57]
	v_mfma_f32_16x16x32_bf16 v[50:53], v[178:181], v[202:205], v[50:53]
	v_mfma_f32_16x16x32_bf16 v[38:41], v[170:173], v[210:213], v[38:41]
	v_mfma_f32_16x16x32_bf16 v[34:37], v[178:181], v[210:213], v[34:37]
	v_mfma_f32_16x16x32_bf16 v[22:25], v[170:173], v[236:239], v[22:25]
	v_mfma_f32_16x16x32_bf16 v[18:21], v[178:181], v[236:239], v[18:21]
	v_mfma_f32_16x16x32_bf16 v[6:9], v[170:173], v[244:247], v[6:9]
	v_mfma_f32_16x16x32_bf16 v[2:5], v[178:181], v[244:247], v[2:5]
	s_setprio 0
	s_barrier
; #define PG8_STAGE(bufoff, gbase, voff) do { _Pragma("unroll") for (int _i = 0; _i < 2; ++_i) \
;         __builtin_amdgcn_global_load_lds((const unsigned*)((const char*)(gbase) + (voff)[_i]), (PG8_LAS unsigned*)(lds + (bufoff) + ldsw + _i * 8192), 16, 0, 0); } while (0)
; #define PG8_LDA(dst, b, h) do { _Pragma("unroll") for (int m = 0; m < 4; ++m) _Pragma("unroll") for (int k = 0; k < 2; ++k) dst[m][k] = *(const PG8_LAS bf16x8*)(lds + PG8_SA(b, h) + aoff + m * 2048 + k * 1024); } while (0)
; #define PG8_LDB(dst, b, h) do { _Pragma("unroll") for (int n = 0; n < 2; ++n) _Pragma("unroll") for (int k = 0; k < 2; ++k) dst[n][k] = *(const PG8_LAS bf16x8*)(lds + PG8_SB(b, h) + boff + n * 2048 + k * 1024); } while (0)
; #define PG8_MMA(ai, bj, At, Bt) do { __builtin_amdgcn_s_setprio(1); _Pragma("unroll") for (int m = 0; m < 4; ++m) _Pragma("unroll") for (int n = 0; n < 2; ++n) _Pragma("unroll") for (int k = 0; k < 2; ++k) \
;         acc[ai][bj][m][n] = __builtin_amdgcn_mfma_f32_16x16x32_bf16(Bt[n][k], At[m][k], acc[ai][bj][m][n], 0, 0, 0); __builtin_amdgcn_s_setprio(0); } while (0)
; #define PG8_WAIT_V(n) asm volatile("s_waitcnt vmcnt(" #n ")" ::: "memory")
; #define PG8_WAIT_L(n) asm volatile("s_waitcnt lgkmcnt(" #n ")" ::: "memory")
; #define PG8_BAR __builtin_amdgcn_s_barrier()
; #define PG8_SCHED __builtin_amdgcn_sched_barrier(0)
; template <class Epi, class Sched, bool ALIGN_EPI = false, bool SP2 = false>
; __device__ __forceinline__ void gemm_phase(PG8_LAS unsigned char* lds, const Gemm g, const Sched& S, const Epi& E) {
;     ...
;         for (int t = 0; t < nt; t += 2) {
;     ...
;             PG8_LDB(B0, 1, 0); PG8_LDB(B1, 1, 1); PG8_SCHED; PG8_LDA(At, 1, 0); PG8_STAGE(PG8_SA(0, 1), a2 + hstepA, voffA);
;             PG8_WAIT_V(8); PG8_WAIT_L(0); PG8_BAR; PG8_MMA(0, 0, At, B0); PG8_MMA(0, 1, At, B1); PG8_BAR; PG8_SCHED;
;             PG8_LDA(At, 1, 1); PG8_STAGE(PG8_SB(1, 0), b3, voffB); PG8_STAGE(PG8_SB(1, 1), b3 + hstepB, voffB); PG8_STAGE(PG8_SA(1, 0), a3, voffA);
;             PG8_WAIT_V(8); PG8_WAIT_L(0); PG8_BAR; PG8_MMA(1, 0, At, B0); PG8_MMA(1, 1, At, B1); PG8_BAR; PG8_SCHED;
;     ...
;         if constexpr (ALIGN_EPI) { if (wr == 0) PG8_BAR; }
	s_add_i32 s49, 0, 0x18000
	v_add_u32_e32 v144, s49, v145
	s_add_i32 s50, 0, 0x1c000
	ds_read_b128 v[150:153], v144
	ds_read_b128 v[154:157], v144 offset:1024
	ds_read_b128 v[158:161], v144 offset:2048
	ds_read_b128 v[162:165], v144 offset:3072
	v_add_u32_e32 v144, s50, v145
	ds_read_b128 v[166:169], v144
	ds_read_b128 v[170:173], v144 offset:1024
	ds_read_b128 v[174:177], v144 offset:2048
	ds_read_b128 v[178:181], v144 offset:3072
	s_add_u32 s26, s26, 0x40000
	s_addc_u32 s27, s27, 0
	s_mov_b32 m0, s38
	ds_read_b128 v[182:185], v148 offset:32768
	ds_read_b128 v[202:205], v148 offset:33792
	ds_read_b128 v[206:209], v148 offset:34816
	ds_read_b128 v[210:213], v148 offset:35840
	ds_read_b128 v[232:235], v148 offset:36864
	ds_read_b128 v[236:239], v148 offset:37888
	ds_read_b128 v[240:243], v148 offset:38912
	ds_read_b128 v[244:247], v148 offset:39936
	global_load_lds_dwordx4 v136, s[26:27]
	s_mov_b32 m0, s39
	s_nop 0
	global_load_lds_dwordx4 v132, s[26:27]
	s_waitcnt vmcnt(8) lgkmcnt(0)
	s_setprio 1
	s_barrier
	v_mfma_f32_16x16x32_bf16 v[126:129], v[150:153], v[182:185], v[126:129]
	v_mfma_f32_16x16x32_bf16 v[122:125], v[158:161], v[182:185], v[122:125]
	v_mfma_f32_16x16x32_bf16 v[114:117], v[150:153], v[206:209], v[114:117]
	v_mfma_f32_16x16x32_bf16 v[106:109], v[158:161], v[206:209], v[106:109]
	v_mfma_f32_16x16x32_bf16 v[98:101], v[150:153], v[232:235], v[98:101]
	v_mfma_f32_16x16x32_bf16 v[90:93], v[158:161], v[232:235], v[90:93]
	v_mfma_f32_16x16x32_bf16 v[78:81], v[150:153], v[240:243], v[78:81]
	v_mfma_f32_16x16x32_bf16 v[74:77], v[158:161], v[240:243], v[74:77]
	v_mfma_f32_16x16x32_bf16 v[126:129], v[154:157], v[202:205], v[126:129]
	v_mfma_f32_16x16x32_bf16 v[122:125], v[162:165], v[202:205], v[122:125]
	v_mfma_f32_16x16x32_bf16 v[114:117], v[154:157], v[210:213], v[114:117]
	v_mfma_f32_16x16x32_bf16 v[106:109], v[162:165], v[210:213], v[106:109]
	v_mfma_f32_16x16x32_bf16 v[98:101], v[154:157], v[236:239], v[98:101]
	v_mfma_f32_16x16x32_bf16 v[90:93], v[162:165], v[236:239], v[90:93]
	v_mfma_f32_16x16x32_bf16 v[78:81], v[154:157], v[244:247], v[78:81]
	v_mfma_f32_16x16x32_bf16 v[74:77], v[162:165], v[244:247], v[74:77]
	s_setprio 0
	s_setprio 1
	v_mfma_f32_16x16x32_bf16 v[118:121], v[166:169], v[182:185], v[118:121]
	v_mfma_f32_16x16x32_bf16 v[110:113], v[174:177], v[182:185], v[110:113]
	v_mfma_f32_16x16x32_bf16 v[102:105], v[166:169], v[206:209], v[102:105]
	v_mfma_f32_16x16x32_bf16 v[94:97], v[174:177], v[206:209], v[94:97]
	v_mfma_f32_16x16x32_bf16 v[86:89], v[166:169], v[232:235], v[86:89]
	v_mfma_f32_16x16x32_bf16 v[82:85], v[174:177], v[232:235], v[82:85]
	v_mfma_f32_16x16x32_bf16 v[70:73], v[166:169], v[240:243], v[70:73]
	v_mfma_f32_16x16x32_bf16 v[66:69], v[174:177], v[240:243], v[66:69]
	v_mfma_f32_16x16x32_bf16 v[118:121], v[170:173], v[202:205], v[118:121]
	v_mfma_f32_16x16x32_bf16 v[110:113], v[178:181], v[202:205], v[110:113]
	v_mfma_f32_16x16x32_bf16 v[102:105], v[170:173], v[210:213], v[102:105]
	v_mfma_f32_16x16x32_bf16 v[94:97], v[178:181], v[210:213], v[94:97]
	v_mfma_f32_16x16x32_bf16 v[86:89], v[170:173], v[236:239], v[86:89]
	v_mfma_f32_16x16x32_bf16 v[82:85], v[178:181], v[236:239], v[82:85]
	v_mfma_f32_16x16x32_bf16 v[70:73], v[170:173], v[244:247], v[70:73]
	v_mfma_f32_16x16x32_bf16 v[66:69], v[178:181], v[244:247], v[66:69]
	s_setprio 0
	s_barrier
	s_add_i32 s26, s49, s34
	s_mov_b32 m0, s26
	ds_read_b128 v[182:185], v148 offset:49152
	ds_read_b128 v[202:205], v148 offset:50176
	ds_read_b128 v[206:209], v148 offset:51200
	ds_read_b128 v[210:213], v148 offset:52224
	ds_read_b128 v[232:235], v148 offset:53248
	ds_read_b128 v[236:239], v148 offset:54272
	ds_read_b128 v[240:243], v148 offset:55296
	ds_read_b128 v[244:247], v148 offset:56320
	global_load_lds_dwordx4 v134, s[60:61]
	s_add_i32 m0, s26, 0x2000
	s_add_u32 s24, s24, 0x40080
	s_addc_u32 s25, s25, 0
	s_add_i32 s26, s50, s34
	global_load_lds_dwordx4 v130, s[60:61]
	s_mov_b32 m0, s26
	s_nop 0
	global_load_lds_dwordx4 v134, s[24:25]
	s_add_i32 m0, s26, 0x2000
	s_nop 0
	global_load_lds_dwordx4 v130, s[24:25]
	s_mov_b32 m0, s40
	s_nop 0
	global_load_lds_dwordx4 v136, s[62:63]
	s_mov_b32 m0, s41
	s_nop 0
	global_load_lds_dwordx4 v132, s[62:63]
	s_waitcnt vmcnt(8) lgkmcnt(0)
	s_setprio 1
	s_barrier
	v_mfma_f32_16x16x32_bf16 v[62:65], v[150:153], v[182:185], v[62:65]
	v_mfma_f32_16x16x32_bf16 v[58:61], v[158:161], v[182:185], v[58:61]
	v_mfma_f32_16x16x32_bf16 v[46:49], v[150:153], v[206:209], v[46:49]
	v_mfma_f32_16x16x32_bf16 v[42:45], v[158:161], v[206:209], v[42:45]
	v_mfma_f32_16x16x32_bf16 v[30:33], v[150:153], v[232:235], v[30:33]
	v_mfma_f32_16x16x32_bf16 v[26:29], v[158:161], v[232:235], v[26:29]
	v_mfma_f32_16x16x32_bf16 v[14:17], v[150:153], v[240:243], v[14:17]
	v_mfma_f32_16x16x32_bf16 v[10:13], v[158:161], v[240:243], v[10:13]
	v_mfma_f32_16x16x32_bf16 v[62:65], v[154:157], v[202:205], v[62:65]
	v_mfma_f32_16x16x32_bf16 v[58:61], v[162:165], v[202:205], v[58:61]
	v_mfma_f32_16x16x32_bf16 v[46:49], v[154:157], v[210:213], v[46:49]
	v_mfma_f32_16x16x32_bf16 v[42:45], v[162:165], v[210:213], v[42:45]
	v_mfma_f32_16x16x32_bf16 v[30:33], v[154:157], v[236:239], v[30:33]
	v_mfma_f32_16x16x32_bf16 v[26:29], v[162:165], v[236:239], v[26:29]
	v_mfma_f32_16x16x32_bf16 v[14:17], v[154:157], v[244:247], v[14:17]
	v_mfma_f32_16x16x32_bf16 v[10:13], v[162:165], v[244:247], v[10:13]
	s_setprio 0
	s_setprio 1
	v_mfma_f32_16x16x32_bf16 v[54:57], v[166:169], v[182:185], v[54:57]
	v_mfma_f32_16x16x32_bf16 v[50:53], v[174:177], v[182:185], v[50:53]
	v_mfma_f32_16x16x32_bf16 v[38:41], v[166:169], v[206:209], v[38:41]
	v_mfma_f32_16x16x32_bf16 v[34:37], v[174:177], v[206:209], v[34:37]
	v_mfma_f32_16x16x32_bf16 v[22:25], v[166:169], v[232:235], v[22:25]
	v_mfma_f32_16x16x32_bf16 v[18:21], v[174:177], v[232:235], v[18:21]
	v_mfma_f32_16x16x32_bf16 v[6:9], v[166:169], v[240:243], v[6:9]
	v_mfma_f32_16x16x32_bf16 v[2:5], v[174:177], v[240:243], v[2:5]
	v_mfma_f32_16x16x32_bf16 v[54:57], v[170:173], v[202:205], v[54:57]
	v_mfma_f32_16x16x32_bf16 v[50:53], v[178:181], v[202:205], v[50:53]
	v_mfma_f32_16x16x32_bf16 v[38:41], v[170:173], v[210:213], v[38:41]
	v_mfma_f32_16x16x32_bf16 v[34:37], v[178:181], v[210:213], v[34:37]
	v_mfma_f32_16x16x32_bf16 v[22:25], v[170:173], v[236:239], v[22:25]
	v_mfma_f32_16x16x32_bf16 v[18:21], v[178:181], v[236:239], v[18:21]
	v_mfma_f32_16x16x32_bf16 v[6:9], v[170:173], v[244:247], v[6:9]
	v_mfma_f32_16x16x32_bf16 v[2:5], v[178:181], v[244:247], v[2:5]
	s_setprio 0
	s_barrier
	s_add_i32 s48, s48, 2
	s_add_u32 s22, s22, 0x100
	s_addc_u32 s23, s23, 0
	s_add_u32 s46, s46, 0x100
	s_addc_u32 s47, s47, 0
	s_cmp_gt_u32 s48, 13
	s_cbranch_scc0 .LBB0_1354
	s_and_b64 vcc, exec, s[10:11]
	s_cbranch_vccz .LBB0_1357
	s_barrier

; #define PG8_STAGE(bufoff, gbase, voff) do { _Pragma("unroll") for (int _i = 0; _i < 2; ++_i) \
;         __builtin_amdgcn_global_load_lds((const unsigned*)((const char*)(gbase) + (voff)[_i]), (PG8_LAS unsigned*)(lds + (bufoff) + ldsw + _i * 8192), 16, 0, 0); } while (0)
; #define PG8_LDA(dst, b, h) do { _Pragma("unroll") for (int m = 0; m < 4; ++m) _Pragma("unroll") for (int k = 0; k < 2; ++k) dst[m][k] = *(const PG8_LAS bf16x8*)(lds + PG8_SA(b, h) + aoff + m * 2048 + k * 1024); } while (0)
; #define PG8_LDB(dst, b, h) do { _Pragma("unroll") for (int n = 0; n < 2; ++n) _Pragma("unroll") for (int k = 0; k < 2; ++k) dst[n][k] = *(const PG8_LAS bf16x8*)(lds + PG8_SB(b, h) + boff + n * 2048 + k * 1024); } while (0)
; #define PG8_MMA(ai, bj, At, Bt) do { __builtin_amdgcn_s_setprio(1); _Pragma("unroll") for (int m = 0; m < 4; ++m) _Pragma("unroll") for (int n = 0; n < 2; ++n) _Pragma("unroll") for (int k = 0; k < 2; ++k) \
;         acc[ai][bj][m][n] = __builtin_amdgcn_mfma_f32_16x16x32_bf16(Bt[n][k], At[m][k], acc[ai][bj][m][n], 0, 0, 0); __builtin_amdgcn_s_setprio(0); } while (0)
; #define PG8_WAIT_V(n) asm volatile("s_waitcnt vmcnt(" #n ")" ::: "memory")
; #define PG8_WAIT_L(n) asm volatile("s_waitcnt lgkmcnt(" #n ")" ::: "memory")
; template <class Epi, class Sched, bool ALIGN_EPI = false, bool SP2 = false>
; __device__ __forceinline__ void gemm_phase(PG8_LAS unsigned char* lds, const Gemm g, const Sched& S, const Epi& E) {
;     ...
;             const bool last = (t == nt - 2);
;             const char* a1 = cA + (size_t)(t + 1) * kstep;
;             const char* a2 = last ? nA : cA + (size_t)(t + 2) * kstep; const char* b2 = last ? nB : cB + (size_t)(t + 2) * kstep;
;             const char* a3 = a2 + kstep; const char* b3 = b2 + kstep;
;             if (last && has_next) S.a_ready(nxt);
;             if constexpr (SP2) {
;             PG8_LDB(B0, 0, 0); PG8_LDB(B1, 0, 1); PG8_SCHED; PG8_LDA(At, 0, 0); PG8_STAGE(PG8_SA(1, 1), a1 + hstepA, voffA);
;             PG8_WAIT_V(8); PG8_WAIT_L(0); PG8_BAR; PG8_MMA(0, 0, At, B0); PG8_MMA(0, 1, At, B1); PG8_BAR; PG8_SCHED;
;             PG8_LDA(At, 0, 1); PG8_STAGE(PG8_SB(0, 0), b2, voffB); PG8_STAGE(PG8_SB(0, 1), b2 + hstepB, voffB); PG8_STAGE(PG8_SA(0, 0), a2, voffA);
;             PG8_WAIT_V(8); PG8_WAIT_L(0); PG8_BAR; PG8_MMA(1, 0, At, B0); PG8_MMA(1, 1, At, B1); PG8_BAR; PG8_SCHED;
.LBB0_1438:
	s_add_u32 s20, s18, 0x100
	s_addc_u32 s21, s19, 0
	s_add_i32 s50, 0, 0x10000
	s_cmp_eq_u32 s49, 40
	s_cselect_b32 s25, s9, s21
	s_cselect_b32 s24, s8, s20
	s_cselect_b32 s23, s17, s48
	s_cselect_b32 s22, s16, s47
	s_add_i32 s51, 0, 0x14000
	v_add_u32_e32 v142, s50, v186
	v_add_u32_e32 v172, s51, v186
	ds_read_b128 v[130:133], v142
	ds_read_b128 v[134:137], v142 offset:1024
	ds_read_b128 v[138:141], v142 offset:2048
	ds_read_b128 v[142:145], v142 offset:3072
	ds_read_b128 v[146:149], v172
	ds_read_b128 v[150:153], v172 offset:1024
	ds_read_b128 v[168:171], v172 offset:2048
	ds_read_b128 v[172:175], v172 offset:3072
	s_add_i32 m0, s31, 0xc000
	ds_read_b128 v[176:179], v200
	ds_read_b128 v[180:183], v200 offset:1024
	ds_read_b128 v[202:205], v200 offset:2048
	ds_read_b128 v[206:209], v200 offset:3072
	ds_read_b128 v[210:213], v200 offset:4096
	ds_read_b128 v[232:235], v200 offset:5120
	ds_read_b128 v[236:239], v200 offset:6144
	ds_read_b128 v[240:243], v200 offset:7168
	global_load_lds_dwordx4 v164, s[18:19]
	s_add_i32 m0, s31, 0xe000
	s_nop 0
	global_load_lds_dwordx4 v166, s[18:19]
	s_waitcnt vmcnt(8) lgkmcnt(0)
	s_setprio 1
	s_barrier
	v_mfma_f32_16x16x32_bf16 v[126:129], v[130:133], v[176:179], v[126:129]
	v_mfma_f32_16x16x32_bf16 v[122:125], v[138:141], v[176:179], v[122:125]
	v_mfma_f32_16x16x32_bf16 v[110:113], v[130:133], v[202:205], v[110:113]
	v_mfma_f32_16x16x32_bf16 v[106:109], v[138:141], v[202:205], v[106:109]
	v_mfma_f32_16x16x32_bf16 v[94:97], v[130:133], v[210:213], v[94:97]
	v_mfma_f32_16x16x32_bf16 v[90:93], v[138:141], v[210:213], v[90:93]
	v_mfma_f32_16x16x32_bf16 v[78:81], v[130:133], v[236:239], v[78:81]
	v_mfma_f32_16x16x32_bf16 v[74:77], v[138:141], v[236:239], v[74:77]
	v_mfma_f32_16x16x32_bf16 v[126:129], v[134:137], v[180:183], v[126:129]
	v_mfma_f32_16x16x32_bf16 v[122:125], v[142:145], v[180:183], v[122:125]
	v_mfma_f32_16x16x32_bf16 v[110:113], v[134:137], v[206:209], v[110:113]
	v_mfma_f32_16x16x32_bf16 v[106:109], v[142:145], v[206:209], v[106:109]
	v_mfma_f32_16x16x32_bf16 v[94:97], v[134:137], v[232:235], v[94:97]
	v_mfma_f32_16x16x32_bf16 v[90:93], v[142:145], v[232:235], v[90:93]
	v_mfma_f32_16x16x32_bf16 v[78:81], v[134:137], v[240:243], v[78:81]
	v_mfma_f32_16x16x32_bf16 v[74:77], v[142:145], v[240:243], v[74:77]
	s_setprio 0
	s_setprio 1
	v_mfma_f32_16x16x32_bf16 v[118:121], v[146:149], v[176:179], v[118:121]
	v_mfma_f32_16x16x32_bf16 v[114:117], v[168:171], v[176:179], v[114:117]
	v_mfma_f32_16x16x32_bf16 v[102:105], v[146:149], v[202:205], v[102:105]
	v_mfma_f32_16x16x32_bf16 v[98:101], v[168:171], v[202:205], v[98:101]
	v_mfma_f32_16x16x32_bf16 v[86:89], v[146:149], v[210:213], v[86:89]
	v_mfma_f32_16x16x32_bf16 v[82:85], v[168:171], v[210:213], v[82:85]
	v_mfma_f32_16x16x32_bf16 v[70:73], v[146:149], v[236:239], v[70:73]
	v_mfma_f32_16x16x32_bf16 v[66:69], v[168:171], v[236:239], v[66:69]
	v_mfma_f32_16x16x32_bf16 v[118:121], v[150:153], v[180:183], v[118:121]
	v_mfma_f32_16x16x32_bf16 v[114:117], v[172:175], v[180:183], v[114:117]
	v_mfma_f32_16x16x32_bf16 v[102:105], v[150:153], v[206:209], v[102:105]
	v_mfma_f32_16x16x32_bf16 v[98:101], v[172:175], v[206:209], v[98:101]
	v_mfma_f32_16x16x32_bf16 v[86:89], v[150:153], v[232:235], v[86:89]
	v_mfma_f32_16x16x32_bf16 v[82:85], v[172:175], v[232:235], v[82:85]
	v_mfma_f32_16x16x32_bf16 v[70:73], v[150:153], v[240:243], v[70:73]
	v_mfma_f32_16x16x32_bf16 v[66:69], v[172:175], v[240:243], v[66:69]
	s_setprio 0
	s_barrier
	s_add_i32 s18, s50, s30
	s_mov_b32 m0, s18
	ds_read_b128 v[176:179], v200 offset:16384
	ds_read_b128 v[180:183], v200 offset:17408
	ds_read_b128 v[202:205], v200 offset:18432
	ds_read_b128 v[206:209], v200 offset:19456
	ds_read_b128 v[210:213], v200 offset:20480
	ds_read_b128 v[232:235], v200 offset:21504
	ds_read_b128 v[236:239], v200 offset:22528
	ds_read_b128 v[240:243], v200 offset:23552
	s_add_u32 s60, s22, 0x80
	s_addc_u32 s61, s23, 0
	s_add_u32 s62, s24, 0x80
	s_addc_u32 s63, s25, 0
	global_load_lds_dwordx4 v156, s[22:23]
	s_add_i32 m0, s18, 0x2000
	s_add_u32 s18, s22, 0xb0000
	s_addc_u32 s19, s23, 0
	s_add_i32 s50, s51, s30
	global_load_lds_dwordx4 v160, s[22:23]
	s_mov_b32 m0, s50
	s_nop 0
	global_load_lds_dwordx4 v156, s[18:19]
	s_add_i32 m0, s50, 0x2000
	s_nop 0
	global_load_lds_dwordx4 v160, s[18:19]
	s_mov_b32 m0, s31
	s_nop 0
	global_load_lds_dwordx4 v154, s[24:25]
	s_mov_b32 m0, s34
	s_nop 0
	global_load_lds_dwordx4 v158, s[24:25]
	s_waitcnt vmcnt(8) lgkmcnt(0)
	s_setprio 1
	s_barrier
	v_mfma_f32_16x16x32_bf16 v[62:65], v[130:133], v[176:179], v[62:65]
	v_mfma_f32_16x16x32_bf16 v[58:61], v[138:141], v[176:179], v[58:61]
	v_mfma_f32_16x16x32_bf16 v[46:49], v[130:133], v[202:205], v[46:49]
	v_mfma_f32_16x16x32_bf16 v[42:45], v[138:141], v[202:205], v[42:45]
	v_mfma_f32_16x16x32_bf16 v[30:33], v[130:133], v[210:213], v[30:33]
	v_mfma_f32_16x16x32_bf16 v[26:29], v[138:141], v[210:213], v[26:29]
	v_mfma_f32_16x16x32_bf16 v[14:17], v[130:133], v[236:239], v[14:17]
	v_mfma_f32_16x16x32_bf16 v[10:13], v[138:141], v[236:239], v[10:13]
	v_mfma_f32_16x16x32_bf16 v[62:65], v[134:137], v[180:183], v[62:65]
	v_mfma_f32_16x16x32_bf16 v[58:61], v[142:145], v[180:183], v[58:61]
	v_mfma_f32_16x16x32_bf16 v[46:49], v[134:137], v[206:209], v[46:49]
	v_mfma_f32_16x16x32_bf16 v[42:45], v[142:145], v[206:209], v[42:45]
	v_mfma_f32_16x16x32_bf16 v[30:33], v[134:137], v[232:235], v[30:33]
	v_mfma_f32_16x16x32_bf16 v[26:29], v[142:145], v[232:235], v[26:29]
	v_mfma_f32_16x16x32_bf16 v[14:17], v[134:137], v[240:243], v[14:17]
	v_mfma_f32_16x16x32_bf16 v[10:13], v[142:145], v[240:243], v[10:13]
	s_setprio 0
	s_setprio 1
	v_mfma_f32_16x16x32_bf16 v[54:57], v[146:149], v[176:179], v[54:57]
	v_mfma_f32_16x16x32_bf16 v[50:53], v[168:171], v[176:179], v[50:53]
	v_mfma_f32_16x16x32_bf16 v[38:41], v[146:149], v[202:205], v[38:41]
	v_mfma_f32_16x16x32_bf16 v[34:37], v[168:171], v[202:205], v[34:37]
	v_mfma_f32_16x16x32_bf16 v[22:25], v[146:149], v[210:213], v[22:25]
	v_mfma_f32_16x16x32_bf16 v[18:21], v[168:171], v[210:213], v[18:21]
	v_mfma_f32_16x16x32_bf16 v[6:9], v[146:149], v[236:239], v[6:9]
	v_mfma_f32_16x16x32_bf16 v[2:5], v[168:171], v[236:239], v[2:5]
	v_mfma_f32_16x16x32_bf16 v[54:57], v[150:153], v[180:183], v[54:57]
	v_mfma_f32_16x16x32_bf16 v[50:53], v[172:175], v[180:183], v[50:53]
	v_mfma_f32_16x16x32_bf16 v[38:41], v[150:153], v[206:209], v[38:41]
	v_mfma_f32_16x16x32_bf16 v[34:37], v[172:175], v[206:209], v[34:37]
	v_mfma_f32_16x16x32_bf16 v[22:25], v[150:153], v[232:235], v[22:25]
	v_mfma_f32_16x16x32_bf16 v[18:21], v[172:175], v[232:235], v[18:21]
	v_mfma_f32_16x16x32_bf16 v[6:9], v[150:153], v[240:243], v[6:9]
	v_mfma_f32_16x16x32_bf16 v[2:5], v[172:175], v[240:243], v[2:5]
	s_setprio 0
	s_barrier
; #define PG8_STAGE(bufoff, gbase, voff) do { _Pragma("unroll") for (int _i = 0; _i < 2; ++_i) \
;         __builtin_amdgcn_global_load_lds((const unsigned*)((const char*)(gbase) + (voff)[_i]), (PG8_LAS unsigned*)(lds + (bufoff) + ldsw + _i * 8192), 16, 0, 0); } while (0)
; #define PG8_LDA(dst, b, h) do { _Pragma("unroll") for (int m = 0; m < 4; ++m) _Pragma("unroll") for (int k = 0; k < 2; ++k) dst[m][k] = *(const PG8_LAS bf16x8*)(lds + PG8_SA(b, h) + aoff + m * 2048 + k * 1024); } while (0)
; #define PG8_LDB(dst, b, h) do { _Pragma("unroll") for (int n = 0; n < 2; ++n) _Pragma("unroll") for (int k = 0; k < 2; ++k) dst[n][k] = *(const PG8_LAS bf16x8*)(lds + PG8_SB(b, h) + boff + n * 2048 + k * 1024); } while (0)
; #define PG8_MMA(ai, bj, At, Bt) do { __builtin_amdgcn_s_setprio(1); _Pragma("unroll") for (int m = 0; m < 4; ++m) _Pragma("unroll") for (int n = 0; n < 2; ++n) _Pragma("unroll") for (int k = 0; k < 2; ++k) \
;         acc[ai][bj][m][n] = __builtin_amdgcn_mfma_f32_16x16x32_bf16(Bt[n][k], At[m][k], acc[ai][bj][m][n], 0, 0, 0); __builtin_amdgcn_s_setprio(0); } while (0)
; #define PG8_WAIT_V(n) asm volatile("s_waitcnt vmcnt(" #n ")" ::: "memory")
; #define PG8_WAIT_L(n) asm volatile("s_waitcnt lgkmcnt(" #n ")" ::: "memory")
; #define PG8_BAR __builtin_amdgcn_s_barrier()
; #define PG8_SCHED __builtin_amdgcn_sched_barrier(0)
; template <class Epi, class Sched, bool ALIGN_EPI = false, bool SP2 = false>
; __device__ __forceinline__ void gemm_phase(PG8_LAS unsigned char* lds, const Gemm g, const Sched& S, const Epi& E) {
;     ...
;         for (int t = 0; t < nt; t += 2) {
;     ...
;             PG8_LDB(B0, 1, 0); PG8_LDB(B1, 1, 1); PG8_SCHED; PG8_LDA(At, 1, 0); PG8_STAGE(PG8_SA(0, 1), a2 + hstepA, voffA);
;             PG8_WAIT_V(8); PG8_WAIT_L(0); PG8_BAR; PG8_MMA(0, 0, At, B0); PG8_MMA(0, 1, At, B1); PG8_BAR; PG8_SCHED;
;             PG8_LDA(At, 1, 1); PG8_STAGE(PG8_SB(1, 0), b3, voffB); PG8_STAGE(PG8_SB(1, 1), b3 + hstepB, voffB); PG8_STAGE(PG8_SA(1, 0), a3, voffA);
;             PG8_WAIT_V(8); PG8_WAIT_L(0); PG8_BAR; PG8_MMA(1, 0, At, B0); PG8_MMA(1, 1, At, B1); PG8_BAR; PG8_SCHED;
;     ...
;         if constexpr (ALIGN_EPI) { if (wr == 0) PG8_BAR; }
	s_add_i32 s50, 0, 0x18000
	s_add_i32 s51, 0, 0x1c000
	v_add_u32_e32 v142, s50, v186
	v_add_u32_e32 v172, s51, v186
	ds_read_b128 v[130:133], v142
	ds_read_b128 v[134:137], v142 offset:1024
	ds_read_b128 v[138:141], v142 offset:2048
	ds_read_b128 v[142:145], v142 offset:3072
	ds_read_b128 v[146:149], v172
	ds_read_b128 v[150:153], v172 offset:1024
	ds_read_b128 v[168:171], v172 offset:2048
	ds_read_b128 v[172:175], v172 offset:3072
	s_add_u32 s18, s24, 0xb0000
	s_addc_u32 s19, s25, 0
	s_mov_b32 m0, s35
	ds_read_b128 v[176:179], v200 offset:32768
	ds_read_b128 v[180:183], v200 offset:33792
	ds_read_b128 v[202:205], v200 offset:34816
	ds_read_b128 v[206:209], v200 offset:35840
	ds_read_b128 v[210:213], v200 offset:36864
	ds_read_b128 v[232:235], v200 offset:37888
	ds_read_b128 v[236:239], v200 offset:38912
	ds_read_b128 v[240:243], v200 offset:39936
	global_load_lds_dwordx4 v154, s[18:19]
	s_mov_b32 m0, s36
	s_nop 0
	global_load_lds_dwordx4 v158, s[18:19]
	s_waitcnt vmcnt(8) lgkmcnt(0)
	s_setprio 1
	s_barrier
	v_mfma_f32_16x16x32_bf16 v[126:129], v[130:133], v[176:179], v[126:129]
	v_mfma_f32_16x16x32_bf16 v[122:125], v[138:141], v[176:179], v[122:125]
	v_mfma_f32_16x16x32_bf16 v[110:113], v[130:133], v[202:205], v[110:113]
	v_mfma_f32_16x16x32_bf16 v[106:109], v[138:141], v[202:205], v[106:109]
	v_mfma_f32_16x16x32_bf16 v[94:97], v[130:133], v[210:213], v[94:97]
	v_mfma_f32_16x16x32_bf16 v[90:93], v[138:141], v[210:213], v[90:93]
	v_mfma_f32_16x16x32_bf16 v[78:81], v[130:133], v[236:239], v[78:81]
	v_mfma_f32_16x16x32_bf16 v[74:77], v[138:141], v[236:239], v[74:77]
	v_mfma_f32_16x16x32_bf16 v[126:129], v[134:137], v[180:183], v[126:129]
	v_mfma_f32_16x16x32_bf16 v[122:125], v[142:145], v[180:183], v[122:125]
	v_mfma_f32_16x16x32_bf16 v[110:113], v[134:137], v[206:209], v[110:113]
	v_mfma_f32_16x16x32_bf16 v[106:109], v[142:145], v[206:209], v[106:109]
	v_mfma_f32_16x16x32_bf16 v[94:97], v[134:137], v[232:235], v[94:97]
	v_mfma_f32_16x16x32_bf16 v[90:93], v[142:145], v[232:235], v[90:93]
	v_mfma_f32_16x16x32_bf16 v[78:81], v[134:137], v[240:243], v[78:81]
	v_mfma_f32_16x16x32_bf16 v[74:77], v[142:145], v[240:243], v[74:77]
	s_setprio 0
	s_setprio 1
	v_mfma_f32_16x16x32_bf16 v[118:121], v[146:149], v[176:179], v[118:121]
	v_mfma_f32_16x16x32_bf16 v[114:117], v[168:171], v[176:179], v[114:117]
	v_mfma_f32_16x16x32_bf16 v[102:105], v[146:149], v[202:205], v[102:105]
	v_mfma_f32_16x16x32_bf16 v[98:101], v[168:171], v[202:205], v[98:101]
	v_mfma_f32_16x16x32_bf16 v[86:89], v[146:149], v[210:213], v[86:89]
	v_mfma_f32_16x16x32_bf16 v[82:85], v[168:171], v[210:213], v[82:85]
	v_mfma_f32_16x16x32_bf16 v[70:73], v[146:149], v[236:239], v[70:73]
	v_mfma_f32_16x16x32_bf16 v[66:69], v[168:171], v[236:239], v[66:69]
	v_mfma_f32_16x16x32_bf16 v[118:121], v[150:153], v[180:183], v[118:121]
	v_mfma_f32_16x16x32_bf16 v[114:117], v[172:175], v[180:183], v[114:117]
	v_mfma_f32_16x16x32_bf16 v[102:105], v[150:153], v[206:209], v[102:105]
	v_mfma_f32_16x16x32_bf16 v[98:101], v[172:175], v[206:209], v[98:101]
	v_mfma_f32_16x16x32_bf16 v[86:89], v[150:153], v[232:235], v[86:89]
	v_mfma_f32_16x16x32_bf16 v[82:85], v[172:175], v[232:235], v[82:85]
	v_mfma_f32_16x16x32_bf16 v[70:73], v[150:153], v[240:243], v[70:73]
	v_mfma_f32_16x16x32_bf16 v[66:69], v[172:175], v[240:243], v[66:69]
	s_setprio 0
	s_barrier
	s_add_i32 s18, s50, s30
	s_mov_b32 m0, s18
	ds_read_b128 v[176:179], v200 offset:49152
	ds_read_b128 v[180:183], v200 offset:50176
	ds_read_b128 v[202:205], v200 offset:51200
	ds_read_b128 v[206:209], v200 offset:52224
	ds_read_b128 v[210:213], v200 offset:53248
	ds_read_b128 v[232:235], v200 offset:54272
	ds_read_b128 v[236:239], v200 offset:55296
	ds_read_b128 v[240:243], v200 offset:56320
	global_load_lds_dwordx4 v156, s[60:61]
	s_add_i32 m0, s18, 0x2000
	s_add_u32 s18, s22, 0xb0080
	s_addc_u32 s19, s23, 0
	s_add_i32 s22, s51, s30
	global_load_lds_dwordx4 v160, s[60:61]
	s_mov_b32 m0, s22
	s_nop 0
	global_load_lds_dwordx4 v156, s[18:19]
	s_add_i32 m0, s22, 0x2000
	s_nop 0
	global_load_lds_dwordx4 v160, s[18:19]
	s_mov_b32 m0, s38
	s_nop 0
	global_load_lds_dwordx4 v154, s[62:63]
	s_mov_b32 m0, s39
	s_nop 0
	global_load_lds_dwordx4 v158, s[62:63]
	s_waitcnt vmcnt(8) lgkmcnt(0)
	s_setprio 1
	s_barrier
	v_mfma_f32_16x16x32_bf16 v[62:65], v[130:133], v[176:179], v[62:65]
	v_mfma_f32_16x16x32_bf16 v[58:61], v[138:141], v[176:179], v[58:61]
	v_mfma_f32_16x16x32_bf16 v[46:49], v[130:133], v[202:205], v[46:49]
	v_mfma_f32_16x16x32_bf16 v[42:45], v[138:141], v[202:205], v[42:45]
	v_mfma_f32_16x16x32_bf16 v[30:33], v[130:133], v[210:213], v[30:33]
	v_mfma_f32_16x16x32_bf16 v[26:29], v[138:141], v[210:213], v[26:29]
	v_mfma_f32_16x16x32_bf16 v[14:17], v[130:133], v[236:239], v[14:17]
	v_mfma_f32_16x16x32_bf16 v[10:13], v[138:141], v[236:239], v[10:13]
	v_mfma_f32_16x16x32_bf16 v[62:65], v[134:137], v[180:183], v[62:65]
	v_mfma_f32_16x16x32_bf16 v[58:61], v[142:145], v[180:183], v[58:61]
	v_mfma_f32_16x16x32_bf16 v[46:49], v[134:137], v[206:209], v[46:49]
	v_mfma_f32_16x16x32_bf16 v[42:45], v[142:145], v[206:209], v[42:45]
	v_mfma_f32_16x16x32_bf16 v[30:33], v[134:137], v[232:235], v[30:33]
	v_mfma_f32_16x16x32_bf16 v[26:29], v[142:145], v[232:235], v[26:29]
	v_mfma_f32_16x16x32_bf16 v[14:17], v[134:137], v[240:243], v[14:17]
	v_mfma_f32_16x16x32_bf16 v[10:13], v[142:145], v[240:243], v[10:13]
	s_setprio 0
	s_setprio 1
	v_mfma_f32_16x16x32_bf16 v[54:57], v[146:149], v[176:179], v[54:57]
	v_mfma_f32_16x16x32_bf16 v[50:53], v[168:171], v[176:179], v[50:53]
	v_mfma_f32_16x16x32_bf16 v[38:41], v[146:149], v[202:205], v[38:41]
	v_mfma_f32_16x16x32_bf16 v[34:37], v[168:171], v[202:205], v[34:37]
	v_mfma_f32_16x16x32_bf16 v[22:25], v[146:149], v[210:213], v[22:25]
	v_mfma_f32_16x16x32_bf16 v[18:21], v[168:171], v[210:213], v[18:21]
	v_mfma_f32_16x16x32_bf16 v[6:9], v[146:149], v[236:239], v[6:9]
	v_mfma_f32_16x16x32_bf16 v[2:5], v[168:171], v[236:239], v[2:5]
	v_mfma_f32_16x16x32_bf16 v[54:57], v[150:153], v[180:183], v[54:57]
	v_mfma_f32_16x16x32_bf16 v[50:53], v[172:175], v[180:183], v[50:53]
	v_mfma_f32_16x16x32_bf16 v[38:41], v[150:153], v[206:209], v[38:41]
	v_mfma_f32_16x16x32_bf16 v[34:37], v[172:175], v[206:209], v[34:37]
	v_mfma_f32_16x16x32_bf16 v[22:25], v[150:153], v[232:235], v[22:25]
	v_mfma_f32_16x16x32_bf16 v[18:21], v[172:175], v[232:235], v[18:21]
	v_mfma_f32_16x16x32_bf16 v[6:9], v[150:153], v[240:243], v[6:9]
	v_mfma_f32_16x16x32_bf16 v[2:5], v[172:175], v[240:243], v[2:5]
	s_setprio 0
	s_barrier
	s_add_i32 s49, s49, 2
	s_add_u32 s47, s47, 0x100
	s_addc_u32 s48, s48, 0
	s_cmp_gt_u32 s49, 41
	s_mov_b64 s[18:19], s[20:21]
	s_cbranch_scc0 .LBB0_1438
	s_and_b64 vcc, exec, s[14:15]
	s_cbranch_vccz .LBB0_1441
	s_barrier
